# t2 + load-segment instruction trimming: s_nop after m0 write replaced by a moved ds_read, in-proj LDS-offset constants folded into literals
# baseline (speedup 1.0000x reference)
; #define PG8_STAGE(bufoff, gbase, voff) do { _Pragma("unroll") for (int _i = 0; _i < 2; ++_i) \
;         __builtin_amdgcn_global_load_lds((const unsigned*)((const char*)(gbase) + (voff)[_i]), (LAS unsigned*)(lds + (bufoff) + ldsw + _i * 8192), 16, 0, 0); } while (0)
; #define PG8_LDA(dst, b, h) do { _Pragma("unroll") for (int m = 0; m < 4; ++m) _Pragma("unroll") for (int k = 0; k < 2; ++k) dst[m][k] = *(const LAS bf16x8*)(lds + PG8_SA(b, h) + aoff + m * 2048 + k * 1024); } while (0)
; #define PG8_LDB(dst, b, h) do { _Pragma("unroll") for (int n = 0; n < 2; ++n) _Pragma("unroll") for (int k = 0; k < 2; ++k) dst[n][k] = *(const LAS bf16x8*)(lds + PG8_SB(b, h) + boff + n * 2048 + k * 1024); } while (0)
; #define PG8_MMA(ai, bj, At, Bt) do { __builtin_amdgcn_s_setprio(1); _Pragma("unroll") for (int m = 0; m < 4; ++m) _Pragma("unroll") for (int n = 0; n < 2; ++n) _Pragma("unroll") for (int k = 0; k < 2; ++k) \
;         acc[ai][bj][m][n] = __builtin_amdgcn_mfma_f32_16x16x32_bf16(Bt[n][k], At[m][k], acc[ai][bj][m][n], 0, 0, 0); __builtin_amdgcn_s_setprio(0); } while (0)
; #define PG8_WAIT_V(n) asm volatile("s_waitcnt vmcnt(" #n ")" ::: "memory")
; #define PG8_WAIT_L(n) asm volatile("s_waitcnt lgkmcnt(" #n ")" ::: "memory")
; template <class Epi, class Sched, bool ALIGN_EPI, class Hook = NoHook>
; __device__ __forceinline__ void gemm_phase(LAS unsigned char* lds, const Gemm g, const Sched& S, const Epi& E, const Hook& H = Hook()) {
;     ...
;         for (int t = tb; t < te; t += 2) {
;             const bool last = (t == nt - 2);
;             const char* a1 = cA + (size_t)(t + 1) * kstep;
;             const char* a2 = last ? nA : cA + (size_t)(t + 2) * kstep; const char* b2 = last ? nB : cB + (size_t)(t + 2) * kstep;
;             const char* a3 = a2 + kstep; const char* b3 = b2 + kstep;
;             if (last && has_next) S.a_ready(nxt);
;             PG8_LDB(B0, 0, 0); PG8_LDB(B1, 0, 1); PG8_SCHED; PG8_LDA(At, 0, 0); PG8_STAGE(PG8_SA(1, 1), a1 + hA, voffA);
;             PG8_WAIT_V(8); PG8_WAIT_L(0); PG8_BAR; PG8_MMA(0, 0, At, B0); PG8_MMA(0, 1, At, B1); PG8_BAR; PG8_SCHED;
;             PG8_LDA(At, 0, 1); PG8_STAGE(PG8_SB(0, 0), b2, voffB); PG8_STAGE(PG8_SB(0, 1), b2 + hB, voffB); PG8_STAGE(PG8_SA(0, 0), a2, voffA);
;             PG8_WAIT_V(8); PG8_WAIT_L(0); PG8_BAR; PG8_MMA(1, 0, At, B0); PG8_MMA(1, 1, At, B1); PG8_BAR; PG8_SCHED;
.LBB0_199:
	ds_read_b128 v[130:133], v217
	ds_read_b128 v[134:137], v217 offset:1024
	s_add_i32 m0, s40, 0xc000
	ds_read_b128 v[138:141], v217 offset:2048
	global_load_lds_dwordx4 v172, s[4:5]
	ds_read_b128 v[142:145], v217 offset:3072
	ds_read_b128 v[146:149], v218
	ds_read_b128 v[150:153], v218 offset:1024
	ds_read_b128 v[154:157], v218 offset:2048
	ds_read_b128 v[158:161], v218 offset:3072
	ds_read_b128 v[180:183], v219
	s_add_i32 m0, s40, 0xe000
	s_nop 0
	global_load_lds_dwordx4 v174, s[4:5]
	s_add_u32 s34, s4, 0x100
	s_addc_u32 s35, s5, 0
	s_cmp_eq_u32 s64, 60
	s_cselect_b32 s39, s7, s35
	s_cselect_b32 s38, s8, s34
	s_cselect_b32 s37, s23, s63
	s_cselect_b32 s36, s25, s31
	ds_read_b128 v[184:187], v219 offset:1024
	ds_read_b128 v[188:191], v219 offset:2048
	ds_read_b128 v[192:195], v219 offset:3072
	ds_read_b128 v[196:199], v219 offset:4096
	ds_read_b128 v[200:203], v219 offset:5120
	ds_read_b128 v[204:207], v219 offset:6144
	ds_read_b128 v[208:211], v219 offset:7168
	s_barrier
	s_setprio 1
	s_waitcnt lgkmcnt(0)
	v_mfma_f32_16x16x32_bf16 v[126:129], v[130:133], v[180:183], v[126:129]
	v_mfma_f32_16x16x32_bf16 v[94:97], v[138:141], v[180:183], v[94:97]
	v_mfma_f32_16x16x32_bf16 v[122:125], v[130:133], v[188:191], v[122:125]
	v_mfma_f32_16x16x32_bf16 v[90:93], v[138:141], v[188:191], v[90:93]
	v_mfma_f32_16x16x32_bf16 v[118:121], v[130:133], v[196:199], v[118:121]
	v_mfma_f32_16x16x32_bf16 v[86:89], v[138:141], v[196:199], v[86:89]
	v_mfma_f32_16x16x32_bf16 v[114:117], v[130:133], v[204:207], v[114:117]
	v_mfma_f32_16x16x32_bf16 v[82:85], v[138:141], v[204:207], v[82:85]
	v_mfma_f32_16x16x32_bf16 v[126:129], v[134:137], v[184:187], v[126:129]
	v_mfma_f32_16x16x32_bf16 v[94:97], v[142:145], v[184:187], v[94:97]
	v_mfma_f32_16x16x32_bf16 v[122:125], v[134:137], v[192:195], v[122:125]
	v_mfma_f32_16x16x32_bf16 v[90:93], v[142:145], v[192:195], v[90:93]
	v_mfma_f32_16x16x32_bf16 v[118:121], v[134:137], v[200:203], v[118:121]
	v_mfma_f32_16x16x32_bf16 v[86:89], v[142:145], v[200:203], v[86:89]
	v_mfma_f32_16x16x32_bf16 v[114:117], v[134:137], v[208:211], v[114:117]
	v_mfma_f32_16x16x32_bf16 v[82:85], v[142:145], v[208:211], v[82:85]
	s_setprio 0
	s_setprio 1
	v_mfma_f32_16x16x32_bf16 v[62:65], v[146:149], v[180:183], v[62:65]
	v_mfma_f32_16x16x32_bf16 v[30:33], v[154:157], v[180:183], v[30:33]
	v_mfma_f32_16x16x32_bf16 v[58:61], v[146:149], v[188:191], v[58:61]
	v_mfma_f32_16x16x32_bf16 v[26:29], v[154:157], v[188:191], v[26:29]
	v_mfma_f32_16x16x32_bf16 v[54:57], v[146:149], v[196:199], v[54:57]
	v_mfma_f32_16x16x32_bf16 v[22:25], v[154:157], v[196:199], v[22:25]
	v_mfma_f32_16x16x32_bf16 v[50:53], v[146:149], v[204:207], v[50:53]
	v_mfma_f32_16x16x32_bf16 v[18:21], v[154:157], v[204:207], v[18:21]
	v_mfma_f32_16x16x32_bf16 v[62:65], v[150:153], v[184:187], v[62:65]
	v_mfma_f32_16x16x32_bf16 v[30:33], v[158:161], v[184:187], v[30:33]
	v_mfma_f32_16x16x32_bf16 v[58:61], v[150:153], v[192:195], v[58:61]
	v_mfma_f32_16x16x32_bf16 v[26:29], v[158:161], v[192:195], v[26:29]
	v_mfma_f32_16x16x32_bf16 v[54:57], v[150:153], v[200:203], v[54:57]
	v_mfma_f32_16x16x32_bf16 v[22:25], v[158:161], v[200:203], v[22:25]
	v_mfma_f32_16x16x32_bf16 v[50:53], v[150:153], v[208:211], v[50:53]
	v_mfma_f32_16x16x32_bf16 v[18:21], v[158:161], v[208:211], v[18:21]
	s_waitcnt vmcnt(8)
	s_barrier
	s_setprio 0
	s_add_i32 s4, s59, s21
	s_mov_b32 m0, s4
	ds_read_b128 v[180:183], v219 offset:16384
	ds_read_b128 v[184:187], v219 offset:17408
	global_load_lds_dwordx4 v164, s[36:37]
	ds_read_b128 v[188:191], v219 offset:18432
	s_add_i32 m0, s4, 0x2000
	s_add_u32 s4, s36, 0x100000
	s_addc_u32 s5, s37, 0
	s_add_i32 s65, s60, s21
	global_load_lds_dwordx4 v168, s[36:37]
	ds_read_b128 v[192:195], v219 offset:19456
	s_mov_b32 m0, s65
	ds_read_b128 v[196:199], v219 offset:20480
	global_load_lds_dwordx4 v164, s[4:5]
	s_add_i32 m0, s65, 0x2000
	ds_read_b128 v[200:203], v219 offset:21504
	global_load_lds_dwordx4 v168, s[4:5]
	s_mov_b32 m0, s40
	ds_read_b128 v[204:207], v219 offset:22528
	global_load_lds_dwordx4 v162, s[38:39]
	s_mov_b32 m0, s41
	ds_read_b128 v[208:211], v219 offset:23552
	global_load_lds_dwordx4 v166, s[38:39]
	s_barrier
	s_setprio 1
	s_waitcnt lgkmcnt(0)
	v_mfma_f32_16x16x32_bf16 v[110:113], v[130:133], v[180:183], v[110:113]
	v_mfma_f32_16x16x32_bf16 v[78:81], v[138:141], v[180:183], v[78:81]
	v_mfma_f32_16x16x32_bf16 v[106:109], v[130:133], v[188:191], v[106:109]
	v_mfma_f32_16x16x32_bf16 v[74:77], v[138:141], v[188:191], v[74:77]
	v_mfma_f32_16x16x32_bf16 v[102:105], v[130:133], v[196:199], v[102:105]
	v_mfma_f32_16x16x32_bf16 v[70:73], v[138:141], v[196:199], v[70:73]
	v_mfma_f32_16x16x32_bf16 v[98:101], v[130:133], v[204:207], v[98:101]
	v_mfma_f32_16x16x32_bf16 v[66:69], v[138:141], v[204:207], v[66:69]
	v_mfma_f32_16x16x32_bf16 v[110:113], v[134:137], v[184:187], v[110:113]
	v_mfma_f32_16x16x32_bf16 v[78:81], v[142:145], v[184:187], v[78:81]
	v_mfma_f32_16x16x32_bf16 v[106:109], v[134:137], v[192:195], v[106:109]
	v_mfma_f32_16x16x32_bf16 v[74:77], v[142:145], v[192:195], v[74:77]
	v_mfma_f32_16x16x32_bf16 v[102:105], v[134:137], v[200:203], v[102:105]
	v_mfma_f32_16x16x32_bf16 v[70:73], v[142:145], v[200:203], v[70:73]
	v_mfma_f32_16x16x32_bf16 v[98:101], v[134:137], v[208:211], v[98:101]
	v_mfma_f32_16x16x32_bf16 v[66:69], v[142:145], v[208:211], v[66:69]
	s_setprio 0
	s_setprio 1
	v_mfma_f32_16x16x32_bf16 v[46:49], v[146:149], v[180:183], v[46:49]
	v_mfma_f32_16x16x32_bf16 v[14:17], v[154:157], v[180:183], v[14:17]
	v_mfma_f32_16x16x32_bf16 v[42:45], v[146:149], v[188:191], v[42:45]
	v_mfma_f32_16x16x32_bf16 v[10:13], v[154:157], v[188:191], v[10:13]
	v_mfma_f32_16x16x32_bf16 v[38:41], v[146:149], v[196:199], v[38:41]
	v_mfma_f32_16x16x32_bf16 v[6:9], v[154:157], v[196:199], v[6:9]
	v_mfma_f32_16x16x32_bf16 v[34:37], v[146:149], v[204:207], v[34:37]
	v_mfma_f32_16x16x32_bf16 v[2:5], v[154:157], v[204:207], v[2:5]
	v_mfma_f32_16x16x32_bf16 v[46:49], v[150:153], v[184:187], v[46:49]
	v_mfma_f32_16x16x32_bf16 v[14:17], v[158:161], v[184:187], v[14:17]
	v_mfma_f32_16x16x32_bf16 v[42:45], v[150:153], v[192:195], v[42:45]
	v_mfma_f32_16x16x32_bf16 v[10:13], v[158:161], v[192:195], v[10:13]
	v_mfma_f32_16x16x32_bf16 v[38:41], v[150:153], v[200:203], v[38:41]
	v_mfma_f32_16x16x32_bf16 v[6:9], v[158:161], v[200:203], v[6:9]
	v_mfma_f32_16x16x32_bf16 v[34:37], v[150:153], v[208:211], v[34:37]
	v_mfma_f32_16x16x32_bf16 v[2:5], v[158:161], v[208:211], v[2:5]
	s_waitcnt vmcnt(8)
	s_barrier
; #define PG8_STAGE(bufoff, gbase, voff) do { _Pragma("unroll") for (int _i = 0; _i < 2; ++_i) \
;         __builtin_amdgcn_global_load_lds((const unsigned*)((const char*)(gbase) + (voff)[_i]), (LAS unsigned*)(lds + (bufoff) + ldsw + _i * 8192), 16, 0, 0); } while (0)
; #define PG8_LDA(dst, b, h) do { _Pragma("unroll") for (int m = 0; m < 4; ++m) _Pragma("unroll") for (int k = 0; k < 2; ++k) dst[m][k] = *(const LAS bf16x8*)(lds + PG8_SA(b, h) + aoff + m * 2048 + k * 1024); } while (0)
; #define PG8_LDB(dst, b, h) do { _Pragma("unroll") for (int n = 0; n < 2; ++n) _Pragma("unroll") for (int k = 0; k < 2; ++k) dst[n][k] = *(const LAS bf16x8*)(lds + PG8_SB(b, h) + boff + n * 2048 + k * 1024); } while (0)
; #define PG8_MMA(ai, bj, At, Bt) do { __builtin_amdgcn_s_setprio(1); _Pragma("unroll") for (int m = 0; m < 4; ++m) _Pragma("unroll") for (int n = 0; n < 2; ++n) _Pragma("unroll") for (int k = 0; k < 2; ++k) \
;         acc[ai][bj][m][n] = __builtin_amdgcn_mfma_f32_16x16x32_bf16(Bt[n][k], At[m][k], acc[ai][bj][m][n], 0, 0, 0); __builtin_amdgcn_s_setprio(0); } while (0)
; #define PG8_WAIT_V(n) asm volatile("s_waitcnt vmcnt(" #n ")" ::: "memory")
; #define PG8_WAIT_L(n) asm volatile("s_waitcnt lgkmcnt(" #n ")" ::: "memory")
; #define PG8_BAR __builtin_amdgcn_s_barrier()
; #define PG8_SCHED __builtin_amdgcn_sched_barrier(0)
; template <class Epi, class Sched, bool ALIGN_EPI, class Hook = NoHook>
; __device__ __forceinline__ void gemm_phase(LAS unsigned char* lds, const Gemm g, const Sched& S, const Epi& E, const Hook& H = Hook()) {
;     ...
;             PG8_LDB(B0, 1, 0); PG8_LDB(B1, 1, 1); PG8_SCHED; PG8_LDA(At, 1, 0); PG8_STAGE(PG8_SA(0, 1), a2 + hA, voffA);
;             PG8_WAIT_V(8); PG8_WAIT_L(0); PG8_BAR; PG8_MMA(0, 0, At, B0); PG8_MMA(0, 1, At, B1); PG8_BAR; PG8_SCHED;
;             PG8_LDA(At, 1, 1); PG8_STAGE(PG8_SB(1, 0), b3, voffB); PG8_STAGE(PG8_SB(1, 1), b3 + hB, voffB); PG8_STAGE(PG8_SA(1, 0), a3, voffA);
;             PG8_WAIT_V(8); PG8_WAIT_L(0); PG8_BAR; PG8_MMA(1, 0, At, B0); PG8_MMA(1, 1, At, B1); PG8_BAR; PG8_SCHED;
;         }
	s_setprio 0
	v_add_u32_e32 v142, 0x18000, v213
	v_add_u32_e32 v158, 0x1c000, v213
	ds_read_b128 v[130:133], v142
	ds_read_b128 v[134:137], v142 offset:1024
	s_add_u32 s4, s38, 0x8000
	s_addc_u32 s5, s39, 0
	s_mov_b32 m0, s42
	ds_read_b128 v[138:141], v142 offset:2048
	global_load_lds_dwordx4 v162, s[4:5]
	ds_read_b128 v[142:145], v142 offset:3072
	ds_read_b128 v[146:149], v158
	ds_read_b128 v[150:153], v158 offset:1024
	ds_read_b128 v[154:157], v158 offset:2048
	ds_read_b128 v[158:161], v158 offset:3072
	ds_read_b128 v[180:183], v219 offset:32768
	s_mov_b32 m0, s43
	ds_read_b128 v[184:187], v219 offset:33792
	global_load_lds_dwordx4 v166, s[4:5]
	ds_read_b128 v[188:191], v219 offset:34816
	ds_read_b128 v[192:195], v219 offset:35840
	ds_read_b128 v[196:199], v219 offset:36864
	ds_read_b128 v[200:203], v219 offset:37888
	ds_read_b128 v[204:207], v219 offset:38912
	ds_read_b128 v[208:211], v219 offset:39936
	s_barrier
	s_setprio 1
	s_waitcnt lgkmcnt(0)
	v_mfma_f32_16x16x32_bf16 v[126:129], v[130:133], v[180:183], v[126:129]
	v_mfma_f32_16x16x32_bf16 v[94:97], v[138:141], v[180:183], v[94:97]
	v_mfma_f32_16x16x32_bf16 v[122:125], v[130:133], v[188:191], v[122:125]
	v_mfma_f32_16x16x32_bf16 v[90:93], v[138:141], v[188:191], v[90:93]
	v_mfma_f32_16x16x32_bf16 v[118:121], v[130:133], v[196:199], v[118:121]
	v_mfma_f32_16x16x32_bf16 v[86:89], v[138:141], v[196:199], v[86:89]
	v_mfma_f32_16x16x32_bf16 v[114:117], v[130:133], v[204:207], v[114:117]
	v_mfma_f32_16x16x32_bf16 v[82:85], v[138:141], v[204:207], v[82:85]
	v_mfma_f32_16x16x32_bf16 v[126:129], v[134:137], v[184:187], v[126:129]
	v_mfma_f32_16x16x32_bf16 v[94:97], v[142:145], v[184:187], v[94:97]
	v_mfma_f32_16x16x32_bf16 v[122:125], v[134:137], v[192:195], v[122:125]
	v_mfma_f32_16x16x32_bf16 v[90:93], v[142:145], v[192:195], v[90:93]
	v_mfma_f32_16x16x32_bf16 v[118:121], v[134:137], v[200:203], v[118:121]
	v_mfma_f32_16x16x32_bf16 v[86:89], v[142:145], v[200:203], v[86:89]
	v_mfma_f32_16x16x32_bf16 v[114:117], v[134:137], v[208:211], v[114:117]
	v_mfma_f32_16x16x32_bf16 v[82:85], v[142:145], v[208:211], v[82:85]
	s_setprio 0
	s_setprio 1
	v_mfma_f32_16x16x32_bf16 v[62:65], v[146:149], v[180:183], v[62:65]
	v_mfma_f32_16x16x32_bf16 v[30:33], v[154:157], v[180:183], v[30:33]
	v_mfma_f32_16x16x32_bf16 v[58:61], v[146:149], v[188:191], v[58:61]
	v_mfma_f32_16x16x32_bf16 v[26:29], v[154:157], v[188:191], v[26:29]
	v_mfma_f32_16x16x32_bf16 v[54:57], v[146:149], v[196:199], v[54:57]
	v_mfma_f32_16x16x32_bf16 v[22:25], v[154:157], v[196:199], v[22:25]
	v_mfma_f32_16x16x32_bf16 v[50:53], v[146:149], v[204:207], v[50:53]
	v_mfma_f32_16x16x32_bf16 v[18:21], v[154:157], v[204:207], v[18:21]
	v_mfma_f32_16x16x32_bf16 v[62:65], v[150:153], v[184:187], v[62:65]
	v_mfma_f32_16x16x32_bf16 v[30:33], v[158:161], v[184:187], v[30:33]
	v_mfma_f32_16x16x32_bf16 v[58:61], v[150:153], v[192:195], v[58:61]
	v_mfma_f32_16x16x32_bf16 v[26:29], v[158:161], v[192:195], v[26:29]
	v_mfma_f32_16x16x32_bf16 v[54:57], v[150:153], v[200:203], v[54:57]
	v_mfma_f32_16x16x32_bf16 v[22:25], v[158:161], v[200:203], v[22:25]
	v_mfma_f32_16x16x32_bf16 v[50:53], v[150:153], v[208:211], v[50:53]
	v_mfma_f32_16x16x32_bf16 v[18:21], v[158:161], v[208:211], v[18:21]
	s_waitcnt vmcnt(8)
	s_barrier
	s_setprio 0
	s_add_i32 s4, s21, 0x18000
	s_add_u32 s68, s36, s14
	s_addc_u32 s69, s37, s15
	s_mov_b32 m0, s4
	ds_read_b128 v[180:183], v219 offset:49152
	ds_read_b128 v[184:187], v219 offset:50176
	global_load_lds_dwordx4 v164, s[68:69]
	ds_read_b128 v[188:191], v219 offset:51200
	s_add_i32 m0, s4, 0x2000
	s_add_u32 s4, s36, 0x100080
	s_addc_u32 s5, s37, 0
	s_add_i32 s36, s21, 0x1c000
	global_load_lds_dwordx4 v168, s[68:69]
	ds_read_b128 v[192:195], v219 offset:52224
	s_mov_b32 m0, s36
	ds_read_b128 v[196:199], v219 offset:53248
	global_load_lds_dwordx4 v164, s[4:5]
	s_add_i32 m0, s36, 0x2000
	ds_read_b128 v[200:203], v219 offset:54272
	global_load_lds_dwordx4 v168, s[4:5]
	s_add_u32 s70, s38, s14
	s_addc_u32 s71, s39, s15
	s_mov_b32 m0, s51
	ds_read_b128 v[204:207], v219 offset:55296
	global_load_lds_dwordx4 v162, s[70:71]
	s_mov_b32 m0, s52
	s_nop 0
	global_load_lds_dwordx4 v166, s[70:71]
	s_add_i32 s64, s64, 2
	s_add_u32 s31, s31, 0x100
	s_addc_u32 s63, s63, 0
	s_cmp_gt_u32 s64, 61
	s_mov_b64 s[4:5], s[34:35]
	ds_read_b128 v[208:211], v219 offset:56320
	s_barrier
	s_setprio 1
	s_waitcnt lgkmcnt(0)
	v_mfma_f32_16x16x32_bf16 v[110:113], v[130:133], v[180:183], v[110:113]
	v_mfma_f32_16x16x32_bf16 v[78:81], v[138:141], v[180:183], v[78:81]
	v_mfma_f32_16x16x32_bf16 v[106:109], v[130:133], v[188:191], v[106:109]
	v_mfma_f32_16x16x32_bf16 v[74:77], v[138:141], v[188:191], v[74:77]
	v_mfma_f32_16x16x32_bf16 v[102:105], v[130:133], v[196:199], v[102:105]
	v_mfma_f32_16x16x32_bf16 v[70:73], v[138:141], v[196:199], v[70:73]
	v_mfma_f32_16x16x32_bf16 v[98:101], v[130:133], v[204:207], v[98:101]
	v_mfma_f32_16x16x32_bf16 v[66:69], v[138:141], v[204:207], v[66:69]
	v_mfma_f32_16x16x32_bf16 v[110:113], v[134:137], v[184:187], v[110:113]
	v_mfma_f32_16x16x32_bf16 v[78:81], v[142:145], v[184:187], v[78:81]
	v_mfma_f32_16x16x32_bf16 v[106:109], v[134:137], v[192:195], v[106:109]
	v_mfma_f32_16x16x32_bf16 v[74:77], v[142:145], v[192:195], v[74:77]
	v_mfma_f32_16x16x32_bf16 v[102:105], v[134:137], v[200:203], v[102:105]
	v_mfma_f32_16x16x32_bf16 v[70:73], v[142:145], v[200:203], v[70:73]
	v_mfma_f32_16x16x32_bf16 v[98:101], v[134:137], v[208:211], v[98:101]
	v_mfma_f32_16x16x32_bf16 v[66:69], v[142:145], v[208:211], v[66:69]
	s_setprio 0
	s_setprio 1
	v_mfma_f32_16x16x32_bf16 v[46:49], v[146:149], v[180:183], v[46:49]
	v_mfma_f32_16x16x32_bf16 v[14:17], v[154:157], v[180:183], v[14:17]
	v_mfma_f32_16x16x32_bf16 v[42:45], v[146:149], v[188:191], v[42:45]
	v_mfma_f32_16x16x32_bf16 v[10:13], v[154:157], v[188:191], v[10:13]
	v_mfma_f32_16x16x32_bf16 v[38:41], v[146:149], v[196:199], v[38:41]
	v_mfma_f32_16x16x32_bf16 v[6:9], v[154:157], v[196:199], v[6:9]
	v_mfma_f32_16x16x32_bf16 v[34:37], v[146:149], v[204:207], v[34:37]
	v_mfma_f32_16x16x32_bf16 v[2:5], v[154:157], v[204:207], v[2:5]
	v_mfma_f32_16x16x32_bf16 v[46:49], v[150:153], v[184:187], v[46:49]
	v_mfma_f32_16x16x32_bf16 v[14:17], v[158:161], v[184:187], v[14:17]
	v_mfma_f32_16x16x32_bf16 v[42:45], v[150:153], v[192:195], v[42:45]
	v_mfma_f32_16x16x32_bf16 v[10:13], v[158:161], v[192:195], v[10:13]
	v_mfma_f32_16x16x32_bf16 v[38:41], v[150:153], v[200:203], v[38:41]
	v_mfma_f32_16x16x32_bf16 v[6:9], v[158:161], v[200:203], v[6:9]
	v_mfma_f32_16x16x32_bf16 v[34:37], v[150:153], v[208:211], v[34:37]
	v_mfma_f32_16x16x32_bf16 v[2:5], v[158:161], v[208:211], v[2:5]
	s_waitcnt vmcnt(8)
	s_barrier
	s_setprio 0
	s_cbranch_scc0 .LBB0_199
	s_branch .Lmy_d199X
; #define PG8_STAGE(bufoff, gbase, voff) do { _Pragma("unroll") for (int _i = 0; _i < 2; ++_i) \
;         __builtin_amdgcn_global_load_lds((const unsigned*)((const char*)(gbase) + (voff)[_i]), (LAS unsigned*)(lds + (bufoff) + ldsw + _i * 8192), 16, 0, 0); } while (0)
; #define PG8_LDA(dst, b, h) do { _Pragma("unroll") for (int m = 0; m < 4; ++m) _Pragma("unroll") for (int k = 0; k < 2; ++k) dst[m][k] = *(const LAS bf16x8*)(lds + PG8_SA(b, h) + aoff + m * 2048 + k * 1024); } while (0)
; #define PG8_LDB(dst, b, h) do { _Pragma("unroll") for (int n = 0; n < 2; ++n) _Pragma("unroll") for (int k = 0; k < 2; ++k) dst[n][k] = *(const LAS bf16x8*)(lds + PG8_SB(b, h) + boff + n * 2048 + k * 1024); } while (0)
; #define PG8_MMA(ai, bj, At, Bt) do { __builtin_amdgcn_s_setprio(1); _Pragma("unroll") for (int m = 0; m < 4; ++m) _Pragma("unroll") for (int n = 0; n < 2; ++n) _Pragma("unroll") for (int k = 0; k < 2; ++k) \
;         acc[ai][bj][m][n] = __builtin_amdgcn_mfma_f32_16x16x32_bf16(Bt[n][k], At[m][k], acc[ai][bj][m][n], 0, 0, 0); __builtin_amdgcn_s_setprio(0); } while (0)
; #define PG8_WAIT_V(n) asm volatile("s_waitcnt vmcnt(" #n ")" ::: "memory")
; #define PG8_WAIT_L(n) asm volatile("s_waitcnt lgkmcnt(" #n ")" ::: "memory")
; template <class Epi, class Sched, bool ALIGN_EPI, class Hook = NoHook>
; __device__ __forceinline__ void gemm_phase(LAS unsigned char* lds, const Gemm g, const Sched& S, const Epi& E, const Hook& H = Hook()) {
;     ...
;         for (int t = tb; t < te; t += 2) {
;             const bool last = (t == nt - 2);
;             const char* a1 = cA + (size_t)(t + 1) * kstep;
;             const char* a2 = last ? nA : cA + (size_t)(t + 2) * kstep; const char* b2 = last ? nB : cB + (size_t)(t + 2) * kstep;
;             const char* a3 = a2 + kstep; const char* b3 = b2 + kstep;
;             if (last && has_next) S.a_ready(nxt);
;             PG8_LDB(B0, 0, 0); PG8_LDB(B1, 0, 1); PG8_SCHED; PG8_LDA(At, 0, 0); PG8_STAGE(PG8_SA(1, 1), a1 + hA, voffA);
;             PG8_WAIT_V(8); PG8_WAIT_L(0); PG8_BAR; PG8_MMA(0, 0, At, B0); PG8_MMA(0, 1, At, B1); PG8_BAR; PG8_SCHED;
;             PG8_LDA(At, 0, 1); PG8_STAGE(PG8_SB(0, 0), b2, voffB); PG8_STAGE(PG8_SB(0, 1), b2 + hB, voffB); PG8_STAGE(PG8_SA(0, 0), a2, voffA);
;             PG8_WAIT_V(8); PG8_WAIT_L(0); PG8_BAR; PG8_MMA(1, 0, At, B0); PG8_MMA(1, 1, At, B1); PG8_BAR; PG8_SCHED;
.Lmy_d199B:
	ds_read_b128 v[130:133], v217
	ds_read_b128 v[134:137], v217 offset:1024
	s_add_i32 m0, s40, 0xc000
	ds_read_b128 v[138:141], v217 offset:2048
	global_load_lds_dwordx4 v172, s[4:5]
	ds_read_b128 v[142:145], v217 offset:3072
	ds_read_b128 v[146:149], v218
	ds_read_b128 v[150:153], v218 offset:1024
	ds_read_b128 v[154:157], v218 offset:2048
	ds_read_b128 v[158:161], v218 offset:3072
	ds_read_b128 v[180:183], v219
	s_add_i32 m0, s40, 0xe000
	s_nop 0
	global_load_lds_dwordx4 v174, s[4:5]
	s_add_u32 s34, s4, 0x100
	s_addc_u32 s35, s5, 0
	s_cmp_eq_u32 s64, 60
	s_cselect_b32 s39, s7, s35
	s_cselect_b32 s38, s8, s34
	s_cselect_b32 s37, s23, s63
	s_cselect_b32 s36, s25, s31
	ds_read_b128 v[184:187], v219 offset:1024
	ds_read_b128 v[188:191], v219 offset:2048
	ds_read_b128 v[192:195], v219 offset:3072
	ds_read_b128 v[196:199], v219 offset:4096
	ds_read_b128 v[200:203], v219 offset:5120
	ds_read_b128 v[204:207], v219 offset:6144
	ds_read_b128 v[208:211], v219 offset:7168
	s_waitcnt vmcnt(8) lgkmcnt(0)
	s_barrier
	s_setprio 1
	v_mfma_f32_16x16x32_bf16 v[126:129], v[130:133], v[180:183], v[126:129]
	v_mfma_f32_16x16x32_bf16 v[94:97], v[138:141], v[180:183], v[94:97]
	v_mfma_f32_16x16x32_bf16 v[122:125], v[130:133], v[188:191], v[122:125]
	v_mfma_f32_16x16x32_bf16 v[90:93], v[138:141], v[188:191], v[90:93]
	v_mfma_f32_16x16x32_bf16 v[118:121], v[130:133], v[196:199], v[118:121]
	v_mfma_f32_16x16x32_bf16 v[86:89], v[138:141], v[196:199], v[86:89]
	v_mfma_f32_16x16x32_bf16 v[114:117], v[130:133], v[204:207], v[114:117]
	v_mfma_f32_16x16x32_bf16 v[82:85], v[138:141], v[204:207], v[82:85]
	v_mfma_f32_16x16x32_bf16 v[126:129], v[134:137], v[184:187], v[126:129]
	v_mfma_f32_16x16x32_bf16 v[94:97], v[142:145], v[184:187], v[94:97]
	v_mfma_f32_16x16x32_bf16 v[122:125], v[134:137], v[192:195], v[122:125]
	v_mfma_f32_16x16x32_bf16 v[90:93], v[142:145], v[192:195], v[90:93]
	v_mfma_f32_16x16x32_bf16 v[118:121], v[134:137], v[200:203], v[118:121]
	v_mfma_f32_16x16x32_bf16 v[86:89], v[142:145], v[200:203], v[86:89]
	v_mfma_f32_16x16x32_bf16 v[114:117], v[134:137], v[208:211], v[114:117]
	v_mfma_f32_16x16x32_bf16 v[82:85], v[142:145], v[208:211], v[82:85]
	s_setprio 0
	s_setprio 1
	v_mfma_f32_16x16x32_bf16 v[62:65], v[146:149], v[180:183], v[62:65]
	v_mfma_f32_16x16x32_bf16 v[30:33], v[154:157], v[180:183], v[30:33]
	v_mfma_f32_16x16x32_bf16 v[58:61], v[146:149], v[188:191], v[58:61]
	v_mfma_f32_16x16x32_bf16 v[26:29], v[154:157], v[188:191], v[26:29]
	v_mfma_f32_16x16x32_bf16 v[54:57], v[146:149], v[196:199], v[54:57]
	v_mfma_f32_16x16x32_bf16 v[22:25], v[154:157], v[196:199], v[22:25]
	v_mfma_f32_16x16x32_bf16 v[50:53], v[146:149], v[204:207], v[50:53]
	v_mfma_f32_16x16x32_bf16 v[18:21], v[154:157], v[204:207], v[18:21]
	v_mfma_f32_16x16x32_bf16 v[62:65], v[150:153], v[184:187], v[62:65]
	v_mfma_f32_16x16x32_bf16 v[30:33], v[158:161], v[184:187], v[30:33]
	v_mfma_f32_16x16x32_bf16 v[58:61], v[150:153], v[192:195], v[58:61]
	v_mfma_f32_16x16x32_bf16 v[26:29], v[158:161], v[192:195], v[26:29]
	v_mfma_f32_16x16x32_bf16 v[54:57], v[150:153], v[200:203], v[54:57]
	v_mfma_f32_16x16x32_bf16 v[22:25], v[158:161], v[200:203], v[22:25]
	v_mfma_f32_16x16x32_bf16 v[50:53], v[150:153], v[208:211], v[50:53]
	v_mfma_f32_16x16x32_bf16 v[18:21], v[158:161], v[208:211], v[18:21]
	s_barrier
	s_setprio 0
	s_add_i32 s4, s59, s21
	s_mov_b32 m0, s4
	ds_read_b128 v[180:183], v219 offset:16384
	ds_read_b128 v[184:187], v219 offset:17408
	global_load_lds_dwordx4 v164, s[36:37]
	ds_read_b128 v[188:191], v219 offset:18432
	s_add_i32 m0, s4, 0x2000
	s_add_u32 s4, s36, 0x100000
	s_addc_u32 s5, s37, 0
	s_add_i32 s65, s60, s21
	global_load_lds_dwordx4 v168, s[36:37]
	ds_read_b128 v[192:195], v219 offset:19456
	s_mov_b32 m0, s65
	ds_read_b128 v[196:199], v219 offset:20480
	global_load_lds_dwordx4 v164, s[4:5]
	s_add_i32 m0, s65, 0x2000
	ds_read_b128 v[200:203], v219 offset:21504
	global_load_lds_dwordx4 v168, s[4:5]
	s_mov_b32 m0, s40
	ds_read_b128 v[204:207], v219 offset:22528
	global_load_lds_dwordx4 v162, s[38:39]
	s_mov_b32 m0, s41
	ds_read_b128 v[208:211], v219 offset:23552
	global_load_lds_dwordx4 v166, s[38:39]
	s_waitcnt vmcnt(8) lgkmcnt(0)
	s_barrier
	s_setprio 1
	v_mfma_f32_16x16x32_bf16 v[110:113], v[130:133], v[180:183], v[110:113]
	v_mfma_f32_16x16x32_bf16 v[78:81], v[138:141], v[180:183], v[78:81]
	v_mfma_f32_16x16x32_bf16 v[106:109], v[130:133], v[188:191], v[106:109]
	v_mfma_f32_16x16x32_bf16 v[74:77], v[138:141], v[188:191], v[74:77]
	v_mfma_f32_16x16x32_bf16 v[102:105], v[130:133], v[196:199], v[102:105]
	v_mfma_f32_16x16x32_bf16 v[70:73], v[138:141], v[196:199], v[70:73]
	v_mfma_f32_16x16x32_bf16 v[98:101], v[130:133], v[204:207], v[98:101]
	v_mfma_f32_16x16x32_bf16 v[66:69], v[138:141], v[204:207], v[66:69]
	v_mfma_f32_16x16x32_bf16 v[110:113], v[134:137], v[184:187], v[110:113]
	v_mfma_f32_16x16x32_bf16 v[78:81], v[142:145], v[184:187], v[78:81]
	v_mfma_f32_16x16x32_bf16 v[106:109], v[134:137], v[192:195], v[106:109]
	v_mfma_f32_16x16x32_bf16 v[74:77], v[142:145], v[192:195], v[74:77]
	v_mfma_f32_16x16x32_bf16 v[102:105], v[134:137], v[200:203], v[102:105]
	v_mfma_f32_16x16x32_bf16 v[70:73], v[142:145], v[200:203], v[70:73]
	v_mfma_f32_16x16x32_bf16 v[98:101], v[134:137], v[208:211], v[98:101]
	v_mfma_f32_16x16x32_bf16 v[66:69], v[142:145], v[208:211], v[66:69]
	s_setprio 0
	s_setprio 1
	v_mfma_f32_16x16x32_bf16 v[46:49], v[146:149], v[180:183], v[46:49]
	v_mfma_f32_16x16x32_bf16 v[14:17], v[154:157], v[180:183], v[14:17]
	v_mfma_f32_16x16x32_bf16 v[42:45], v[146:149], v[188:191], v[42:45]
	v_mfma_f32_16x16x32_bf16 v[10:13], v[154:157], v[188:191], v[10:13]
	v_mfma_f32_16x16x32_bf16 v[38:41], v[146:149], v[196:199], v[38:41]
	v_mfma_f32_16x16x32_bf16 v[6:9], v[154:157], v[196:199], v[6:9]
	v_mfma_f32_16x16x32_bf16 v[34:37], v[146:149], v[204:207], v[34:37]
	v_mfma_f32_16x16x32_bf16 v[2:5], v[154:157], v[204:207], v[2:5]
	v_mfma_f32_16x16x32_bf16 v[46:49], v[150:153], v[184:187], v[46:49]
	v_mfma_f32_16x16x32_bf16 v[14:17], v[158:161], v[184:187], v[14:17]
	v_mfma_f32_16x16x32_bf16 v[42:45], v[150:153], v[192:195], v[42:45]
	v_mfma_f32_16x16x32_bf16 v[10:13], v[158:161], v[192:195], v[10:13]
	v_mfma_f32_16x16x32_bf16 v[38:41], v[150:153], v[200:203], v[38:41]
	v_mfma_f32_16x16x32_bf16 v[6:9], v[158:161], v[200:203], v[6:9]
	v_mfma_f32_16x16x32_bf16 v[34:37], v[150:153], v[208:211], v[34:37]
	v_mfma_f32_16x16x32_bf16 v[2:5], v[158:161], v[208:211], v[2:5]
	s_barrier
; #define PG8_STAGE(bufoff, gbase, voff) do { _Pragma("unroll") for (int _i = 0; _i < 2; ++_i) \
;         __builtin_amdgcn_global_load_lds((const unsigned*)((const char*)(gbase) + (voff)[_i]), (LAS unsigned*)(lds + (bufoff) + ldsw + _i * 8192), 16, 0, 0); } while (0)
; #define PG8_LDA(dst, b, h) do { _Pragma("unroll") for (int m = 0; m < 4; ++m) _Pragma("unroll") for (int k = 0; k < 2; ++k) dst[m][k] = *(const LAS bf16x8*)(lds + PG8_SA(b, h) + aoff + m * 2048 + k * 1024); } while (0)
; #define PG8_LDB(dst, b, h) do { _Pragma("unroll") for (int n = 0; n < 2; ++n) _Pragma("unroll") for (int k = 0; k < 2; ++k) dst[n][k] = *(const LAS bf16x8*)(lds + PG8_SB(b, h) + boff + n * 2048 + k * 1024); } while (0)
; #define PG8_MMA(ai, bj, At, Bt) do { __builtin_amdgcn_s_setprio(1); _Pragma("unroll") for (int m = 0; m < 4; ++m) _Pragma("unroll") for (int n = 0; n < 2; ++n) _Pragma("unroll") for (int k = 0; k < 2; ++k) \
;         acc[ai][bj][m][n] = __builtin_amdgcn_mfma_f32_16x16x32_bf16(Bt[n][k], At[m][k], acc[ai][bj][m][n], 0, 0, 0); __builtin_amdgcn_s_setprio(0); } while (0)
; #define PG8_WAIT_V(n) asm volatile("s_waitcnt vmcnt(" #n ")" ::: "memory")
; #define PG8_WAIT_L(n) asm volatile("s_waitcnt lgkmcnt(" #n ")" ::: "memory")
; #define PG8_BAR __builtin_amdgcn_s_barrier()
; #define PG8_SCHED __builtin_amdgcn_sched_barrier(0)
; template <class Epi, class Sched, bool ALIGN_EPI, class Hook = NoHook>
; __device__ __forceinline__ void gemm_phase(LAS unsigned char* lds, const Gemm g, const Sched& S, const Epi& E, const Hook& H = Hook()) {
;     ...
;             PG8_LDB(B0, 1, 0); PG8_LDB(B1, 1, 1); PG8_SCHED; PG8_LDA(At, 1, 0); PG8_STAGE(PG8_SA(0, 1), a2 + hA, voffA);
;             PG8_WAIT_V(8); PG8_WAIT_L(0); PG8_BAR; PG8_MMA(0, 0, At, B0); PG8_MMA(0, 1, At, B1); PG8_BAR; PG8_SCHED;
;             PG8_LDA(At, 1, 1); PG8_STAGE(PG8_SB(1, 0), b3, voffB); PG8_STAGE(PG8_SB(1, 1), b3 + hB, voffB); PG8_STAGE(PG8_SA(1, 0), a3, voffA);
;             PG8_WAIT_V(8); PG8_WAIT_L(0); PG8_BAR; PG8_MMA(1, 0, At, B0); PG8_MMA(1, 1, At, B1); PG8_BAR; PG8_SCHED;
;         }
	s_setprio 0
	v_add_u32_e32 v142, 0x18000, v213
	v_add_u32_e32 v158, 0x1c000, v213
	ds_read_b128 v[130:133], v142
	ds_read_b128 v[134:137], v142 offset:1024
	s_add_u32 s4, s38, 0x8000
	s_addc_u32 s5, s39, 0
	s_mov_b32 m0, s42
	ds_read_b128 v[138:141], v142 offset:2048
	global_load_lds_dwordx4 v162, s[4:5]
	ds_read_b128 v[142:145], v142 offset:3072
	ds_read_b128 v[146:149], v158
	ds_read_b128 v[150:153], v158 offset:1024
	ds_read_b128 v[154:157], v158 offset:2048
	ds_read_b128 v[158:161], v158 offset:3072
	ds_read_b128 v[180:183], v219 offset:32768
	s_mov_b32 m0, s43
	ds_read_b128 v[184:187], v219 offset:33792
	global_load_lds_dwordx4 v166, s[4:5]
	ds_read_b128 v[188:191], v219 offset:34816
	ds_read_b128 v[192:195], v219 offset:35840
	ds_read_b128 v[196:199], v219 offset:36864
	ds_read_b128 v[200:203], v219 offset:37888
	ds_read_b128 v[204:207], v219 offset:38912
	ds_read_b128 v[208:211], v219 offset:39936
	s_waitcnt vmcnt(8) lgkmcnt(0)
	s_barrier
	s_setprio 1
	v_mfma_f32_16x16x32_bf16 v[126:129], v[130:133], v[180:183], v[126:129]
	v_mfma_f32_16x16x32_bf16 v[94:97], v[138:141], v[180:183], v[94:97]
	v_mfma_f32_16x16x32_bf16 v[122:125], v[130:133], v[188:191], v[122:125]
	v_mfma_f32_16x16x32_bf16 v[90:93], v[138:141], v[188:191], v[90:93]
	v_mfma_f32_16x16x32_bf16 v[118:121], v[130:133], v[196:199], v[118:121]
	v_mfma_f32_16x16x32_bf16 v[86:89], v[138:141], v[196:199], v[86:89]
	v_mfma_f32_16x16x32_bf16 v[114:117], v[130:133], v[204:207], v[114:117]
	v_mfma_f32_16x16x32_bf16 v[82:85], v[138:141], v[204:207], v[82:85]
	v_mfma_f32_16x16x32_bf16 v[126:129], v[134:137], v[184:187], v[126:129]
	v_mfma_f32_16x16x32_bf16 v[94:97], v[142:145], v[184:187], v[94:97]
	v_mfma_f32_16x16x32_bf16 v[122:125], v[134:137], v[192:195], v[122:125]
	v_mfma_f32_16x16x32_bf16 v[90:93], v[142:145], v[192:195], v[90:93]
	v_mfma_f32_16x16x32_bf16 v[118:121], v[134:137], v[200:203], v[118:121]
	v_mfma_f32_16x16x32_bf16 v[86:89], v[142:145], v[200:203], v[86:89]
	v_mfma_f32_16x16x32_bf16 v[114:117], v[134:137], v[208:211], v[114:117]
	v_mfma_f32_16x16x32_bf16 v[82:85], v[142:145], v[208:211], v[82:85]
	s_setprio 0
	s_setprio 1
	v_mfma_f32_16x16x32_bf16 v[62:65], v[146:149], v[180:183], v[62:65]
	v_mfma_f32_16x16x32_bf16 v[30:33], v[154:157], v[180:183], v[30:33]
	v_mfma_f32_16x16x32_bf16 v[58:61], v[146:149], v[188:191], v[58:61]
	v_mfma_f32_16x16x32_bf16 v[26:29], v[154:157], v[188:191], v[26:29]
	v_mfma_f32_16x16x32_bf16 v[54:57], v[146:149], v[196:199], v[54:57]
	v_mfma_f32_16x16x32_bf16 v[22:25], v[154:157], v[196:199], v[22:25]
	v_mfma_f32_16x16x32_bf16 v[50:53], v[146:149], v[204:207], v[50:53]
	v_mfma_f32_16x16x32_bf16 v[18:21], v[154:157], v[204:207], v[18:21]
	v_mfma_f32_16x16x32_bf16 v[62:65], v[150:153], v[184:187], v[62:65]
	v_mfma_f32_16x16x32_bf16 v[30:33], v[158:161], v[184:187], v[30:33]
	v_mfma_f32_16x16x32_bf16 v[58:61], v[150:153], v[192:195], v[58:61]
	v_mfma_f32_16x16x32_bf16 v[26:29], v[158:161], v[192:195], v[26:29]
	v_mfma_f32_16x16x32_bf16 v[54:57], v[150:153], v[200:203], v[54:57]
	v_mfma_f32_16x16x32_bf16 v[22:25], v[158:161], v[200:203], v[22:25]
	v_mfma_f32_16x16x32_bf16 v[50:53], v[150:153], v[208:211], v[50:53]
	v_mfma_f32_16x16x32_bf16 v[18:21], v[158:161], v[208:211], v[18:21]
	s_barrier
	s_setprio 0
	s_add_i32 s4, s21, 0x18000
	s_add_u32 s68, s36, s14
	s_addc_u32 s69, s37, s15
	s_mov_b32 m0, s4
	ds_read_b128 v[180:183], v219 offset:49152
	ds_read_b128 v[184:187], v219 offset:50176
	global_load_lds_dwordx4 v164, s[68:69]
	ds_read_b128 v[188:191], v219 offset:51200
	s_add_i32 m0, s4, 0x2000
	s_add_u32 s4, s36, 0x100080
	s_addc_u32 s5, s37, 0
	s_add_i32 s36, s21, 0x1c000
	global_load_lds_dwordx4 v168, s[68:69]
	ds_read_b128 v[192:195], v219 offset:52224
	s_mov_b32 m0, s36
	ds_read_b128 v[196:199], v219 offset:53248
	global_load_lds_dwordx4 v164, s[4:5]
	s_add_i32 m0, s36, 0x2000
	ds_read_b128 v[200:203], v219 offset:54272
	global_load_lds_dwordx4 v168, s[4:5]
	s_add_u32 s70, s38, s14
	s_addc_u32 s71, s39, s15
	s_mov_b32 m0, s51
	ds_read_b128 v[204:207], v219 offset:55296
	global_load_lds_dwordx4 v162, s[70:71]
	s_mov_b32 m0, s52
	s_nop 0
	global_load_lds_dwordx4 v166, s[70:71]
	s_add_i32 s64, s64, 2
	s_add_u32 s31, s31, 0x100
	s_addc_u32 s63, s63, 0
	s_cmp_gt_u32 s64, 61
	s_mov_b64 s[4:5], s[34:35]
	ds_read_b128 v[208:211], v219 offset:56320
	s_waitcnt vmcnt(8) lgkmcnt(0)
	s_barrier
	s_setprio 1
	v_mfma_f32_16x16x32_bf16 v[110:113], v[130:133], v[180:183], v[110:113]
	v_mfma_f32_16x16x32_bf16 v[78:81], v[138:141], v[180:183], v[78:81]
	v_mfma_f32_16x16x32_bf16 v[106:109], v[130:133], v[188:191], v[106:109]
	v_mfma_f32_16x16x32_bf16 v[74:77], v[138:141], v[188:191], v[74:77]
	v_mfma_f32_16x16x32_bf16 v[102:105], v[130:133], v[196:199], v[102:105]
	v_mfma_f32_16x16x32_bf16 v[70:73], v[138:141], v[196:199], v[70:73]
	v_mfma_f32_16x16x32_bf16 v[98:101], v[130:133], v[204:207], v[98:101]
	v_mfma_f32_16x16x32_bf16 v[66:69], v[138:141], v[204:207], v[66:69]
	v_mfma_f32_16x16x32_bf16 v[110:113], v[134:137], v[184:187], v[110:113]
	v_mfma_f32_16x16x32_bf16 v[78:81], v[142:145], v[184:187], v[78:81]
	v_mfma_f32_16x16x32_bf16 v[106:109], v[134:137], v[192:195], v[106:109]
	v_mfma_f32_16x16x32_bf16 v[74:77], v[142:145], v[192:195], v[74:77]
	v_mfma_f32_16x16x32_bf16 v[102:105], v[134:137], v[200:203], v[102:105]
	v_mfma_f32_16x16x32_bf16 v[70:73], v[142:145], v[200:203], v[70:73]
	v_mfma_f32_16x16x32_bf16 v[98:101], v[134:137], v[208:211], v[98:101]
	v_mfma_f32_16x16x32_bf16 v[66:69], v[142:145], v[208:211], v[66:69]
	s_setprio 0
	s_setprio 1
	v_mfma_f32_16x16x32_bf16 v[46:49], v[146:149], v[180:183], v[46:49]
	v_mfma_f32_16x16x32_bf16 v[14:17], v[154:157], v[180:183], v[14:17]
	v_mfma_f32_16x16x32_bf16 v[42:45], v[146:149], v[188:191], v[42:45]
	v_mfma_f32_16x16x32_bf16 v[10:13], v[154:157], v[188:191], v[10:13]
	v_mfma_f32_16x16x32_bf16 v[38:41], v[146:149], v[196:199], v[38:41]
	v_mfma_f32_16x16x32_bf16 v[6:9], v[154:157], v[196:199], v[6:9]
	v_mfma_f32_16x16x32_bf16 v[34:37], v[146:149], v[204:207], v[34:37]
	v_mfma_f32_16x16x32_bf16 v[2:5], v[154:157], v[204:207], v[2:5]
	v_mfma_f32_16x16x32_bf16 v[46:49], v[150:153], v[184:187], v[46:49]
	v_mfma_f32_16x16x32_bf16 v[14:17], v[158:161], v[184:187], v[14:17]
	v_mfma_f32_16x16x32_bf16 v[42:45], v[150:153], v[192:195], v[42:45]
	v_mfma_f32_16x16x32_bf16 v[10:13], v[158:161], v[192:195], v[10:13]
	v_mfma_f32_16x16x32_bf16 v[38:41], v[150:153], v[200:203], v[38:41]
	v_mfma_f32_16x16x32_bf16 v[6:9], v[158:161], v[200:203], v[6:9]
	v_mfma_f32_16x16x32_bf16 v[34:37], v[150:153], v[208:211], v[34:37]
	v_mfma_f32_16x16x32_bf16 v[2:5], v[158:161], v[208:211], v[2:5]
	s_barrier
	s_setprio 0
	s_cbranch_scc0 .Lmy_d199B

; #define PG8_STAGE(bufoff, gbase, voff) do { _Pragma("unroll") for (int _i = 0; _i < 2; ++_i) \
;         __builtin_amdgcn_global_load_lds((const unsigned*)((const char*)(gbase) + (voff)[_i]), (LAS unsigned*)(lds + (bufoff) + ldsw + _i * 8192), 16, 0, 0); } while (0)
; #define PG8_LDA(dst, b, h) do { _Pragma("unroll") for (int m = 0; m < 4; ++m) _Pragma("unroll") for (int k = 0; k < 2; ++k) dst[m][k] = *(const LAS bf16x8*)(lds + PG8_SA(b, h) + aoff + m * 2048 + k * 1024); } while (0)
; #define PG8_LDB(dst, b, h) do { _Pragma("unroll") for (int n = 0; n < 2; ++n) _Pragma("unroll") for (int k = 0; k < 2; ++k) dst[n][k] = *(const LAS bf16x8*)(lds + PG8_SB(b, h) + boff + n * 2048 + k * 1024); } while (0)
; #define PG8_MMA(ai, bj, At, Bt) do { __builtin_amdgcn_s_setprio(1); _Pragma("unroll") for (int m = 0; m < 4; ++m) _Pragma("unroll") for (int n = 0; n < 2; ++n) _Pragma("unroll") for (int k = 0; k < 2; ++k) \
;         acc[ai][bj][m][n] = __builtin_amdgcn_mfma_f32_16x16x32_bf16(Bt[n][k], At[m][k], acc[ai][bj][m][n], 0, 0, 0); __builtin_amdgcn_s_setprio(0); } while (0)
; #define PG8_WAIT_V(n) asm volatile("s_waitcnt vmcnt(" #n ")" ::: "memory")
; #define PG8_WAIT_L(n) asm volatile("s_waitcnt lgkmcnt(" #n ")" ::: "memory")
; template <class Epi, class Sched, bool ALIGN_EPI, class Hook = NoHook>
; __device__ __forceinline__ void gemm_phase(LAS unsigned char* lds, const Gemm g, const Sched& S, const Epi& E, const Hook& H = Hook()) {
;     ...
;         for (int t = tb; t < te; t += 2) {
;             const bool last = (t == nt - 2);
;             const char* a1 = cA + (size_t)(t + 1) * kstep;
;             const char* a2 = last ? nA : cA + (size_t)(t + 2) * kstep; const char* b2 = last ? nB : cB + (size_t)(t + 2) * kstep;
;             const char* a3 = a2 + kstep; const char* b3 = b2 + kstep;
;             if (last && has_next) S.a_ready(nxt);
;             PG8_LDB(B0, 0, 0); PG8_LDB(B1, 0, 1); PG8_SCHED; PG8_LDA(At, 0, 0); PG8_STAGE(PG8_SA(1, 1), a1 + hA, voffA);
;             PG8_WAIT_V(8); PG8_WAIT_L(0); PG8_BAR; PG8_MMA(0, 0, At, B0); PG8_MMA(0, 1, At, B1); PG8_BAR; PG8_SCHED;
;             PG8_LDA(At, 0, 1); PG8_STAGE(PG8_SB(0, 0), b2, voffB); PG8_STAGE(PG8_SB(0, 1), b2 + hB, voffB); PG8_STAGE(PG8_SA(0, 0), a2, voffA);
;             PG8_WAIT_V(8); PG8_WAIT_L(0); PG8_BAR; PG8_MMA(1, 0, At, B0); PG8_MMA(1, 1, At, B1); PG8_BAR; PG8_SCHED;
.LBB0_262:
	ds_read_b128 v[148:151], v145
	ds_read_b128 v[152:155], v145 offset:1024
	s_add_u32 s22, s20, 0xfff00080
	s_addc_u32 s23, s21, -1
	s_cmp_eq_u32 s50, 4
	s_cselect_b32 s25, s11, s23
	s_cselect_b32 s24, s13, s22
	s_cselect_b32 s23, s40, s43
	s_cselect_b32 s22, s41, s42
	s_add_i32 m0, s5, 0xc000
	ds_read_b128 v[156:159], v145 offset:2048
	global_load_lds_dwordx4 v136, s[20:21]
	ds_read_b128 v[160:163], v145 offset:3072
	ds_read_b128 v[164:167], v146
	ds_read_b128 v[168:171], v146 offset:1024
	ds_read_b128 v[172:175], v146 offset:2048
	ds_read_b128 v[176:179], v146 offset:3072
	ds_read_b128 v[180:183], v147
	s_add_i32 m0, s5, 0xe000
	ds_read_b128 v[184:187], v147 offset:1024
	global_load_lds_dwordx4 v138, s[20:21]
	ds_read_b128 v[188:191], v147 offset:2048
	ds_read_b128 v[192:195], v147 offset:3072
	ds_read_b128 v[196:199], v147 offset:4096
	ds_read_b128 v[200:203], v147 offset:5120
	ds_read_b128 v[204:207], v147 offset:6144
	ds_read_b128 v[208:211], v147 offset:7168
	s_waitcnt vmcnt(8) lgkmcnt(0)
	s_barrier
	s_setprio 1
	v_mfma_f32_16x16x32_bf16 v[126:129], v[148:151], v[180:183], v[126:129]
	v_mfma_f32_16x16x32_bf16 v[122:125], v[156:159], v[180:183], v[122:125]
	v_mfma_f32_16x16x32_bf16 v[118:121], v[148:151], v[188:191], v[118:121]
	v_mfma_f32_16x16x32_bf16 v[114:117], v[156:159], v[188:191], v[114:117]
	v_mfma_f32_16x16x32_bf16 v[106:109], v[148:151], v[196:199], v[106:109]
	v_mfma_f32_16x16x32_bf16 v[98:101], v[156:159], v[196:199], v[98:101]
	v_mfma_f32_16x16x32_bf16 v[90:93], v[148:151], v[204:207], v[90:93]
	v_mfma_f32_16x16x32_bf16 v[82:85], v[156:159], v[204:207], v[82:85]
	v_mfma_f32_16x16x32_bf16 v[126:129], v[152:155], v[184:187], v[126:129]
	v_mfma_f32_16x16x32_bf16 v[122:125], v[160:163], v[184:187], v[122:125]
	v_mfma_f32_16x16x32_bf16 v[118:121], v[152:155], v[192:195], v[118:121]
	v_mfma_f32_16x16x32_bf16 v[114:117], v[160:163], v[192:195], v[114:117]
	v_mfma_f32_16x16x32_bf16 v[106:109], v[152:155], v[200:203], v[106:109]
	v_mfma_f32_16x16x32_bf16 v[98:101], v[160:163], v[200:203], v[98:101]
	v_mfma_f32_16x16x32_bf16 v[90:93], v[152:155], v[208:211], v[90:93]
	v_mfma_f32_16x16x32_bf16 v[82:85], v[160:163], v[208:211], v[82:85]
	s_setprio 0
	s_setprio 1
	v_mfma_f32_16x16x32_bf16 v[110:113], v[164:167], v[180:183], v[110:113]
	v_mfma_f32_16x16x32_bf16 v[102:105], v[172:175], v[180:183], v[102:105]
	v_mfma_f32_16x16x32_bf16 v[94:97], v[164:167], v[188:191], v[94:97]
	v_mfma_f32_16x16x32_bf16 v[86:89], v[172:175], v[188:191], v[86:89]
	v_mfma_f32_16x16x32_bf16 v[78:81], v[164:167], v[196:199], v[78:81]
	v_mfma_f32_16x16x32_bf16 v[74:77], v[172:175], v[196:199], v[74:77]
	v_mfma_f32_16x16x32_bf16 v[70:73], v[164:167], v[204:207], v[70:73]
	v_mfma_f32_16x16x32_bf16 v[66:69], v[172:175], v[204:207], v[66:69]
	v_mfma_f32_16x16x32_bf16 v[110:113], v[168:171], v[184:187], v[110:113]
	v_mfma_f32_16x16x32_bf16 v[102:105], v[176:179], v[184:187], v[102:105]
	v_mfma_f32_16x16x32_bf16 v[94:97], v[168:171], v[192:195], v[94:97]
	v_mfma_f32_16x16x32_bf16 v[86:89], v[176:179], v[192:195], v[86:89]
	v_mfma_f32_16x16x32_bf16 v[78:81], v[168:171], v[200:203], v[78:81]
	v_mfma_f32_16x16x32_bf16 v[74:77], v[176:179], v[200:203], v[74:77]
	v_mfma_f32_16x16x32_bf16 v[70:73], v[168:171], v[208:211], v[70:73]
	v_mfma_f32_16x16x32_bf16 v[66:69], v[176:179], v[208:211], v[66:69]
	s_barrier
	s_setprio 0
	s_add_i32 s51, s38, s29
	s_mov_b32 m0, s51
	ds_read_b128 v[180:183], v147 offset:16384
	ds_read_b128 v[184:187], v147 offset:17408
	global_load_lds_dwordx4 v132, s[22:23]
	ds_read_b128 v[188:191], v147 offset:18432
	s_add_i32 m0, s51, 0x2000
	s_add_u32 s52, s22, 0x100000
	s_addc_u32 s53, s23, 0
	s_add_i32 s51, s39, s29
	global_load_lds_dwordx4 v130, s[22:23]
	ds_read_b128 v[192:195], v147 offset:19456
	s_mov_b32 m0, s51
	ds_read_b128 v[196:199], v147 offset:20480
	global_load_lds_dwordx4 v132, s[52:53]
	s_add_i32 m0, s51, 0x2000
	ds_read_b128 v[200:203], v147 offset:21504
	global_load_lds_dwordx4 v130, s[52:53]
	s_add_u32 s56, s24, s8
	s_addc_u32 s57, s25, s9
	s_mov_b32 m0, s5
	ds_read_b128 v[204:207], v147 offset:22528
	global_load_lds_dwordx4 v132, s[24:25]
	s_mov_b32 m0, s7
	ds_read_b128 v[208:211], v147 offset:23552
	global_load_lds_dwordx4 v130, s[24:25]
	s_waitcnt vmcnt(8) lgkmcnt(0)
	s_barrier
	s_setprio 1
	v_mfma_f32_16x16x32_bf16 v[62:65], v[148:151], v[180:183], v[62:65]
	v_mfma_f32_16x16x32_bf16 v[58:61], v[156:159], v[180:183], v[58:61]
	v_mfma_f32_16x16x32_bf16 v[54:57], v[148:151], v[188:191], v[54:57]
	v_mfma_f32_16x16x32_bf16 v[50:53], v[156:159], v[188:191], v[50:53]
	v_mfma_f32_16x16x32_bf16 v[38:41], v[148:151], v[196:199], v[38:41]
	v_mfma_f32_16x16x32_bf16 v[34:37], v[156:159], v[196:199], v[34:37]
	v_mfma_f32_16x16x32_bf16 v[22:25], v[148:151], v[204:207], v[22:25]
	v_mfma_f32_16x16x32_bf16 v[18:21], v[156:159], v[204:207], v[18:21]
	v_mfma_f32_16x16x32_bf16 v[62:65], v[152:155], v[184:187], v[62:65]
	v_mfma_f32_16x16x32_bf16 v[58:61], v[160:163], v[184:187], v[58:61]
	v_mfma_f32_16x16x32_bf16 v[54:57], v[152:155], v[192:195], v[54:57]
	v_mfma_f32_16x16x32_bf16 v[50:53], v[160:163], v[192:195], v[50:53]
	v_mfma_f32_16x16x32_bf16 v[38:41], v[152:155], v[200:203], v[38:41]
	v_mfma_f32_16x16x32_bf16 v[34:37], v[160:163], v[200:203], v[34:37]
	v_mfma_f32_16x16x32_bf16 v[22:25], v[152:155], v[208:211], v[22:25]
	v_mfma_f32_16x16x32_bf16 v[18:21], v[160:163], v[208:211], v[18:21]
	s_setprio 0
	s_setprio 1
	v_mfma_f32_16x16x32_bf16 v[46:49], v[164:167], v[180:183], v[46:49]
	v_mfma_f32_16x16x32_bf16 v[42:45], v[172:175], v[180:183], v[42:45]
	v_mfma_f32_16x16x32_bf16 v[30:33], v[164:167], v[188:191], v[30:33]
	v_mfma_f32_16x16x32_bf16 v[26:29], v[172:175], v[188:191], v[26:29]
	v_mfma_f32_16x16x32_bf16 v[14:17], v[164:167], v[196:199], v[14:17]
	v_mfma_f32_16x16x32_bf16 v[10:13], v[172:175], v[196:199], v[10:13]
	v_mfma_f32_16x16x32_bf16 v[6:9], v[164:167], v[204:207], v[6:9]
	v_mfma_f32_16x16x32_bf16 v[2:5], v[172:175], v[204:207], v[2:5]
	v_mfma_f32_16x16x32_bf16 v[46:49], v[168:171], v[184:187], v[46:49]
	v_mfma_f32_16x16x32_bf16 v[42:45], v[176:179], v[184:187], v[42:45]
	v_mfma_f32_16x16x32_bf16 v[30:33], v[168:171], v[192:195], v[30:33]
	v_mfma_f32_16x16x32_bf16 v[26:29], v[176:179], v[192:195], v[26:29]
	v_mfma_f32_16x16x32_bf16 v[14:17], v[168:171], v[200:203], v[14:17]
	v_mfma_f32_16x16x32_bf16 v[10:13], v[176:179], v[200:203], v[10:13]
	v_mfma_f32_16x16x32_bf16 v[6:9], v[168:171], v[208:211], v[6:9]
	v_mfma_f32_16x16x32_bf16 v[2:5], v[176:179], v[208:211], v[2:5]
	s_barrier
; #define PG8_STAGE(bufoff, gbase, voff) do { _Pragma("unroll") for (int _i = 0; _i < 2; ++_i) \
;         __builtin_amdgcn_global_load_lds((const unsigned*)((const char*)(gbase) + (voff)[_i]), (LAS unsigned*)(lds + (bufoff) + ldsw + _i * 8192), 16, 0, 0); } while (0)
; #define PG8_LDA(dst, b, h) do { _Pragma("unroll") for (int m = 0; m < 4; ++m) _Pragma("unroll") for (int k = 0; k < 2; ++k) dst[m][k] = *(const LAS bf16x8*)(lds + PG8_SA(b, h) + aoff + m * 2048 + k * 1024); } while (0)
; #define PG8_LDB(dst, b, h) do { _Pragma("unroll") for (int n = 0; n < 2; ++n) _Pragma("unroll") for (int k = 0; k < 2; ++k) dst[n][k] = *(const LAS bf16x8*)(lds + PG8_SB(b, h) + boff + n * 2048 + k * 1024); } while (0)
; #define PG8_MMA(ai, bj, At, Bt) do { __builtin_amdgcn_s_setprio(1); _Pragma("unroll") for (int m = 0; m < 4; ++m) _Pragma("unroll") for (int n = 0; n < 2; ++n) _Pragma("unroll") for (int k = 0; k < 2; ++k) \
;         acc[ai][bj][m][n] = __builtin_amdgcn_mfma_f32_16x16x32_bf16(Bt[n][k], At[m][k], acc[ai][bj][m][n], 0, 0, 0); __builtin_amdgcn_s_setprio(0); } while (0)
; #define PG8_WAIT_V(n) asm volatile("s_waitcnt vmcnt(" #n ")" ::: "memory")
; #define PG8_WAIT_L(n) asm volatile("s_waitcnt lgkmcnt(" #n ")" ::: "memory")
; #define PG8_BAR __builtin_amdgcn_s_barrier()
; #define PG8_SCHED __builtin_amdgcn_sched_barrier(0)
; template <class Epi, class Sched, bool ALIGN_EPI, class Hook = NoHook>
; __device__ __forceinline__ void gemm_phase(LAS unsigned char* lds, const Gemm g, const Sched& S, const Epi& E, const Hook& H = Hook()) {
;     ...
;             PG8_LDB(B0, 1, 0); PG8_LDB(B1, 1, 1); PG8_SCHED; PG8_LDA(At, 1, 0); PG8_STAGE(PG8_SA(0, 1), a2 + hA, voffA);
;             PG8_WAIT_V(8); PG8_WAIT_L(0); PG8_BAR; PG8_MMA(0, 0, At, B0); PG8_MMA(0, 1, At, B1); PG8_BAR; PG8_SCHED;
;             PG8_LDA(At, 1, 1); PG8_STAGE(PG8_SB(1, 0), b3, voffB); PG8_STAGE(PG8_SB(1, 1), b3 + hB, voffB); PG8_STAGE(PG8_SA(1, 0), a3, voffA);
;             PG8_WAIT_V(8); PG8_WAIT_L(0); PG8_BAR; PG8_MMA(1, 0, At, B0); PG8_MMA(1, 1, At, B1); PG8_BAR; PG8_SCHED;
	s_setprio 0
	s_add_i32 s51, 0, 0x18000
	s_add_i32 s52, 0, 0x1c000
	v_add_u32_e32 v160, s51, v144
	v_add_u32_e32 v176, s52, v144
	ds_read_b128 v[148:151], v160
	ds_read_b128 v[152:155], v160 offset:1024
	s_add_u32 s24, s24, 0x100000
	s_addc_u32 s25, s25, 0
	s_mov_b32 m0, s30
	ds_read_b128 v[156:159], v160 offset:2048
	global_load_lds_dwordx4 v132, s[24:25]
	ds_read_b128 v[160:163], v160 offset:3072
	ds_read_b128 v[164:167], v176
	ds_read_b128 v[168:171], v176 offset:1024
	ds_read_b128 v[172:175], v176 offset:2048
	ds_read_b128 v[176:179], v176 offset:3072
	ds_read_b128 v[180:183], v147 offset:32768
	s_mov_b32 m0, s31
	ds_read_b128 v[184:187], v147 offset:33792
	global_load_lds_dwordx4 v130, s[24:25]
	ds_read_b128 v[188:191], v147 offset:34816
	ds_read_b128 v[192:195], v147 offset:35840
	ds_read_b128 v[196:199], v147 offset:36864
	ds_read_b128 v[200:203], v147 offset:37888
	ds_read_b128 v[204:207], v147 offset:38912
	ds_read_b128 v[208:211], v147 offset:39936
	s_waitcnt vmcnt(8) lgkmcnt(0)
	s_barrier
	s_setprio 1
	v_mfma_f32_16x16x32_bf16 v[126:129], v[148:151], v[180:183], v[126:129]
	v_mfma_f32_16x16x32_bf16 v[122:125], v[156:159], v[180:183], v[122:125]
	v_mfma_f32_16x16x32_bf16 v[118:121], v[148:151], v[188:191], v[118:121]
	v_mfma_f32_16x16x32_bf16 v[114:117], v[156:159], v[188:191], v[114:117]
	v_mfma_f32_16x16x32_bf16 v[106:109], v[148:151], v[196:199], v[106:109]
	v_mfma_f32_16x16x32_bf16 v[98:101], v[156:159], v[196:199], v[98:101]
	v_mfma_f32_16x16x32_bf16 v[90:93], v[148:151], v[204:207], v[90:93]
	v_mfma_f32_16x16x32_bf16 v[82:85], v[156:159], v[204:207], v[82:85]
	v_mfma_f32_16x16x32_bf16 v[126:129], v[152:155], v[184:187], v[126:129]
	v_mfma_f32_16x16x32_bf16 v[122:125], v[160:163], v[184:187], v[122:125]
	v_mfma_f32_16x16x32_bf16 v[118:121], v[152:155], v[192:195], v[118:121]
	v_mfma_f32_16x16x32_bf16 v[114:117], v[160:163], v[192:195], v[114:117]
	v_mfma_f32_16x16x32_bf16 v[106:109], v[152:155], v[200:203], v[106:109]
	v_mfma_f32_16x16x32_bf16 v[98:101], v[160:163], v[200:203], v[98:101]
	v_mfma_f32_16x16x32_bf16 v[90:93], v[152:155], v[208:211], v[90:93]
	v_mfma_f32_16x16x32_bf16 v[82:85], v[160:163], v[208:211], v[82:85]
	s_setprio 0
	s_setprio 1
	v_mfma_f32_16x16x32_bf16 v[110:113], v[164:167], v[180:183], v[110:113]
	v_mfma_f32_16x16x32_bf16 v[102:105], v[172:175], v[180:183], v[102:105]
	v_mfma_f32_16x16x32_bf16 v[94:97], v[164:167], v[188:191], v[94:97]
	v_mfma_f32_16x16x32_bf16 v[86:89], v[172:175], v[188:191], v[86:89]
	v_mfma_f32_16x16x32_bf16 v[78:81], v[164:167], v[196:199], v[78:81]
	v_mfma_f32_16x16x32_bf16 v[74:77], v[172:175], v[196:199], v[74:77]
	v_mfma_f32_16x16x32_bf16 v[70:73], v[164:167], v[204:207], v[70:73]
	v_mfma_f32_16x16x32_bf16 v[66:69], v[172:175], v[204:207], v[66:69]
	v_mfma_f32_16x16x32_bf16 v[110:113], v[168:171], v[184:187], v[110:113]
	v_mfma_f32_16x16x32_bf16 v[102:105], v[176:179], v[184:187], v[102:105]
	v_mfma_f32_16x16x32_bf16 v[94:97], v[168:171], v[192:195], v[94:97]
	v_mfma_f32_16x16x32_bf16 v[86:89], v[176:179], v[192:195], v[86:89]
	v_mfma_f32_16x16x32_bf16 v[78:81], v[168:171], v[200:203], v[78:81]
	v_mfma_f32_16x16x32_bf16 v[74:77], v[176:179], v[200:203], v[74:77]
	v_mfma_f32_16x16x32_bf16 v[70:73], v[168:171], v[208:211], v[70:73]
	v_mfma_f32_16x16x32_bf16 v[66:69], v[176:179], v[208:211], v[66:69]
	s_barrier
	s_setprio 0
	s_add_i32 s24, s51, s29
	s_add_u32 s54, s22, s8
	s_addc_u32 s55, s23, s9
	s_mov_b32 m0, s24
	ds_read_b128 v[180:183], v147 offset:49152
	ds_read_b128 v[184:187], v147 offset:50176
	global_load_lds_dwordx4 v132, s[54:55]
	ds_read_b128 v[188:191], v147 offset:51200
	s_add_i32 m0, s24, 0x2000
	s_add_u32 s22, s22, 0x100080
	s_addc_u32 s23, s23, 0
	s_add_i32 s24, s52, s29
	global_load_lds_dwordx4 v130, s[54:55]
	ds_read_b128 v[192:195], v147 offset:52224
	s_mov_b32 m0, s24
	ds_read_b128 v[196:199], v147 offset:53248
	global_load_lds_dwordx4 v132, s[22:23]
	s_add_i32 m0, s24, 0x2000
	ds_read_b128 v[200:203], v147 offset:54272
	global_load_lds_dwordx4 v130, s[22:23]
	s_mov_b32 m0, s35
	ds_read_b128 v[204:207], v147 offset:55296
	global_load_lds_dwordx4 v132, s[56:57]
	s_mov_b32 m0, s36
	s_nop 0
	global_load_lds_dwordx4 v130, s[56:57]
	s_add_i32 s50, s50, 2
	s_add_u32 s20, s20, 0x100
	s_addc_u32 s21, s21, 0
	s_add_u32 s42, s42, 0x100
	s_addc_u32 s43, s43, 0
	s_cmp_gt_u32 s50, 5
	ds_read_b128 v[208:211], v147 offset:56320
	s_waitcnt vmcnt(8) lgkmcnt(0)
	s_barrier
; #define PG8_MMA(ai, bj, At, Bt) do { __builtin_amdgcn_s_setprio(1); _Pragma("unroll") for (int m = 0; m < 4; ++m) _Pragma("unroll") for (int n = 0; n < 2; ++n) _Pragma("unroll") for (int k = 0; k < 2; ++k) \
;         acc[ai][bj][m][n] = __builtin_amdgcn_mfma_f32_16x16x32_bf16(Bt[n][k], At[m][k], acc[ai][bj][m][n], 0, 0, 0); __builtin_amdgcn_s_setprio(0); } while (0)
; #define PG8_WAIT_V(n) asm volatile("s_waitcnt vmcnt(" #n ")" ::: "memory")
; #define PG8_WAIT_L(n) asm volatile("s_waitcnt lgkmcnt(" #n ")" ::: "memory")
; #define PG8_BAR __builtin_amdgcn_s_barrier()
; #define PG8_SCHED __builtin_amdgcn_sched_barrier(0)
;     __device__ __forceinline__ void operator()(const f32x4 (&acc)[2][2][4][2], const Unit& u, int wr, int wc, int fr, int fq) const {
;         float* base = C + (size_t)(u.ka / kslab) * slab_stride;
;         const int row0 = u.pm * BM + wr * 64 + fr, col0 = wc * 32 + 4 * fq;
; #pragma unroll
;         for (int ai = 0; ai < 2; ++ai)
; #pragma unroll
;             for (int m = 0; m < 4; ++m) { float* rowp = base + (size_t)(row0 + ai * HALF + m * 16) * 256 + col0;
; #pragma unroll
;                 for (int bj = 0; bj < 2; ++bj)
; #pragma unroll
;                     for (int n = 0; n < 2; ++n) *(f32x4*)(rowp + bj * HALF + n * 16) = acc[ai][bj][m][n]; }
;     }
; template <class Epi, class Sched, bool ALIGN_EPI, class Hook = NoHook>
; __device__ __forceinline__ void gemm_phase(LAS unsigned char* lds, const Gemm g, const Sched& S, const Epi& E, const Hook& H = Hook()) {
;     ...
;             PG8_WAIT_V(8); PG8_WAIT_L(0); PG8_BAR; PG8_MMA(1, 0, At, B0); PG8_MMA(1, 1, At, B1); PG8_BAR; PG8_SCHED;
;         }
;         if constexpr (Hook::ON) H.after(te, acc, cur, wr, wc, fr, fq);
;         }
;         if constexpr (ALIGN_EPI) { if (wr == 0) PG8_BAR; }
;         if constexpr (!Epi::AFTER_DRAIN) { E(acc, cur, wr, wc, fr, fq); S.done(cur); }
	s_setprio 1
	v_mfma_f32_16x16x32_bf16 v[62:65], v[148:151], v[180:183], v[62:65]
	v_mfma_f32_16x16x32_bf16 v[58:61], v[156:159], v[180:183], v[58:61]
	v_mfma_f32_16x16x32_bf16 v[54:57], v[148:151], v[188:191], v[54:57]
	v_mfma_f32_16x16x32_bf16 v[50:53], v[156:159], v[188:191], v[50:53]
	v_mfma_f32_16x16x32_bf16 v[38:41], v[148:151], v[196:199], v[38:41]
	v_mfma_f32_16x16x32_bf16 v[34:37], v[156:159], v[196:199], v[34:37]
	v_mfma_f32_16x16x32_bf16 v[22:25], v[148:151], v[204:207], v[22:25]
	v_mfma_f32_16x16x32_bf16 v[18:21], v[156:159], v[204:207], v[18:21]
	v_mfma_f32_16x16x32_bf16 v[62:65], v[152:155], v[184:187], v[62:65]
	v_mfma_f32_16x16x32_bf16 v[58:61], v[160:163], v[184:187], v[58:61]
	v_mfma_f32_16x16x32_bf16 v[54:57], v[152:155], v[192:195], v[54:57]
	v_mfma_f32_16x16x32_bf16 v[50:53], v[160:163], v[192:195], v[50:53]
	v_mfma_f32_16x16x32_bf16 v[38:41], v[152:155], v[200:203], v[38:41]
	v_mfma_f32_16x16x32_bf16 v[34:37], v[160:163], v[200:203], v[34:37]
	v_mfma_f32_16x16x32_bf16 v[22:25], v[152:155], v[208:211], v[22:25]
	v_mfma_f32_16x16x32_bf16 v[18:21], v[160:163], v[208:211], v[18:21]
	s_setprio 0
	s_setprio 1
	v_mfma_f32_16x16x32_bf16 v[46:49], v[164:167], v[180:183], v[46:49]
	v_mfma_f32_16x16x32_bf16 v[42:45], v[172:175], v[180:183], v[42:45]
	v_mfma_f32_16x16x32_bf16 v[30:33], v[164:167], v[188:191], v[30:33]
	v_mfma_f32_16x16x32_bf16 v[26:29], v[172:175], v[188:191], v[26:29]
	v_mfma_f32_16x16x32_bf16 v[14:17], v[164:167], v[196:199], v[14:17]
	v_mfma_f32_16x16x32_bf16 v[10:13], v[172:175], v[196:199], v[10:13]
	v_mfma_f32_16x16x32_bf16 v[6:9], v[164:167], v[204:207], v[6:9]
	v_mfma_f32_16x16x32_bf16 v[2:5], v[172:175], v[204:207], v[2:5]
	v_mfma_f32_16x16x32_bf16 v[46:49], v[168:171], v[184:187], v[46:49]
	v_mfma_f32_16x16x32_bf16 v[42:45], v[176:179], v[184:187], v[42:45]
	v_mfma_f32_16x16x32_bf16 v[30:33], v[168:171], v[192:195], v[30:33]
	v_mfma_f32_16x16x32_bf16 v[26:29], v[176:179], v[192:195], v[26:29]
	v_mfma_f32_16x16x32_bf16 v[14:17], v[168:171], v[200:203], v[14:17]
	v_mfma_f32_16x16x32_bf16 v[10:13], v[176:179], v[200:203], v[10:13]
	v_mfma_f32_16x16x32_bf16 v[6:9], v[168:171], v[208:211], v[6:9]
	v_mfma_f32_16x16x32_bf16 v[2:5], v[176:179], v[208:211], v[2:5]
	s_barrier
	s_setprio 0
	s_cbranch_scc0 .LBB0_262
	s_ashr_i32 s11, s6, 31
	s_lshr_b32 s11, s11, 23
	s_add_i32 s6, s6, s11
	s_ashr_i32 s20, s6, 9
	s_ashr_i32 s21, s20, 31
	v_lshl_add_u32 v148, s4, 8, v1
	s_lshl_b64 s[20:21], s[20:21], 23
	v_ashrrev_i32_e32 v149, 31, v148
	v_lshl_add_u64 v[150:151], v[134:135], 0, s[20:21]
	v_lshlrev_b64 v[152:153], 10, v[148:149]
	v_lshl_add_u64 v[152:153], v[150:151], 0, v[152:153]
	global_store_dwordx4 v[152:153], v[126:129], off
	global_store_dwordx4 v[152:153], v[122:125], off offset:64
	global_store_dwordx4 v[152:153], v[110:113], off offset:512
	global_store_dwordx4 v[152:153], v[102:105], off offset:576
	s_mov_b32 s4, 0x20000
	s_mov_b64 s[20:21], 0x20000
	v_or_b32_e32 v102, 16, v148
	v_ashrrev_i32_e32 v103, 31, v102
	v_lshlrev_b64 v[102:103], 10, v[102:103]
	v_lshl_add_u64 v[102:103], v[150:151], 0, v[102:103]
	global_store_dwordx4 v[102:103], v[118:121], off
	global_store_dwordx4 v[102:103], v[114:117], off offset:64
	global_store_dwordx4 v[102:103], v[94:97], off offset:512
	global_store_dwordx4 v[102:103], v[86:89], off offset:576
	s_mov_b32 s6, s12
	s_mov_b64 s[22:23], s[18:19]
	v_or_b32_e32 v86, 32, v148
	v_ashrrev_i32_e32 v87, 31, v86
	v_lshlrev_b64 v[86:87], 10, v[86:87]
	v_lshl_add_u64 v[86:87], v[150:151], 0, v[86:87]
	global_store_dwordx4 v[86:87], v[106:109], off
	global_store_dwordx4 v[86:87], v[98:101], off offset:64
	global_store_dwordx4 v[86:87], v[78:81], off offset:512
	global_store_dwordx4 v[86:87], v[74:77], off offset:576
	s_nop 1
	v_or_b32_e32 v74, 48, v148
	v_ashrrev_i32_e32 v75, 31, v74
	v_lshlrev_b64 v[74:75], 10, v[74:75]
	v_lshl_add_u64 v[74:75], v[150:151], 0, v[74:75]
	global_store_dwordx4 v[74:75], v[90:93], off
	global_store_dwordx4 v[74:75], v[82:85], off offset:64
	global_store_dwordx4 v[74:75], v[70:73], off offset:512
	global_store_dwordx4 v[74:75], v[66:69], off offset:576
	s_nop 1
	v_add_co_u32_e32 v68, vcc, s4, v152
	s_mov_b32 s4, 0x24000
	s_nop 0
	v_addc_co_u32_e32 v69, vcc, 0, v153, vcc
	v_lshl_add_u64 v[66:67], v[152:153], 0, s[20:21]
	global_store_dwordx4 v[68:69], v[62:65], off
	global_store_dwordx4 v[66:67], v[58:61], off offset:64
	global_store_dwordx4 v[66:67], v[46:49], off offset:512
	global_store_dwordx4 v[66:67], v[42:45], off offset:576
	s_mov_b64 s[20:21], 0x24000
	s_nop 0
	v_add_co_u32_e32 v44, vcc, s4, v152
	s_mov_b32 s4, 0x28000
	s_nop 0
	v_addc_co_u32_e32 v45, vcc, 0, v153, vcc
	v_lshl_add_u64 v[42:43], v[152:153], 0, s[20:21]
	global_store_dwordx4 v[44:45], v[54:57], off
	global_store_dwordx4 v[42:43], v[50:53], off offset:64
	global_store_dwordx4 v[42:43], v[30:33], off offset:512
	global_store_dwordx4 v[42:43], v[26:29], off offset:576
	s_mov_b64 s[20:21], 0x28000
	s_nop 0
	v_add_co_u32_e32 v28, vcc, s4, v152
	v_lshl_add_u64 v[26:27], v[152:153], 0, s[20:21]
	s_nop 0
	v_addc_co_u32_e32 v29, vcc, 0, v153, vcc
	global_store_dwordx4 v[28:29], v[38:41], off
	global_store_dwordx4 v[26:27], v[34:37], off offset:64
	global_store_dwordx4 v[26:27], v[14:17], off offset:512
	global_store_dwordx4 v[26:27], v[10:13], off offset:576
	s_mov_b64 s[20:21], 0x2c000
	s_mov_b32 s4, s10
	v_add_co_u32_e32 v12, vcc, 0x2c000, v152
	v_lshl_add_u64 v[10:11], v[152:153], 0, s[20:21]
	s_nop 0
	v_addc_co_u32_e32 v13, vcc, 0, v153, vcc
	s_and_b64 vcc, exec, s[2:3]
	s_mov_b64 s[20:21], s[14:15]
	global_store_dwordx4 v[12:13], v[22:25], off
	global_store_dwordx4 v[10:11], v[18:21], off offset:64
	global_store_dwordx4 v[10:11], v[6:9], off offset:512
	global_store_dwordx4 v[10:11], v[2:5], off offset:576
	s_cbranch_vccz .LBB0_259
	s_waitcnt vmcnt(0)
	s_cmpk_gt_u32 s26, 0xff
	s_cbranch_scc1 .LBB0_266
	s_barrier

; #define PG8_STAGE(bufoff, gbase, voff) do { _Pragma("unroll") for (int _i = 0; _i < 2; ++_i) \
;         __builtin_amdgcn_global_load_lds((const unsigned*)((const char*)(gbase) + (voff)[_i]), (LAS unsigned*)(lds + (bufoff) + ldsw + _i * 8192), 16, 0, 0); } while (0)
; #define PG8_LDA(dst, b, h) do { _Pragma("unroll") for (int m = 0; m < 4; ++m) _Pragma("unroll") for (int k = 0; k < 2; ++k) dst[m][k] = *(const LAS bf16x8*)(lds + PG8_SA(b, h) + aoff + m * 2048 + k * 1024); } while (0)
; #define PG8_LDB(dst, b, h) do { _Pragma("unroll") for (int n = 0; n < 2; ++n) _Pragma("unroll") for (int k = 0; k < 2; ++k) dst[n][k] = *(const LAS bf16x8*)(lds + PG8_SB(b, h) + boff + n * 2048 + k * 1024); } while (0)
; #define PG8_MMA(ai, bj, At, Bt) do { __builtin_amdgcn_s_setprio(1); _Pragma("unroll") for (int m = 0; m < 4; ++m) _Pragma("unroll") for (int n = 0; n < 2; ++n) _Pragma("unroll") for (int k = 0; k < 2; ++k) \
;         acc[ai][bj][m][n] = __builtin_amdgcn_mfma_f32_16x16x32_bf16(Bt[n][k], At[m][k], acc[ai][bj][m][n], 0, 0, 0); __builtin_amdgcn_s_setprio(0); } while (0)
; #define PG8_WAIT_V(n) asm volatile("s_waitcnt vmcnt(" #n ")" ::: "memory")
; #define PG8_WAIT_L(n) asm volatile("s_waitcnt lgkmcnt(" #n ")" ::: "memory")
; template <class Epi, class Sched, bool ALIGN_EPI, class Hook = NoHook>
; __device__ __forceinline__ void gemm_phase(LAS unsigned char* lds, const Gemm g, const Sched& S, const Epi& E, const Hook& H = Hook()) {
;     ...
;         for (int t = tb; t < te; t += 2) {
;             const bool last = (t == nt - 2);
;             const char* a1 = cA + (size_t)(t + 1) * kstep;
;             const char* a2 = last ? nA : cA + (size_t)(t + 2) * kstep; const char* b2 = last ? nB : cB + (size_t)(t + 2) * kstep;
;             const char* a3 = a2 + kstep; const char* b3 = b2 + kstep;
;             if (last && has_next) S.a_ready(nxt);
;             PG8_LDB(B0, 0, 0); PG8_LDB(B1, 0, 1); PG8_SCHED; PG8_LDA(At, 0, 0); PG8_STAGE(PG8_SA(1, 1), a1 + hA, voffA);
;             PG8_WAIT_V(8); PG8_WAIT_L(0); PG8_BAR; PG8_MMA(0, 0, At, B0); PG8_MMA(0, 1, At, B1); PG8_BAR; PG8_SCHED;
;             PG8_LDA(At, 0, 1); PG8_STAGE(PG8_SB(0, 0), b2, voffB); PG8_STAGE(PG8_SB(0, 1), b2 + hB, voffB); PG8_STAGE(PG8_SA(0, 0), a2, voffA);
;             PG8_WAIT_V(8); PG8_WAIT_L(0); PG8_BAR; PG8_MMA(1, 0, At, B0); PG8_MMA(1, 1, At, B1); PG8_BAR; PG8_SCHED;
.LBB0_783:
	v_add_u32_e32 v3, s56, v222
	s_add_i32 s67, s67, 2
	ds_read_b128 v[126:129], v3
	ds_read_b128 v[130:133], v3 offset:1024
	ds_read_b128 v[142:145], v3 offset:2048
	ds_read_b128 v[146:149], v3 offset:3072
	v_add_u32_e32 v3, s57, v222
	s_add_u32 s28, s22, s26
	s_addc_u32 s29, s23, s27
	s_add_u32 s28, s28, 0x100
	s_addc_u32 s29, s29, 0
	s_add_u32 s68, s63, s26
	s_addc_u32 s69, s64, s27
	s_cmpk_eq_i32 s26, 0x5f00
	s_cselect_b32 s31, s5, s29
	s_cselect_b32 s30, s4, s28
	s_cselect_b32 s29, s21, s69
	s_cselect_b32 s28, s20, s68
	ds_read_b128 v[150:153], v3
	ds_read_b128 v[154:157], v3 offset:1024
	ds_read_b128 v[158:161], v3 offset:2048
	ds_read_b128 v[162:165], v3 offset:3072
	v_lshl_add_u64 v[4:5], v[182:183], 0, s[26:27]
	s_add_i32 m0, s37, 0xc000
	ds_read_b128 v[186:189], v224
	global_load_lds_dwordx4 v[4:5], off
	ds_read_b128 v[190:193], v224 offset:1024
	ds_read_b128 v[194:197], v224 offset:2048
	ds_read_b128 v[198:201], v224 offset:3072
	ds_read_b128 v[202:205], v224 offset:4096
	ds_read_b128 v[206:209], v224 offset:5120
	ds_read_b128 v[210:213], v224 offset:6144
	ds_read_b128 v[214:217], v224 offset:7168
	v_lshl_add_u64 v[4:5], v[184:185], 0, s[26:27]
	s_add_i32 m0, s37, 0xe000
	s_nop 0
	global_load_lds_dwordx4 v[4:5], off
	s_waitcnt vmcnt(8) lgkmcnt(0)
	s_barrier
	s_setprio 1
	v_mfma_f32_16x16x32_bf16 v[138:141], v[126:129], v[186:189], v[138:141]
	v_mfma_f32_16x16x32_bf16 v[134:137], v[142:145], v[186:189], v[134:137]
	v_mfma_f32_16x16x32_bf16 v[122:125], v[126:129], v[194:197], v[122:125]
	v_mfma_f32_16x16x32_bf16 v[118:121], v[142:145], v[194:197], v[118:121]
	v_mfma_f32_16x16x32_bf16 v[114:117], v[126:129], v[202:205], v[114:117]
	v_mfma_f32_16x16x32_bf16 v[110:113], v[142:145], v[202:205], v[110:113]
	v_mfma_f32_16x16x32_bf16 v[106:109], v[126:129], v[210:213], v[106:109]
	v_mfma_f32_16x16x32_bf16 v[102:105], v[142:145], v[210:213], v[102:105]
	v_mfma_f32_16x16x32_bf16 v[138:141], v[130:133], v[190:193], v[138:141]
	v_mfma_f32_16x16x32_bf16 v[134:137], v[146:149], v[190:193], v[134:137]
	v_mfma_f32_16x16x32_bf16 v[122:125], v[130:133], v[198:201], v[122:125]
	v_mfma_f32_16x16x32_bf16 v[118:121], v[146:149], v[198:201], v[118:121]
	v_mfma_f32_16x16x32_bf16 v[114:117], v[130:133], v[206:209], v[114:117]
	v_mfma_f32_16x16x32_bf16 v[110:113], v[146:149], v[206:209], v[110:113]
	v_mfma_f32_16x16x32_bf16 v[106:109], v[130:133], v[214:217], v[106:109]
	v_mfma_f32_16x16x32_bf16 v[102:105], v[146:149], v[214:217], v[102:105]
	s_setprio 0
	s_setprio 1
	v_mfma_f32_16x16x32_bf16 v[66:69], v[150:153], v[186:189], v[66:69]
	v_mfma_f32_16x16x32_bf16 v[62:65], v[158:161], v[186:189], v[62:65]
	v_mfma_f32_16x16x32_bf16 v[58:61], v[150:153], v[194:197], v[58:61]
	v_mfma_f32_16x16x32_bf16 v[54:57], v[158:161], v[194:197], v[54:57]
	v_mfma_f32_16x16x32_bf16 v[50:53], v[150:153], v[202:205], v[50:53]
	v_mfma_f32_16x16x32_bf16 v[46:49], v[158:161], v[202:205], v[46:49]
	v_mfma_f32_16x16x32_bf16 v[42:45], v[150:153], v[210:213], v[42:45]
	v_mfma_f32_16x16x32_bf16 v[38:41], v[158:161], v[210:213], v[38:41]
	v_mfma_f32_16x16x32_bf16 v[66:69], v[154:157], v[190:193], v[66:69]
	v_mfma_f32_16x16x32_bf16 v[62:65], v[162:165], v[190:193], v[62:65]
	v_mfma_f32_16x16x32_bf16 v[58:61], v[154:157], v[198:201], v[58:61]
	v_mfma_f32_16x16x32_bf16 v[54:57], v[162:165], v[198:201], v[54:57]
	v_mfma_f32_16x16x32_bf16 v[50:53], v[154:157], v[206:209], v[50:53]
	v_mfma_f32_16x16x32_bf16 v[46:49], v[162:165], v[206:209], v[46:49]
	v_mfma_f32_16x16x32_bf16 v[42:45], v[154:157], v[214:217], v[42:45]
	v_mfma_f32_16x16x32_bf16 v[38:41], v[162:165], v[214:217], v[38:41]
	s_barrier
	s_setprio 0
	s_add_i32 s68, s56, s35
	s_mov_b32 m0, s68
	ds_read_b128 v[186:189], v224 offset:16384
	ds_read_b128 v[190:193], v224 offset:17408
	global_load_lds_dwordx4 v168, s[28:29]
	ds_read_b128 v[194:197], v224 offset:18432
	s_add_i32 m0, s68, 0x2000
	s_add_u32 s68, s28, 0x300000
	s_addc_u32 s69, s29, 0
	s_add_i32 s70, s57, s35
	global_load_lds_dwordx4 v172, s[28:29]
	ds_read_b128 v[198:201], v224 offset:19456
	s_mov_b32 m0, s70
	s_add_u32 s74, s30, s14
	s_addc_u32 s75, s31, s15
	global_load_lds_dwordx4 v168, s[68:69]
	ds_read_b128 v[202:205], v224 offset:20480
	s_add_i32 m0, s70, 0x2000
	ds_read_b128 v[206:209], v224 offset:21504
	global_load_lds_dwordx4 v172, s[68:69]
	s_mov_b32 m0, s37
	ds_read_b128 v[210:213], v224 offset:22528
	global_load_lds_dwordx4 v166, s[30:31]
	s_mov_b32 m0, s38
	ds_read_b128 v[214:217], v224 offset:23552
	global_load_lds_dwordx4 v170, s[30:31]
	s_waitcnt vmcnt(8) lgkmcnt(0)
	s_barrier
; #define PG8_STAGE(bufoff, gbase, voff) do { _Pragma("unroll") for (int _i = 0; _i < 2; ++_i) \
;         __builtin_amdgcn_global_load_lds((const unsigned*)((const char*)(gbase) + (voff)[_i]), (LAS unsigned*)(lds + (bufoff) + ldsw + _i * 8192), 16, 0, 0); } while (0)
; #define PG8_LDA(dst, b, h) do { _Pragma("unroll") for (int m = 0; m < 4; ++m) _Pragma("unroll") for (int k = 0; k < 2; ++k) dst[m][k] = *(const LAS bf16x8*)(lds + PG8_SA(b, h) + aoff + m * 2048 + k * 1024); } while (0)
; #define PG8_LDB(dst, b, h) do { _Pragma("unroll") for (int n = 0; n < 2; ++n) _Pragma("unroll") for (int k = 0; k < 2; ++k) dst[n][k] = *(const LAS bf16x8*)(lds + PG8_SB(b, h) + boff + n * 2048 + k * 1024); } while (0)
; #define PG8_MMA(ai, bj, At, Bt) do { __builtin_amdgcn_s_setprio(1); _Pragma("unroll") for (int m = 0; m < 4; ++m) _Pragma("unroll") for (int n = 0; n < 2; ++n) _Pragma("unroll") for (int k = 0; k < 2; ++k) \
;         acc[ai][bj][m][n] = __builtin_amdgcn_mfma_f32_16x16x32_bf16(Bt[n][k], At[m][k], acc[ai][bj][m][n], 0, 0, 0); __builtin_amdgcn_s_setprio(0); } while (0)
; #define PG8_WAIT_V(n) asm volatile("s_waitcnt vmcnt(" #n ")" ::: "memory")
; template <class Epi, class Sched, bool ALIGN_EPI, class Hook = NoHook>
; __device__ __forceinline__ void gemm_phase(LAS unsigned char* lds, const Gemm g, const Sched& S, const Epi& E, const Hook& H = Hook()) {
;     ...
;             PG8_LDB(B0, 0, 0); PG8_LDB(B1, 0, 1); PG8_SCHED; PG8_LDA(At, 0, 0); PG8_STAGE(PG8_SA(1, 1), a1 + hA, voffA);
;             PG8_WAIT_V(8); PG8_WAIT_L(0); PG8_BAR; PG8_MMA(0, 0, At, B0); PG8_MMA(0, 1, At, B1); PG8_BAR; PG8_SCHED;
;             PG8_LDA(At, 0, 1); PG8_STAGE(PG8_SB(0, 0), b2, voffB); PG8_STAGE(PG8_SB(0, 1), b2 + hB, voffB); PG8_STAGE(PG8_SA(0, 0), a2, voffA);
;             PG8_WAIT_V(8); PG8_WAIT_L(0); PG8_BAR; PG8_MMA(1, 0, At, B0); PG8_MMA(1, 1, At, B1); PG8_BAR; PG8_SCHED;
;             PG8_LDB(B0, 1, 0); PG8_LDB(B1, 1, 1); PG8_SCHED; PG8_LDA(At, 1, 0); PG8_STAGE(PG8_SA(0, 1), a2 + hA, voffA);
;             PG8_WAIT_V(8); PG8_WAIT_L(0); PG8_BAR; PG8_MMA(0, 0, At, B0); PG8_MMA(0, 1, At, B1); PG8_BAR; PG8_SCHED;
;             PG8_LDA(At, 1, 1); PG8_STAGE(PG8_SB(1, 0), b3, voffB); PG8_STAGE(PG8_SB(1, 1), b3 + hB, voffB); PG8_STAGE(PG8_SA(1, 0), a3, voffA);
;             PG8_WAIT_V(8); PG8_WAIT_L(0); PG8_BAR; PG8_MMA(1, 0, At, B0); PG8_MMA(1, 1, At, B1); PG8_BAR; PG8_SCHED;
	s_setprio 1
	v_mfma_f32_16x16x32_bf16 v[98:101], v[126:129], v[186:189], v[98:101]
	v_mfma_f32_16x16x32_bf16 v[94:97], v[142:145], v[186:189], v[94:97]
	v_mfma_f32_16x16x32_bf16 v[90:93], v[126:129], v[194:197], v[90:93]
	v_mfma_f32_16x16x32_bf16 v[86:89], v[142:145], v[194:197], v[86:89]
	v_mfma_f32_16x16x32_bf16 v[82:85], v[126:129], v[202:205], v[82:85]
	v_mfma_f32_16x16x32_bf16 v[78:81], v[142:145], v[202:205], v[78:81]
	v_mfma_f32_16x16x32_bf16 v[74:77], v[126:129], v[210:213], v[74:77]
	v_mfma_f32_16x16x32_bf16 v[70:73], v[142:145], v[210:213], v[70:73]
	v_mfma_f32_16x16x32_bf16 v[98:101], v[130:133], v[190:193], v[98:101]
	v_mfma_f32_16x16x32_bf16 v[94:97], v[146:149], v[190:193], v[94:97]
	v_mfma_f32_16x16x32_bf16 v[90:93], v[130:133], v[198:201], v[90:93]
	v_mfma_f32_16x16x32_bf16 v[86:89], v[146:149], v[198:201], v[86:89]
	v_mfma_f32_16x16x32_bf16 v[82:85], v[130:133], v[206:209], v[82:85]
	v_mfma_f32_16x16x32_bf16 v[78:81], v[146:149], v[206:209], v[78:81]
	v_mfma_f32_16x16x32_bf16 v[74:77], v[130:133], v[214:217], v[74:77]
	v_mfma_f32_16x16x32_bf16 v[70:73], v[146:149], v[214:217], v[70:73]
	s_setprio 0
	s_setprio 1
	v_mfma_f32_16x16x32_bf16 v[34:37], v[150:153], v[186:189], v[34:37]
	v_mfma_f32_16x16x32_bf16 v[30:33], v[158:161], v[186:189], v[30:33]
	v_mfma_f32_16x16x32_bf16 v[26:29], v[150:153], v[194:197], v[26:29]
	v_mfma_f32_16x16x32_bf16 v[22:25], v[158:161], v[194:197], v[22:25]
	v_mfma_f32_16x16x32_bf16 v[18:21], v[150:153], v[202:205], v[18:21]
	v_mfma_f32_16x16x32_bf16 v[14:17], v[158:161], v[202:205], v[14:17]
	v_mfma_f32_16x16x32_bf16 v[10:13], v[150:153], v[210:213], v[10:13]
	v_mfma_f32_16x16x32_bf16 v[4:7], v[158:161], v[210:213], v[6:9]
	v_mfma_f32_16x16x32_bf16 v[34:37], v[154:157], v[190:193], v[34:37]
	v_mfma_f32_16x16x32_bf16 v[30:33], v[162:165], v[190:193], v[30:33]
	v_mfma_f32_16x16x32_bf16 v[26:29], v[154:157], v[198:201], v[26:29]
	v_mfma_f32_16x16x32_bf16 v[22:25], v[162:165], v[198:201], v[22:25]
	v_mfma_f32_16x16x32_bf16 v[18:21], v[154:157], v[206:209], v[18:21]
	v_mfma_f32_16x16x32_bf16 v[14:17], v[162:165], v[206:209], v[14:17]
	v_mfma_f32_16x16x32_bf16 v[10:13], v[154:157], v[214:217], v[10:13]
	v_mfma_f32_16x16x32_bf16 v[4:7], v[162:165], v[214:217], v[4:7]
	s_barrier
	s_setprio 0
	s_add_i32 s68, 0, 0x18000
	v_add_u32_e32 v3, s68, v222
	s_add_i32 s69, 0, 0x1c000
	ds_read_b128 v[126:129], v3
	ds_read_b128 v[130:133], v3 offset:1024
	ds_read_b128 v[142:145], v3 offset:2048
	ds_read_b128 v[146:149], v3 offset:3072
	v_add_u32_e32 v3, s69, v222
	s_add_u32 s30, s30, 0x300000
	s_addc_u32 s31, s31, 0
	s_mov_b32 m0, s39
	ds_read_b128 v[150:153], v3
	global_load_lds_dwordx4 v166, s[30:31]
	ds_read_b128 v[154:157], v3 offset:1024
	ds_read_b128 v[158:161], v3 offset:2048
	ds_read_b128 v[162:165], v3 offset:3072
	ds_read_b128 v[186:189], v224 offset:32768
	ds_read_b128 v[190:193], v224 offset:33792
	ds_read_b128 v[194:197], v224 offset:34816
	s_mov_b32 m0, s40
	ds_read_b128 v[198:201], v224 offset:35840
	global_load_lds_dwordx4 v170, s[30:31]
	ds_read_b128 v[202:205], v224 offset:36864
	ds_read_b128 v[206:209], v224 offset:37888
	ds_read_b128 v[210:213], v224 offset:38912
	ds_read_b128 v[214:217], v224 offset:39936
	s_waitcnt vmcnt(8) lgkmcnt(0)
	s_barrier
	s_setprio 1
	v_mfma_f32_16x16x32_bf16 v[138:141], v[126:129], v[186:189], v[138:141]
	v_mfma_f32_16x16x32_bf16 v[134:137], v[142:145], v[186:189], v[134:137]
	v_mfma_f32_16x16x32_bf16 v[122:125], v[126:129], v[194:197], v[122:125]
	v_mfma_f32_16x16x32_bf16 v[118:121], v[142:145], v[194:197], v[118:121]
	v_mfma_f32_16x16x32_bf16 v[114:117], v[126:129], v[202:205], v[114:117]
	v_mfma_f32_16x16x32_bf16 v[110:113], v[142:145], v[202:205], v[110:113]
	v_mfma_f32_16x16x32_bf16 v[106:109], v[126:129], v[210:213], v[106:109]
	v_mfma_f32_16x16x32_bf16 v[102:105], v[142:145], v[210:213], v[102:105]
	v_mfma_f32_16x16x32_bf16 v[138:141], v[130:133], v[190:193], v[138:141]
	v_mfma_f32_16x16x32_bf16 v[134:137], v[146:149], v[190:193], v[134:137]
	v_mfma_f32_16x16x32_bf16 v[122:125], v[130:133], v[198:201], v[122:125]
	v_mfma_f32_16x16x32_bf16 v[118:121], v[146:149], v[198:201], v[118:121]
	v_mfma_f32_16x16x32_bf16 v[114:117], v[130:133], v[206:209], v[114:117]
	v_mfma_f32_16x16x32_bf16 v[110:113], v[146:149], v[206:209], v[110:113]
	v_mfma_f32_16x16x32_bf16 v[106:109], v[130:133], v[214:217], v[106:109]
	v_mfma_f32_16x16x32_bf16 v[102:105], v[146:149], v[214:217], v[102:105]
	s_setprio 0
	s_setprio 1
	v_mfma_f32_16x16x32_bf16 v[66:69], v[150:153], v[186:189], v[66:69]
	v_mfma_f32_16x16x32_bf16 v[62:65], v[158:161], v[186:189], v[62:65]
	v_mfma_f32_16x16x32_bf16 v[58:61], v[150:153], v[194:197], v[58:61]
	v_mfma_f32_16x16x32_bf16 v[54:57], v[158:161], v[194:197], v[54:57]
	v_mfma_f32_16x16x32_bf16 v[50:53], v[150:153], v[202:205], v[50:53]
	v_mfma_f32_16x16x32_bf16 v[46:49], v[158:161], v[202:205], v[46:49]
	v_mfma_f32_16x16x32_bf16 v[42:45], v[150:153], v[210:213], v[42:45]
	v_mfma_f32_16x16x32_bf16 v[38:41], v[158:161], v[210:213], v[38:41]
	v_mfma_f32_16x16x32_bf16 v[66:69], v[154:157], v[190:193], v[66:69]
	v_mfma_f32_16x16x32_bf16 v[62:65], v[162:165], v[190:193], v[62:65]
	v_mfma_f32_16x16x32_bf16 v[58:61], v[154:157], v[198:201], v[58:61]
	v_mfma_f32_16x16x32_bf16 v[54:57], v[162:165], v[198:201], v[54:57]
	v_mfma_f32_16x16x32_bf16 v[50:53], v[154:157], v[206:209], v[50:53]
	v_mfma_f32_16x16x32_bf16 v[46:49], v[162:165], v[206:209], v[46:49]
	v_mfma_f32_16x16x32_bf16 v[42:45], v[154:157], v[214:217], v[42:45]
	v_mfma_f32_16x16x32_bf16 v[38:41], v[162:165], v[214:217], v[38:41]
	s_barrier
; #define PG8_STAGE(bufoff, gbase, voff) do { _Pragma("unroll") for (int _i = 0; _i < 2; ++_i) \
;         __builtin_amdgcn_global_load_lds((const unsigned*)((const char*)(gbase) + (voff)[_i]), (LAS unsigned*)(lds + (bufoff) + ldsw + _i * 8192), 16, 0, 0); } while (0)
; #define PG8_LDA(dst, b, h) do { _Pragma("unroll") for (int m = 0; m < 4; ++m) _Pragma("unroll") for (int k = 0; k < 2; ++k) dst[m][k] = *(const LAS bf16x8*)(lds + PG8_SA(b, h) + aoff + m * 2048 + k * 1024); } while (0)
; #define PG8_MMA(ai, bj, At, Bt) do { __builtin_amdgcn_s_setprio(1); _Pragma("unroll") for (int m = 0; m < 4; ++m) _Pragma("unroll") for (int n = 0; n < 2; ++n) _Pragma("unroll") for (int k = 0; k < 2; ++k) \
;         acc[ai][bj][m][n] = __builtin_amdgcn_mfma_f32_16x16x32_bf16(Bt[n][k], At[m][k], acc[ai][bj][m][n], 0, 0, 0); __builtin_amdgcn_s_setprio(0); } while (0)
; #define PG8_WAIT_V(n) asm volatile("s_waitcnt vmcnt(" #n ")" ::: "memory")
; #define PG8_WAIT_L(n) asm volatile("s_waitcnt lgkmcnt(" #n ")" ::: "memory")
; #define PG8_BAR __builtin_amdgcn_s_barrier()
; #define PG8_SCHED __builtin_amdgcn_sched_barrier(0)
;     __device__ __forceinline__ void after(int te, f32x4 (&acc)[2][2][4][2], const Unit& u, int wr, int wc, int fr, int fq) const {
;         if (te > D_INNER / BK) return;
;         const int g = (te >> 4) - 1;
;         asm volatile("" : "+v"(fr), "+v"(fq));
; #pragma unroll
;         for (int ai = 0; ai < 2; ++ai)
; #pragma unroll
;             for (int m = 0; m < 4; ++m) { const float f = tab[(ai * HALF + wr * 64 + m * 16 + fr) * 8 + g];
; #pragma unroll
;                 for (int bj = 0; bj < 2; ++bj)
; #pragma unroll
;                     for (int n = 0; n < 2; ++n) acc[ai][bj][m][n] *= f; }
; template <class Epi, class Sched, bool ALIGN_EPI, class Hook = NoHook>
; __device__ __forceinline__ void gemm_phase(LAS unsigned char* lds, const Gemm g, const Sched& S, const Epi& E, const Hook& H = Hook()) {
;     ...
;             PG8_LDA(At, 1, 1); PG8_STAGE(PG8_SB(1, 0), b3, voffB); PG8_STAGE(PG8_SB(1, 1), b3 + hB, voffB); PG8_STAGE(PG8_SA(1, 0), a3, voffA);
;             PG8_WAIT_V(8); PG8_WAIT_L(0); PG8_BAR; PG8_MMA(1, 0, At, B0); PG8_MMA(1, 1, At, B1); PG8_BAR; PG8_SCHED;
;         }
;         if constexpr (Hook::ON) H.after(te, acc, cur, wr, wc, fr, fq);
	s_setprio 0
	s_add_i32 s30, s68, s35
	s_add_u32 s72, s28, s14
	s_addc_u32 s73, s29, s15
	s_mov_b32 m0, s30
	ds_read_b128 v[186:189], v224 offset:49152
	ds_read_b128 v[190:193], v224 offset:50176
	global_load_lds_dwordx4 v168, s[72:73]
	ds_read_b128 v[194:197], v224 offset:51200
	s_add_i32 m0, s30, 0x2000
	s_add_u32 s28, s28, 0x300080
	s_addc_u32 s29, s29, 0
	s_add_i32 s30, s69, s35
	global_load_lds_dwordx4 v172, s[72:73]
	ds_read_b128 v[198:201], v224 offset:52224
	s_mov_b32 m0, s30
	ds_read_b128 v[202:205], v224 offset:53248
	global_load_lds_dwordx4 v168, s[28:29]
	s_add_i32 m0, s30, 0x2000
	ds_read_b128 v[206:209], v224 offset:54272
	global_load_lds_dwordx4 v172, s[28:29]
	s_mov_b32 m0, s45
	ds_read_b128 v[210:213], v224 offset:55296
	global_load_lds_dwordx4 v166, s[74:75]
	s_mov_b32 m0, s46
	s_nop 0
	global_load_lds_dwordx4 v170, s[74:75]
	s_add_u32 s26, s26, 0x100
	s_addc_u32 s27, s27, 0
	s_cmp_ge_u32 s67, s66
	ds_read_b128 v[214:217], v224 offset:56320
	s_waitcnt vmcnt(8) lgkmcnt(0)
	s_barrier
	s_setprio 1
	v_mfma_f32_16x16x32_bf16 v[98:101], v[126:129], v[186:189], v[98:101]
	v_mfma_f32_16x16x32_bf16 v[94:97], v[142:145], v[186:189], v[94:97]
	v_mfma_f32_16x16x32_bf16 v[90:93], v[126:129], v[194:197], v[90:93]
	v_mfma_f32_16x16x32_bf16 v[86:89], v[142:145], v[194:197], v[86:89]
	v_mfma_f32_16x16x32_bf16 v[82:85], v[126:129], v[202:205], v[82:85]
	v_mfma_f32_16x16x32_bf16 v[78:81], v[142:145], v[202:205], v[78:81]
	v_mfma_f32_16x16x32_bf16 v[74:77], v[126:129], v[210:213], v[74:77]
	v_mfma_f32_16x16x32_bf16 v[70:73], v[142:145], v[210:213], v[70:73]
	v_mfma_f32_16x16x32_bf16 v[98:101], v[130:133], v[190:193], v[98:101]
	v_mfma_f32_16x16x32_bf16 v[94:97], v[146:149], v[190:193], v[94:97]
	v_mfma_f32_16x16x32_bf16 v[90:93], v[130:133], v[198:201], v[90:93]
	v_mfma_f32_16x16x32_bf16 v[86:89], v[146:149], v[198:201], v[86:89]
	v_mfma_f32_16x16x32_bf16 v[82:85], v[130:133], v[206:209], v[82:85]
	v_mfma_f32_16x16x32_bf16 v[78:81], v[146:149], v[206:209], v[78:81]
	v_mfma_f32_16x16x32_bf16 v[74:77], v[130:133], v[214:217], v[74:77]
	v_mfma_f32_16x16x32_bf16 v[70:73], v[146:149], v[214:217], v[70:73]
	s_setprio 0
	s_setprio 1
	v_mfma_f32_16x16x32_bf16 v[34:37], v[150:153], v[186:189], v[34:37]
	v_mfma_f32_16x16x32_bf16 v[30:33], v[158:161], v[186:189], v[30:33]
	v_mfma_f32_16x16x32_bf16 v[26:29], v[150:153], v[194:197], v[26:29]
	v_mfma_f32_16x16x32_bf16 v[22:25], v[158:161], v[194:197], v[22:25]
	v_mfma_f32_16x16x32_bf16 v[18:21], v[150:153], v[202:205], v[18:21]
	v_mfma_f32_16x16x32_bf16 v[14:17], v[158:161], v[202:205], v[14:17]
	v_mfma_f32_16x16x32_bf16 v[8:11], v[150:153], v[210:213], v[10:13]
	v_mfma_f32_16x16x32_bf16 v[4:7], v[158:161], v[210:213], v[4:7]
	v_mfma_f32_16x16x32_bf16 v[34:37], v[154:157], v[190:193], v[34:37]
	v_mfma_f32_16x16x32_bf16 v[30:33], v[162:165], v[190:193], v[30:33]
	v_mfma_f32_16x16x32_bf16 v[26:29], v[154:157], v[198:201], v[26:29]
	v_mfma_f32_16x16x32_bf16 v[22:25], v[162:165], v[198:201], v[22:25]
	v_mfma_f32_16x16x32_bf16 v[18:21], v[154:157], v[206:209], v[18:21]
	v_mfma_f32_16x16x32_bf16 v[14:17], v[162:165], v[206:209], v[14:17]
	v_mfma_f32_16x16x32_bf16 v[10:13], v[154:157], v[214:217], v[8:11]
	v_mfma_f32_16x16x32_bf16 v[6:9], v[162:165], v[214:217], v[4:7]
	s_barrier
	s_setprio 0
	s_cbranch_scc0 .LBB0_783
	s_cmpk_gt_u32 s65, 0x7f
	s_cbranch_scc1 .LBB0_787
	s_lshr_b32 s26, s66, 4
	s_add_i32 s26, s26, -1
	v_mov_b32_e32 v3, v1
	v_mov_b32_e32 v4, v220
	s_lshl_b32 s27, s26, 2
	s_add_i32 s28, s27, s48
	v_lshlrev_b32_e32 v5, 5, v3
	v_add_u32_e32 v126, s28, v5
	ds_read_b32 v126, v126
	s_add_i32 s28, s27, s49
	s_waitcnt lgkmcnt(0)
	v_pk_mul_f32 v[140:141], v[140:141], v[126:127] op_sel_hi:[1,0]
	v_pk_mul_f32 v[138:139], v[138:139], v[126:127] op_sel_hi:[1,0]
	v_pk_mul_f32 v[136:137], v[136:137], v[126:127] op_sel_hi:[1,0]
	v_pk_mul_f32 v[134:135], v[134:135], v[126:127] op_sel_hi:[1,0]
	v_pk_mul_f32 v[68:69], v[68:69], v[126:127] op_sel_hi:[1,0]
	v_pk_mul_f32 v[66:67], v[66:67], v[126:127] op_sel_hi:[1,0]
	v_pk_mul_f32 v[64:65], v[64:65], v[126:127] op_sel_hi:[1,0]
	v_pk_mul_f32 v[62:63], v[62:63], v[126:127] op_sel_hi:[1,0]
	v_add_u32_e32 v126, s28, v5
	ds_read_b32 v126, v126
	s_add_i32 s28, s27, s50
	s_waitcnt lgkmcnt(0)
	v_pk_mul_f32 v[124:125], v[124:125], v[126:127] op_sel_hi:[1,0]
	v_pk_mul_f32 v[122:123], v[122:123], v[126:127] op_sel_hi:[1,0]
	v_pk_mul_f32 v[120:121], v[120:121], v[126:127] op_sel_hi:[1,0]
	v_pk_mul_f32 v[118:119], v[118:119], v[126:127] op_sel_hi:[1,0]
	v_pk_mul_f32 v[60:61], v[60:61], v[126:127] op_sel_hi:[1,0]
	v_pk_mul_f32 v[58:59], v[58:59], v[126:127] op_sel_hi:[1,0]
	v_pk_mul_f32 v[56:57], v[56:57], v[126:127] op_sel_hi:[1,0]
	v_pk_mul_f32 v[54:55], v[54:55], v[126:127] op_sel_hi:[1,0]
	v_add_u32_e32 v126, s28, v5
	ds_read_b32 v126, v126
	s_add_i32 s28, s27, s51
	s_waitcnt lgkmcnt(0)
	v_pk_mul_f32 v[116:117], v[116:117], v[126:127] op_sel_hi:[1,0]
	v_pk_mul_f32 v[114:115], v[114:115], v[126:127] op_sel_hi:[1,0]
	v_pk_mul_f32 v[112:113], v[112:113], v[126:127] op_sel_hi:[1,0]
	v_pk_mul_f32 v[110:111], v[110:111], v[126:127] op_sel_hi:[1,0]
	v_pk_mul_f32 v[52:53], v[52:53], v[126:127] op_sel_hi:[1,0]
	v_pk_mul_f32 v[50:51], v[50:51], v[126:127] op_sel_hi:[1,0]
	v_pk_mul_f32 v[48:49], v[48:49], v[126:127] op_sel_hi:[1,0]
	v_pk_mul_f32 v[46:47], v[46:47], v[126:127] op_sel_hi:[1,0]
	v_add_u32_e32 v126, s28, v5
	ds_read_b32 v126, v126
	s_add_i32 s28, s27, s52
	s_waitcnt lgkmcnt(0)
;     __device__ __forceinline__ void after(int te, f32x4 (&acc)[2][2][4][2], const Unit& u, int wr, int wc, int fr, int fq) const {
;     ...
;             for (int m = 0; m < 4; ++m) { const float f = tab[(ai * HALF + wr * 64 + m * 16 + fr) * 8 + g];
; #pragma unroll
;                 for (int bj = 0; bj < 2; ++bj)
; #pragma unroll
;                     for (int n = 0; n < 2; ++n) acc[ai][bj][m][n] *= f; }
;         if (g == 7) {
;             const int row0 = u.pm * BM + wr * 64 + fr, col0 = u.pn * BM + wc * 32 + 8 * fq;
; #pragma unroll
;             for (int bj = 0; bj < 2; ++bj) { const int c = col0 + bj * HALF;
;                 const f32x4 s0 = *(const f32x4*)(gb + c), s1 = *(const f32x4*)(gb + c + 4), a0 = *(const f32x4*)(gb + D_MODEL + c), a1 = *(const f32x4*)(gb + D_MODEL + c + 4);
; #pragma unroll
;                 for (int ai = 0; ai < 2; ++ai) {
;                     u32x4 gs[4], ga[4];
; #pragma unroll
;                     for (int m = 0; m < 4; ++m) { const size_t r = (size_t)(row0 + ai * HALF + m * 16); gs[m] = *(const u32x4*)(proj + r * LDP + PGS + c); ga[m] = *(const u32x4*)(proj + r * LDP + PGA + c); }
	v_pk_mul_f32 v[108:109], v[108:109], v[126:127] op_sel_hi:[1,0]
	v_pk_mul_f32 v[106:107], v[106:107], v[126:127] op_sel_hi:[1,0]
	v_pk_mul_f32 v[104:105], v[104:105], v[126:127] op_sel_hi:[1,0]
	v_pk_mul_f32 v[102:103], v[102:103], v[126:127] op_sel_hi:[1,0]
	v_pk_mul_f32 v[44:45], v[44:45], v[126:127] op_sel_hi:[1,0]
	v_pk_mul_f32 v[42:43], v[42:43], v[126:127] op_sel_hi:[1,0]
	v_pk_mul_f32 v[40:41], v[40:41], v[126:127] op_sel_hi:[1,0]
	v_pk_mul_f32 v[38:39], v[38:39], v[126:127] op_sel_hi:[1,0]
	v_add_u32_e32 v126, s28, v5
	ds_read_b32 v126, v126
	s_add_i32 s28, s27, s53
	s_waitcnt lgkmcnt(0)
	v_pk_mul_f32 v[100:101], v[100:101], v[126:127] op_sel_hi:[1,0]
	v_pk_mul_f32 v[98:99], v[98:99], v[126:127] op_sel_hi:[1,0]
	v_pk_mul_f32 v[96:97], v[96:97], v[126:127] op_sel_hi:[1,0]
	v_pk_mul_f32 v[94:95], v[94:95], v[126:127] op_sel_hi:[1,0]
	v_pk_mul_f32 v[36:37], v[36:37], v[126:127] op_sel_hi:[1,0]
	v_pk_mul_f32 v[34:35], v[34:35], v[126:127] op_sel_hi:[1,0]
	v_pk_mul_f32 v[32:33], v[32:33], v[126:127] op_sel_hi:[1,0]
	v_pk_mul_f32 v[30:31], v[30:31], v[126:127] op_sel_hi:[1,0]
	v_add_u32_e32 v126, s28, v5
	ds_read_b32 v126, v126
	s_add_i32 s28, s27, s54
	s_add_i32 s27, s27, s55
	s_cmp_lg_u32 s26, 7
	s_waitcnt lgkmcnt(0)
	v_pk_mul_f32 v[92:93], v[92:93], v[126:127] op_sel_hi:[1,0]
	v_pk_mul_f32 v[90:91], v[90:91], v[126:127] op_sel_hi:[1,0]
	v_pk_mul_f32 v[88:89], v[88:89], v[126:127] op_sel_hi:[1,0]
	v_pk_mul_f32 v[86:87], v[86:87], v[126:127] op_sel_hi:[1,0]
	v_pk_mul_f32 v[28:29], v[28:29], v[126:127] op_sel_hi:[1,0]
	v_pk_mul_f32 v[26:27], v[26:27], v[126:127] op_sel_hi:[1,0]
	v_pk_mul_f32 v[24:25], v[24:25], v[126:127] op_sel_hi:[1,0]
	v_pk_mul_f32 v[22:23], v[22:23], v[126:127] op_sel_hi:[1,0]
	v_add_u32_e32 v126, s28, v5
	ds_read_b32 v126, v126
	v_add_u32_e32 v5, s27, v5
	s_waitcnt lgkmcnt(0)
	v_pk_mul_f32 v[84:85], v[84:85], v[126:127] op_sel_hi:[1,0]
	v_pk_mul_f32 v[82:83], v[82:83], v[126:127] op_sel_hi:[1,0]
	v_pk_mul_f32 v[80:81], v[80:81], v[126:127] op_sel_hi:[1,0]
	v_pk_mul_f32 v[78:79], v[78:79], v[126:127] op_sel_hi:[1,0]
	v_pk_mul_f32 v[20:21], v[20:21], v[126:127] op_sel_hi:[1,0]
	v_pk_mul_f32 v[18:19], v[18:19], v[126:127] op_sel_hi:[1,0]
	v_pk_mul_f32 v[16:17], v[16:17], v[126:127] op_sel_hi:[1,0]
	v_pk_mul_f32 v[14:15], v[14:15], v[126:127] op_sel_hi:[1,0]
	ds_read_b32 v126, v5
	s_waitcnt lgkmcnt(0)
	v_pk_mul_f32 v[76:77], v[76:77], v[126:127] op_sel_hi:[1,0]
	v_pk_mul_f32 v[74:75], v[74:75], v[126:127] op_sel_hi:[1,0]
	v_pk_mul_f32 v[72:73], v[72:73], v[126:127] op_sel_hi:[1,0]
	v_pk_mul_f32 v[70:71], v[70:71], v[126:127] op_sel_hi:[1,0]
	v_pk_mul_f32 v[12:13], v[12:13], v[126:127] op_sel_hi:[1,0]
	v_pk_mul_f32 v[10:11], v[10:11], v[126:127] op_sel_hi:[1,0]
	v_pk_mul_f32 v[8:9], v[8:9], v[126:127] op_sel_hi:[1,0]
	v_pk_mul_f32 v[6:7], v[6:7], v[126:127] op_sel_hi:[1,0]
	s_cbranch_scc1 .LBB0_787
	v_add_u32_e32 v126, s62, v3
	v_ashrrev_i32_e32 v127, 31, v126
	v_lshl_add_u32 v4, v4, 3, s61
	v_lshlrev_b64 v[126:127], 14, v[126:127]
	v_ashrrev_i32_e32 v5, 31, v4
	v_lshl_add_u64 v[126:127], s[76:77], 0, v[126:127]
	v_lshl_add_u64 v[192:193], v[4:5], 1, v[126:127]
	v_readlane_b32 s68, v254, 20
	global_load_dwordx4 v[204:207], v[192:193], off
	v_add_co_u32_e32 v126, vcc, s41, v192
	v_lshlrev_b64 v[4:5], 2, v[4:5]
	v_readlane_b32 s70, v254, 22
	v_readlane_b32 s71, v254, 23
	v_addc_co_u32_e32 v127, vcc, 0, v193, vcc
	s_nop 0
	v_lshl_add_u64 v[196:197], s[70:71], 0, v[4:5]
	global_load_dwordx4 v[208:211], v[126:127], off
	global_load_dwordx4 v[142:145], v[196:197], off
	s_nop 0
	global_load_dwordx4 v[126:129], v[196:197], off offset:16
	v_lshl_add_u64 v[198:199], s[12:13], 0, v[4:5]
	global_load_dwordx4 v[146:149], v[198:199], off
	global_load_dwordx4 v[130:133], v[198:199], off offset:16
	s_mov_b64 s[26:27], 0x40000
	v_lshl_add_u64 v[4:5], v[192:193], 0, s[26:27]
	s_mov_b32 s26, 0x40000
	v_add_co_u32_e32 v150, vcc, s26, v192
	s_mov_b64 s[26:27], 0x42000
	s_nop 0
	v_addc_co_u32_e32 v151, vcc, 0, v193, vcc
	v_lshl_add_u64 v[186:187], v[192:193], 0, s[26:27]
	s_mov_b32 s26, 0x42000
	v_add_co_u32_e32 v152, vcc, s26, v192
	s_mov_b64 s[26:27], 0x80000
	s_nop 0
	v_addc_co_u32_e32 v153, vcc, 0, v193, vcc
	v_lshl_add_u64 v[188:189], v[192:193], 0, s[26:27]
	s_mov_b32 s26, 0x80000
	v_add_co_u32_e32 v154, vcc, s26, v192
	s_mov_b64 s[26:27], 0x82000
	s_nop 0
	v_addc_co_u32_e32 v155, vcc, 0, v193, vcc
	v_lshl_add_u64 v[190:191], v[192:193], 0, s[26:27]
	s_mov_b32 s26, 0x82000
	v_add_co_u32_e32 v156, vcc, s26, v192
	s_mov_b64 s[26:27], 0xc0000
	s_nop 0
	v_addc_co_u32_e32 v157, vcc, 0, v193, vcc
	v_lshl_add_u64 v[194:195], v[192:193], 0, s[26:27]
	s_mov_b32 s26, 0xc0000
	v_add_co_u32_e32 v228, vcc, s26, v192
	s_mov_b64 s[26:27], 0xc2000
	s_nop 0
	v_addc_co_u32_e32 v229, vcc, 0, v193, vcc
	v_lshl_add_u64 v[200:201], v[192:193], 0, s[26:27]
	s_mov_b32 s26, 0xc2000
	v_add_co_u32_e32 v230, vcc, s26, v192
	s_mov_b32 s26, 0x200000
	s_nop 0
	v_addc_co_u32_e32 v231, vcc, 0, v193, vcc
	global_load_dwordx4 v[212:215], v[150:151], off
	global_load_dwordx4 v[216:219], v[152:153], off
	global_load_dwordx4 v[162:165], v[154:155], off
	global_load_dwordx4 v[158:161], v[156:157], off
	s_nop 0
	global_load_dwordx4 v[154:157], v[228:229], off
	global_load_dwordx4 v[150:153], v[230:231], off
	v_lshl_add_u64 v[202:203], v[192:193], 0, s[18:19]
	v_readlane_b32 s76, v254, 28
	v_readlane_b32 s77, v254, 29
	v_readlane_b32 s76, v255, 8
	v_readlane_b32 s77, v255, 9
	v_readlane_b32 s69, v254, 21
	v_readlane_b32 s72, v254, 24
	v_readlane_b32 s73, v254, 25
	v_readlane_b32 s74, v254, 26
	v_readlane_b32 s75, v254, 27
	v_readlane_b32 s78, v254, 30
	v_readlane_b32 s79, v254, 31
	v_readlane_b32 s80, v254, 32
	v_readlane_b32 s81, v254, 33
	v_readlane_b32 s82, v254, 34
	v_readlane_b32 s83, v254, 35
	s_waitcnt vmcnt(0)
; __device__ __forceinline__ void unpack8(const u32x4 w, float (&v)[8]) { v[0] = bf_lo(w.x); v[1] = bf_hi(w.x); v[2] = bf_lo(w.y); v[3] = bf_hi(w.y); v[4] = bf_lo(w.z); v[5] = bf_hi(w.z); v[6] = bf_lo(w.w); v[7] = bf_hi(w.w); }
;     __device__ __forceinline__ void after(int te, f32x4 (&acc)[2][2][4][2], const Unit& u, int wr, int wc, int fr, int fq) const {
;     ...
;                     for (int m = 0; m < 4; ++m) { const size_t r = (size_t)(row0 + ai * HALF + m * 16); gs[m] = *(const u32x4*)(proj + r * LDP + PGS + c); ga[m] = *(const u32x4*)(proj + r * LDP + PGA + c); }
; #pragma unroll
;                     for (int m = 0; m < 4; ++m) { float vs[8], va[8]; unpack8(gs[m], vs); unpack8(ga[m], va);
; #pragma unroll
;                         for (int e = 0; e < 4; ++e) {
;                             acc[ai][bj][m][0][e] *= (1.f + __expf(-(va[e] + a0[e]))) * __builtin_amdgcn_rcpf(1.f + __expf(-(vs[e] + s0[e])));
;                             acc[ai][bj][m][1][e] *= (1.f + __expf(-(va[4 + e] + a1[e]))) * __builtin_amdgcn_rcpf(1.f + __expf(-(vs[4 + e] + s1[e]))); } }
	v_lshlrev_b32_e32 v3, 16, v204
	v_and_b32_e32 v204, 0xffff0000, v204
	v_lshlrev_b32_e32 v225, 16, v205
	v_and_b32_e32 v227, 0xffff0000, v205
	v_lshlrev_b32_e32 v205, 16, v206
	v_and_b32_e32 v228, 0xffff0000, v206
	v_lshlrev_b32_e32 v229, 16, v207
	v_and_b32_e32 v233, 0xffff0000, v207
	v_add_f32_e32 v3, v142, v3
	v_add_f32_e32 v204, v143, v204
	v_mul_f32_e32 v3, 0xbfb8aa3b, v3
	v_mul_f32_e32 v204, 0xbfb8aa3b, v204
	v_exp_f32_e32 v3, v3
	v_lshlrev_b32_e32 v230, 16, v209
	v_and_b32_e32 v231, 0xffff0000, v209
	v_exp_f32_e32 v209, v204
	v_lshlrev_b32_e32 v206, 16, v208
	v_and_b32_e32 v207, 0xffff0000, v208
	v_lshlrev_b32_e32 v208, 16, v210
	v_add_f32_e32 v206, v146, v206
	v_add_f32_e32 v208, v130, v208
	v_mul_f32_e32 v206, 0xbfb8aa3b, v206
	v_mul_f32_e32 v208, 0xbfb8aa3b, v208
	v_add_f32_e32 v3, 1.0, v3
	v_exp_f32_e32 v204, v206
	v_exp_f32_e32 v206, v208
	v_rcp_f32_e32 v208, v3
	v_add_f32_e32 v3, 1.0, v209
	v_rcp_f32_e32 v209, v3
	v_add_f32_e32 v3, v127, v228
	v_mul_f32_e32 v3, 0xbfb8aa3b, v3
	v_exp_f32_e32 v3, v3
	v_lshlrev_b32_e32 v234, 16, v211
	v_and_b32_e32 v235, 0xffff0000, v211
	v_add_f32_e32 v205, v126, v205
	v_add_f32_e32 v3, 1.0, v3
	v_rcp_f32_e32 v211, v3
	v_add_f32_e32 v3, v144, v225
	v_mul_f32_e32 v3, 0xbfb8aa3b, v3
	v_exp_f32_e32 v3, v3
	v_mul_f32_e32 v205, 0xbfb8aa3b, v205
	v_exp_f32_e32 v205, v205
	v_add_f32_e32 v225, v148, v230
	v_add_f32_e32 v3, 1.0, v3
	v_rcp_f32_e32 v230, v3
	v_add_f32_e32 v3, v128, v229
	v_mul_f32_e32 v3, 0xbfb8aa3b, v3
	v_add_f32_e32 v227, v145, v227
	v_mul_f32_e32 v225, 0xbfb8aa3b, v225
	v_exp_f32_e32 v3, v3
	v_mul_f32_e32 v227, 0xbfb8aa3b, v227
	v_add_f32_e32 v207, v147, v207
	v_exp_f32_e32 v228, v225
	v_add_f32_e32 v225, v132, v234
	v_exp_f32_e32 v227, v227
	v_and_b32_e32 v232, 0xffff0000, v210
	v_mul_f32_e32 v207, 0xbfb8aa3b, v207
	v_add_f32_e32 v205, 1.0, v205
	v_mul_f32_e32 v225, 0xbfb8aa3b, v225
	v_rcp_f32_e32 v210, v205
	v_exp_f32_e32 v205, v207
	v_add_f32_e32 v207, v131, v232
	v_exp_f32_e32 v232, v225
	v_add_f32_e32 v225, v149, v231
	v_add_f32_e32 v3, 1.0, v3
	v_mul_f32_e32 v225, 0xbfb8aa3b, v225
	v_exp_f32_e32 v229, v225
	v_rcp_f32_e32 v234, v3
	v_add_f32_e32 v3, 1.0, v227
	v_rcp_f32_e32 v231, v3
	v_pk_add_f32 v[228:229], v[228:229], 1.0 op_sel_hi:[1,0]
	v_pk_add_f32 v[204:205], v[204:205], 1.0 op_sel_hi:[1,0]
	v_add_f32_e32 v3, v133, v235
	v_pk_mul_f32 v[204:205], v[204:205], v[208:209]
	v_pk_mul_f32 v[208:209], v[228:229], v[230:231]
	v_mul_f32_e32 v3, 0xbfb8aa3b, v3
	v_pk_mul_f32 v[140:141], v[140:141], v[208:209]
	v_add_f32_e32 v208, v129, v233
	v_mul_f32_e32 v208, 0xbfb8aa3b, v208
	v_exp_f32_e32 v208, v208
	v_exp_f32_e32 v233, v3
	v_mul_f32_e32 v207, 0xbfb8aa3b, v207
	v_exp_f32_e32 v207, v207
	v_add_f32_e32 v3, 1.0, v208
	v_rcp_f32_e32 v235, v3
	v_lshlrev_b32_e32 v3, 16, v212
	v_add_f32_e32 v3, v142, v3
	v_mul_f32_e32 v3, 0xbfb8aa3b, v3
	v_exp_f32_e32 v3, v3
	v_pk_add_f32 v[206:207], v[206:207], 1.0 op_sel_hi:[1,0]
	v_pk_mul_f32 v[138:139], v[138:139], v[204:205]
	v_pk_mul_f32 v[206:207], v[206:207], v[210:211]
	v_add_f32_e32 v3, 1.0, v3
	v_pk_mul_f32 v[134:135], v[134:135], v[206:207]
	v_lshlrev_b32_e32 v207, 16, v214
	v_rcp_f32_e32 v206, v3
	v_add_f32_e32 v3, v126, v207
	v_mul_f32_e32 v3, 0xbfb8aa3b, v3
	v_exp_f32_e32 v3, v3
	v_pk_add_f32 v[204:205], v[232:233], 1.0 op_sel_hi:[1,0]
	v_lshlrev_b32_e32 v208, 16, v218
	v_pk_mul_f32 v[204:205], v[204:205], v[234:235]
	v_add_f32_e32 v3, 1.0, v3
	v_pk_mul_f32 v[136:137], v[136:137], v[204:205]
	v_and_b32_e32 v205, 0xffff0000, v212
	v_rcp_f32_e32 v210, v3
	v_add_f32_e32 v3, v143, v205
	v_mul_f32_e32 v3, 0xbfb8aa3b, v3
	v_exp_f32_e32 v3, v3
	v_add_f32_e32 v207, v130, v208
	v_and_b32_e32 v209, 0xffff0000, v214
	v_mul_f32_e32 v207, 0xbfb8aa3b, v207
	v_add_f32_e32 v3, 1.0, v3
	v_exp_f32_e32 v208, v207
	v_rcp_f32_e32 v207, v3
	v_add_f32_e32 v3, v127, v209
	v_mul_f32_e32 v3, 0xbfb8aa3b, v3
	v_exp_f32_e32 v3, v3
	v_lshlrev_b32_e32 v212, 16, v213
	v_and_b32_e32 v211, 0xffff0000, v216
	v_add_f32_e32 v205, v147, v211
	v_add_f32_e32 v3, 1.0, v3
	v_rcp_f32_e32 v211, v3
	v_add_f32_e32 v3, v144, v212
	v_mul_f32_e32 v3, 0xbfb8aa3b, v3
	v_exp_f32_e32 v3, v3
	v_lshlrev_b32_e32 v225, 16, v215
	v_lshlrev_b32_e32 v214, 16, v217
	v_and_b32_e32 v213, 0xffff0000, v213
	v_add_f32_e32 v3, 1.0, v3
	v_add_f32_e32 v212, v148, v214
	v_rcp_f32_e32 v214, v3
	v_add_f32_e32 v3, v128, v225
	v_mul_f32_e32 v3, 0xbfb8aa3b, v3
	v_add_f32_e32 v213, v145, v213
	v_and_b32_e32 v227, 0xffff0000, v215
	v_lshlrev_b32_e32 v204, 16, v216
	v_and_b32_e32 v215, 0xffff0000, v217
	v_and_b32_e32 v216, 0xffff0000, v218
	v_lshlrev_b32_e32 v217, 16, v219
	v_exp_f32_e32 v3, v3
	v_mul_f32_e32 v213, 0xbfb8aa3b, v213
	v_add_f32_e32 v209, v131, v216
	v_add_f32_e32 v216, v132, v217
	v_exp_f32_e32 v217, v213
	v_add_f32_e32 v204, v146, v204
	v_add_f32_e32 v215, v149, v215
	v_mul_f32_e32 v204, 0xbfb8aa3b, v204
	v_mul_f32_e32 v205, 0xbfb8aa3b, v205
	v_mul_f32_e32 v212, 0xbfb8aa3b, v212
	v_add_f32_e32 v3, 1.0, v3
	v_mul_f32_e32 v213, 0xbfb8aa3b, v215
	v_exp_f32_e32 v204, v204
	v_exp_f32_e32 v205, v205
	v_exp_f32_e32 v212, v212
	v_exp_f32_e32 v213, v213
	v_rcp_f32_e32 v218, v3
	v_add_f32_e32 v3, 1.0, v217
	v_rcp_f32_e32 v215, v3
	v_pk_add_f32 v[212:213], v[212:213], 1.0 op_sel_hi:[1,0]
	v_pk_add_f32 v[204:205], v[204:205], 1.0 op_sel_hi:[1,0]
	v_and_b32_e32 v219, 0xffff0000, v219
	v_pk_mul_f32 v[204:205], v[204:205], v[206:207]
	v_pk_mul_f32 v[206:207], v[212:213], v[214:215]
	v_add_f32_e32 v3, v133, v219
	v_pk_mul_f32 v[124:125], v[124:125], v[206:207]
	v_add_f32_e32 v206, v129, v227
	v_mul_f32_e32 v206, 0xbfb8aa3b, v206
	v_exp_f32_e32 v206, v206
	v_mul_f32_e32 v3, 0xbfb8aa3b, v3
	v_exp_f32_e32 v217, v3
; __device__ __forceinline__ void unpack8(const u32x4 w, float (&v)[8]) { v[0] = bf_lo(w.x); v[1] = bf_hi(w.x); v[2] = bf_lo(w.y); v[3] = bf_hi(w.y); v[4] = bf_lo(w.z); v[5] = bf_hi(w.z); v[6] = bf_lo(w.w); v[7] = bf_hi(w.w); }
;     __device__ __forceinline__ void after(int te, f32x4 (&acc)[2][2][4][2], const Unit& u, int wr, int wc, int fr, int fq) const {
;     ...
;                     for (int m = 0; m < 4; ++m) { const size_t r = (size_t)(row0 + ai * HALF + m * 16); gs[m] = *(const u32x4*)(proj + r * LDP + PGS + c); ga[m] = *(const u32x4*)(proj + r * LDP + PGA + c); }
; #pragma unroll
;                     for (int m = 0; m < 4; ++m) { float vs[8], va[8]; unpack8(gs[m], vs); unpack8(ga[m], va);
; #pragma unroll
;                         for (int e = 0; e < 4; ++e) {
;                             acc[ai][bj][m][0][e] *= (1.f + __expf(-(va[e] + a0[e]))) * __builtin_amdgcn_rcpf(1.f + __expf(-(vs[e] + s0[e])));
;                             acc[ai][bj][m][1][e] *= (1.f + __expf(-(va[4 + e] + a1[e]))) * __builtin_amdgcn_rcpf(1.f + __expf(-(vs[4 + e] + s1[e]))); } }
	v_mul_f32_e32 v216, 0xbfb8aa3b, v216
	v_add_f32_e32 v3, 1.0, v206
	v_rcp_f32_e32 v219, v3
	v_lshlrev_b32_e32 v3, 16, v162
	v_mul_f32_e32 v209, 0xbfb8aa3b, v209
	v_exp_f32_e32 v216, v216
	v_add_f32_e32 v3, v142, v3
	v_exp_f32_e32 v209, v209
	v_mul_f32_e32 v3, 0xbfb8aa3b, v3
	v_exp_f32_e32 v3, v3
	v_pk_mul_f32 v[122:123], v[122:123], v[204:205]
	v_pk_add_f32 v[204:205], v[216:217], 1.0 op_sel_hi:[1,0]
	v_pk_add_f32 v[206:207], v[208:209], 1.0 op_sel_hi:[1,0]
	v_pk_mul_f32 v[204:205], v[204:205], v[218:219]
	v_pk_mul_f32 v[206:207], v[206:207], v[210:211]
	v_pk_mul_f32 v[120:121], v[120:121], v[204:205]
	v_and_b32_e32 v204, 0xffff0000, v162
	v_lshlrev_b32_e32 v162, 16, v164
	v_add_f32_e32 v3, 1.0, v3
	v_pk_mul_f32 v[118:119], v[118:119], v[206:207]
	v_lshlrev_b32_e32 v206, 16, v159
	v_and_b32_e32 v210, 0xffff0000, v159
	v_lshlrev_b32_e32 v159, 16, v160
	v_and_b32_e32 v211, 0xffff0000, v160
	v_rcp_f32_e32 v160, v3
	v_add_f32_e32 v3, v126, v162
	v_mul_f32_e32 v3, 0xbfb8aa3b, v3
	v_exp_f32_e32 v3, v3
	v_lshlrev_b32_e32 v205, 16, v163
	v_and_b32_e32 v207, 0xffff0000, v163
	v_and_b32_e32 v163, 0xffff0000, v164
	v_lshlrev_b32_e32 v164, 16, v158
	v_add_f32_e32 v3, 1.0, v3
	v_lshlrev_b32_e32 v208, 16, v165
	v_and_b32_e32 v209, 0xffff0000, v165
	v_and_b32_e32 v165, 0xffff0000, v158
	v_add_f32_e32 v158, v146, v164
	v_rcp_f32_e32 v164, v3
	v_add_f32_e32 v3, v143, v204
	v_mul_f32_e32 v3, 0xbfb8aa3b, v3
	v_exp_f32_e32 v3, v3
	v_lshlrev_b32_e32 v212, 16, v161
	v_and_b32_e32 v213, 0xffff0000, v161
	v_add_f32_e32 v159, v130, v159
	v_add_f32_e32 v3, 1.0, v3
	v_rcp_f32_e32 v161, v3
	v_add_f32_e32 v3, v127, v163
	v_mul_f32_e32 v3, 0xbfb8aa3b, v3
	v_exp_f32_e32 v3, v3
	v_mul_f32_e32 v159, 0xbfb8aa3b, v159
	v_exp_f32_e32 v162, v159
	v_add_f32_e32 v159, v147, v165
	v_add_f32_e32 v3, 1.0, v3
	v_rcp_f32_e32 v165, v3
	v_add_f32_e32 v3, v144, v205
	v_mul_f32_e32 v3, 0xbfb8aa3b, v3
	v_exp_f32_e32 v3, v3
	v_add_f32_e32 v204, v148, v206
	v_add_f32_e32 v207, v145, v207
	v_mul_f32_e32 v207, 0xbfb8aa3b, v207
	v_add_f32_e32 v3, 1.0, v3
	v_rcp_f32_e32 v206, v3
	v_add_f32_e32 v3, v128, v208
	v_mul_f32_e32 v3, 0xbfb8aa3b, v3
	v_exp_f32_e32 v3, v3
	v_add_f32_e32 v205, v132, v212
	v_exp_f32_e32 v207, v207
	v_mul_f32_e32 v205, 0xbfb8aa3b, v205
	v_exp_f32_e32 v208, v205
	v_add_f32_e32 v205, v149, v210
	v_mul_f32_e32 v158, 0xbfb8aa3b, v158
	v_mul_f32_e32 v159, 0xbfb8aa3b, v159
	v_mul_f32_e32 v204, 0xbfb8aa3b, v204
	v_add_f32_e32 v3, 1.0, v3
	v_mul_f32_e32 v205, 0xbfb8aa3b, v205
	v_exp_f32_e32 v158, v158
	v_exp_f32_e32 v159, v159
	v_exp_f32_e32 v204, v204
	v_exp_f32_e32 v205, v205
	v_rcp_f32_e32 v210, v3
	v_add_f32_e32 v3, 1.0, v207
	v_rcp_f32_e32 v207, v3
	v_pk_add_f32 v[204:205], v[204:205], 1.0 op_sel_hi:[1,0]
	v_pk_add_f32 v[158:159], v[158:159], 1.0 op_sel_hi:[1,0]
	v_add_f32_e32 v3, v133, v213
	v_pk_mul_f32 v[158:159], v[158:159], v[160:161]
	v_pk_mul_f32 v[160:161], v[204:205], v[206:207]
	v_mul_f32_e32 v3, 0xbfb8aa3b, v3
	v_pk_mul_f32 v[116:117], v[116:117], v[160:161]
	v_add_f32_e32 v160, v129, v209
	v_mul_f32_e32 v160, 0xbfb8aa3b, v160
	v_exp_f32_e32 v160, v160
	v_exp_f32_e32 v209, v3
	v_add_f32_e32 v163, v131, v211
	v_mul_f32_e32 v163, 0xbfb8aa3b, v163
	v_add_f32_e32 v3, 1.0, v160
	v_rcp_f32_e32 v211, v3
	v_lshlrev_b32_e32 v3, 16, v154
	v_add_f32_e32 v3, v142, v3
	v_exp_f32_e32 v163, v163
	v_mul_f32_e32 v3, 0xbfb8aa3b, v3
	v_exp_f32_e32 v3, v3
	v_pk_mul_f32 v[114:115], v[114:115], v[158:159]
	v_pk_add_f32 v[158:159], v[208:209], 1.0 op_sel_hi:[1,0]
	v_pk_add_f32 v[160:161], v[162:163], 1.0 op_sel_hi:[1,0]
	v_pk_mul_f32 v[158:159], v[158:159], v[210:211]
	v_pk_mul_f32 v[160:161], v[160:161], v[164:165]
	v_pk_mul_f32 v[112:113], v[112:113], v[158:159]
	v_and_b32_e32 v158, 0xffff0000, v154
	v_lshlrev_b32_e32 v154, 16, v156
	v_add_f32_e32 v3, 1.0, v3
	v_pk_mul_f32 v[110:111], v[110:111], v[160:161]
	v_lshlrev_b32_e32 v160, 16, v151
	v_and_b32_e32 v204, 0xffff0000, v151
	v_lshlrev_b32_e32 v151, 16, v152
	v_and_b32_e32 v162, 0xffff0000, v152
	v_rcp_f32_e32 v152, v3
	v_add_f32_e32 v3, v126, v154
	v_mul_f32_e32 v3, 0xbfb8aa3b, v3
	v_exp_f32_e32 v3, v3
	v_lshlrev_b32_e32 v159, 16, v155
	v_and_b32_e32 v161, 0xffff0000, v155
	v_and_b32_e32 v155, 0xffff0000, v156
	v_lshlrev_b32_e32 v156, 16, v150
	v_add_f32_e32 v3, 1.0, v3
	v_lshlrev_b32_e32 v164, 16, v157
	v_and_b32_e32 v165, 0xffff0000, v157
	v_and_b32_e32 v157, 0xffff0000, v150
	v_add_f32_e32 v150, v146, v156
	v_rcp_f32_e32 v156, v3
	v_add_f32_e32 v3, v143, v158
	v_mul_f32_e32 v3, 0xbfb8aa3b, v3
	v_exp_f32_e32 v3, v3
	v_lshlrev_b32_e32 v205, 16, v153
	v_and_b32_e32 v206, 0xffff0000, v153
	v_add_f32_e32 v151, v130, v151
	v_add_f32_e32 v3, 1.0, v3
	v_rcp_f32_e32 v153, v3
	v_add_f32_e32 v3, v127, v155
	v_add_f32_e32 v155, v131, v162
	v_add_co_u32_e32 v162, vcc, s26, v192
	v_mul_f32_e32 v3, 0xbfb8aa3b, v3
	s_nop 0
	v_addc_co_u32_e32 v163, vcc, 0, v193, vcc
	global_load_dwordx4 v[228:231], v[162:163], off
	v_exp_f32_e32 v3, v3
	v_mul_f32_e32 v151, 0xbfb8aa3b, v151
	s_mov_b32 s26, 0x202000
	v_exp_f32_e32 v154, v151
	v_add_f32_e32 v3, 1.0, v3
	v_add_f32_e32 v151, v147, v157
	v_rcp_f32_e32 v157, v3
	v_add_f32_e32 v3, v144, v159
	v_add_co_u32_e32 v162, vcc, s26, v192
	v_mul_f32_e32 v3, 0xbfb8aa3b, v3
	s_nop 0
	v_addc_co_u32_e32 v163, vcc, 0, v193, vcc
	v_exp_f32_e32 v3, v3
	global_load_dwordx4 v[232:235], v[162:163], off
	v_add_f32_e32 v158, v148, v160
	v_add_f32_e32 v161, v145, v161
	v_add_f32_e32 v3, 1.0, v3
	v_rcp_f32_e32 v160, v3
	v_add_f32_e32 v3, v128, v164
	v_mul_f32_e32 v3, 0xbfb8aa3b, v3
	v_exp_f32_e32 v3, v3
	v_mul_f32_e32 v161, 0xbfb8aa3b, v161
	v_add_f32_e32 v159, v132, v205
	v_exp_f32_e32 v161, v161
	v_mul_f32_e32 v159, 0xbfb8aa3b, v159
; __device__ __forceinline__ void unpack8(const u32x4 w, float (&v)[8]) { v[0] = bf_lo(w.x); v[1] = bf_hi(w.x); v[2] = bf_lo(w.y); v[3] = bf_hi(w.y); v[4] = bf_lo(w.z); v[5] = bf_hi(w.z); v[6] = bf_lo(w.w); v[7] = bf_hi(w.w); }
;     __device__ __forceinline__ void after(int te, f32x4 (&acc)[2][2][4][2], const Unit& u, int wr, int wc, int fr, int fq) const {
;     ...
;                     for (int m = 0; m < 4; ++m) { const size_t r = (size_t)(row0 + ai * HALF + m * 16); gs[m] = *(const u32x4*)(proj + r * LDP + PGS + c); ga[m] = *(const u32x4*)(proj + r * LDP + PGA + c); }
; #pragma unroll
;                     for (int m = 0; m < 4; ++m) { float vs[8], va[8]; unpack8(gs[m], vs); unpack8(ga[m], va);
; #pragma unroll
;                         for (int e = 0; e < 4; ++e) {
;                             acc[ai][bj][m][0][e] *= (1.f + __expf(-(va[e] + a0[e]))) * __builtin_amdgcn_rcpf(1.f + __expf(-(vs[e] + s0[e])));
;                             acc[ai][bj][m][1][e] *= (1.f + __expf(-(va[4 + e] + a1[e]))) * __builtin_amdgcn_rcpf(1.f + __expf(-(vs[4 + e] + s1[e]))); } }
	v_exp_f32_e32 v162, v159
	v_add_f32_e32 v159, v149, v204
	v_mul_f32_e32 v150, 0xbfb8aa3b, v150
	v_mul_f32_e32 v151, 0xbfb8aa3b, v151
	v_mul_f32_e32 v158, 0xbfb8aa3b, v158
	v_add_f32_e32 v3, 1.0, v3
	v_mul_f32_e32 v159, 0xbfb8aa3b, v159
	v_exp_f32_e32 v150, v150
	v_exp_f32_e32 v151, v151
	v_exp_f32_e32 v158, v158
	v_exp_f32_e32 v159, v159
	v_rcp_f32_e32 v164, v3
	v_add_f32_e32 v3, 1.0, v161
	v_rcp_f32_e32 v161, v3
	v_pk_add_f32 v[158:159], v[158:159], 1.0 op_sel_hi:[1,0]
	v_pk_add_f32 v[150:151], v[150:151], 1.0 op_sel_hi:[1,0]
	v_add_f32_e32 v3, v133, v206
	v_pk_mul_f32 v[150:151], v[150:151], v[152:153]
	v_pk_mul_f32 v[152:153], v[158:159], v[160:161]
	v_mul_f32_e32 v3, 0xbfb8aa3b, v3
	v_pk_mul_f32 v[108:109], v[108:109], v[152:153]
	v_add_f32_e32 v152, v129, v165
	v_mul_f32_e32 v152, 0xbfb8aa3b, v152
	v_exp_f32_e32 v152, v152
	v_exp_f32_e32 v163, v3
	v_mul_f32_e32 v155, 0xbfb8aa3b, v155
	v_exp_f32_e32 v155, v155
	v_add_f32_e32 v3, 1.0, v152
	v_rcp_f32_e32 v165, v3
	s_mov_b64 s[26:27], 0x200000
	v_lshl_add_u64 v[218:219], v[192:193], 0, s[26:27]
	s_mov_b64 s[26:27], 0x202000
	v_pk_mul_f32 v[106:107], v[106:107], v[150:151]
	v_pk_add_f32 v[150:151], v[162:163], 1.0 op_sel_hi:[1,0]
	v_lshl_add_u64 v[216:217], v[192:193], 0, s[26:27]
	s_mov_b64 s[26:27], 0x240000
	v_pk_mul_f32 v[150:151], v[150:151], v[164:165]
	v_lshl_add_u64 v[204:205], v[192:193], 0, s[26:27]
	s_mov_b32 s26, 0x240000
	v_pk_add_f32 v[152:153], v[154:155], 1.0 op_sel_hi:[1,0]
	v_pk_mul_f32 v[104:105], v[104:105], v[150:151]
	v_add_co_u32_e32 v150, vcc, s26, v192
	s_mov_b64 s[26:27], 0x242000
	v_pk_mul_f32 v[152:153], v[152:153], v[156:157]
	v_addc_co_u32_e32 v151, vcc, 0, v193, vcc
	v_lshl_add_u64 v[206:207], v[192:193], 0, s[26:27]
	s_mov_b32 s26, 0x242000
	v_pk_mul_f32 v[102:103], v[102:103], v[152:153]
	v_add_co_u32_e32 v152, vcc, s26, v192
	s_mov_b64 s[26:27], 0x280000
	s_nop 0
	v_addc_co_u32_e32 v153, vcc, 0, v193, vcc
	global_load_dwordx4 v[236:239], v[150:151], off
	global_load_dwordx4 v[240:243], v[152:153], off
	s_waitcnt vmcnt(3)
	v_lshlrev_b32_e32 v3, 16, v228
	v_add_f32_e32 v3, v142, v3
	v_mul_f32_e32 v3, 0xbfb8aa3b, v3
	v_exp_f32_e32 v3, v3
	v_lshlrev_b32_e32 v227, 16, v229
	v_and_b32_e32 v245, 0xffff0000, v229
	v_lshlrev_b32_e32 v229, 16, v230
	v_add_f32_e32 v3, 1.0, v3
	v_and_b32_e32 v246, 0xffff0000, v230
	v_rcp_f32_e32 v230, v3
	v_add_f32_e32 v3, v126, v229
	v_mul_f32_e32 v3, 0xbfb8aa3b, v3
	v_exp_f32_e32 v3, v3
	v_lshl_add_u64 v[208:209], v[192:193], 0, s[26:27]
	s_mov_b32 s26, 0x280000
	v_add_co_u32_e32 v150, vcc, s26, v192
	s_mov_b64 s[26:27], 0x282000
	s_nop 0
	v_addc_co_u32_e32 v151, vcc, 0, v193, vcc
	v_lshl_add_u64 v[210:211], v[192:193], 0, s[26:27]
	s_mov_b32 s26, 0x282000
	v_add_co_u32_e32 v152, vcc, s26, v192
	v_and_b32_e32 v225, 0xffff0000, v228
	v_add_f32_e32 v3, 1.0, v3
	v_addc_co_u32_e32 v153, vcc, 0, v193, vcc
	global_load_dwordx4 v[162:165], v[150:151], off
	global_load_dwordx4 v[158:161], v[152:153], off
	v_lshlrev_b32_e32 v247, 16, v231
	v_and_b32_e32 v251, 0xffff0000, v231
	s_waitcnt vmcnt(4)
	v_lshlrev_b32_e32 v228, 16, v232
	v_and_b32_e32 v231, 0xffff0000, v232
	v_lshlrev_b32_e32 v248, 16, v233
	v_and_b32_e32 v249, 0xffff0000, v233
	v_lshlrev_b32_e32 v232, 16, v234
	v_and_b32_e32 v233, 0xffff0000, v234
	v_rcp_f32_e32 v234, v3
	v_add_f32_e32 v3, v143, v225
	v_mul_f32_e32 v3, 0xbfb8aa3b, v3
	v_exp_f32_e32 v3, v3
	v_add_f32_e32 v225, v147, v231
	v_lshlrev_b32_e32 v250, 16, v235
	v_and_b32_e32 v253, 0xffff0000, v235
	v_add_f32_e32 v3, 1.0, v3
	v_rcp_f32_e32 v231, v3
	v_add_f32_e32 v3, v127, v246
	v_mul_f32_e32 v3, 0xbfb8aa3b, v3
	v_exp_f32_e32 v3, v3
	v_add_f32_e32 v229, v130, v232
	v_mul_f32_e32 v229, 0xbfb8aa3b, v229
	v_mul_f32_e32 v225, 0xbfb8aa3b, v225
	v_add_f32_e32 v3, 1.0, v3
	v_rcp_f32_e32 v235, v3
	v_add_f32_e32 v3, v144, v227
	v_mul_f32_e32 v3, 0xbfb8aa3b, v3
	v_exp_f32_e32 v3, v3
	v_exp_f32_e32 v232, v229
	v_exp_f32_e32 v229, v225
	v_add_f32_e32 v225, v131, v233
	v_mul_f32_e32 v225, 0xbfb8aa3b, v225
	v_exp_f32_e32 v233, v225
	v_add_f32_e32 v225, v148, v248
	v_mul_f32_e32 v225, 0xbfb8aa3b, v225
	v_add_f32_e32 v3, 1.0, v3
	v_exp_f32_e32 v246, v225
	v_rcp_f32_e32 v248, v3
	v_add_f32_e32 v3, v128, v247
	v_add_f32_e32 v225, v132, v250
	v_mul_f32_e32 v3, 0xbfb8aa3b, v3
	v_mul_f32_e32 v225, 0xbfb8aa3b, v225
	v_add_f32_e32 v227, v145, v245
	v_exp_f32_e32 v3, v3
	v_exp_f32_e32 v250, v225
	v_add_f32_e32 v225, v149, v249
	v_mul_f32_e32 v227, 0xbfb8aa3b, v227
	v_exp_f32_e32 v227, v227
	v_mul_f32_e32 v225, 0xbfb8aa3b, v225
	v_exp_f32_e32 v247, v225
	v_add_f32_e32 v225, v129, v251
	v_mul_f32_e32 v225, 0xbfb8aa3b, v225
	v_add_f32_e32 v3, 1.0, v3
	v_exp_f32_e32 v225, v225
	v_rcp_f32_e32 v252, v3
	v_add_f32_e32 v3, 1.0, v227
	v_add_f32_e32 v228, v146, v228
	v_rcp_f32_e32 v249, v3
	v_add_f32_e32 v3, v133, v253
	v_mul_f32_e32 v228, 0xbfb8aa3b, v228
	v_mul_f32_e32 v3, 0xbfb8aa3b, v3
	v_exp_f32_e32 v228, v228
	v_exp_f32_e32 v251, v3
	v_add_f32_e32 v3, 1.0, v225
	v_rcp_f32_e32 v253, v3
	s_waitcnt vmcnt(3)
; __device__ __forceinline__ void unpack8(const u32x4 w, float (&v)[8]) { v[0] = bf_lo(w.x); v[1] = bf_hi(w.x); v[2] = bf_lo(w.y); v[3] = bf_hi(w.y); v[4] = bf_lo(w.z); v[5] = bf_hi(w.z); v[6] = bf_lo(w.w); v[7] = bf_hi(w.w); }
;     __device__ __forceinline__ void after(int te, f32x4 (&acc)[2][2][4][2], const Unit& u, int wr, int wc, int fr, int fq) const {
;     ...
;                     for (int m = 0; m < 4; ++m) { const size_t r = (size_t)(row0 + ai * HALF + m * 16); gs[m] = *(const u32x4*)(proj + r * LDP + PGS + c); ga[m] = *(const u32x4*)(proj + r * LDP + PGA + c); }
; #pragma unroll
;                     for (int m = 0; m < 4; ++m) { float vs[8], va[8]; unpack8(gs[m], vs); unpack8(ga[m], va);
; #pragma unroll
;                         for (int e = 0; e < 4; ++e) {
;                             acc[ai][bj][m][0][e] *= (1.f + __expf(-(va[e] + a0[e]))) * __builtin_amdgcn_rcpf(1.f + __expf(-(vs[e] + s0[e])));
;                             acc[ai][bj][m][1][e] *= (1.f + __expf(-(va[4 + e] + a1[e]))) * __builtin_amdgcn_rcpf(1.f + __expf(-(vs[4 + e] + s1[e]))); } }
	v_lshlrev_b32_e32 v3, 16, v236
	v_add_f32_e32 v3, v142, v3
	v_mul_f32_e32 v3, 0xbfb8aa3b, v3
	v_pk_add_f32 v[228:229], v[228:229], 1.0 op_sel_hi:[1,0]
	v_exp_f32_e32 v3, v3
	v_pk_add_f32 v[246:247], v[246:247], 1.0 op_sel_hi:[1,0]
	v_pk_mul_f32 v[228:229], v[228:229], v[230:231]
	v_pk_mul_f32 v[230:231], v[246:247], v[248:249]
	v_pk_mul_f32 v[98:99], v[98:99], v[228:229]
	v_pk_add_f32 v[228:229], v[250:251], 1.0 op_sel_hi:[1,0]
	v_pk_mul_f32 v[100:101], v[100:101], v[230:231]
	v_pk_add_f32 v[230:231], v[232:233], 1.0 op_sel_hi:[1,0]
	v_pk_mul_f32 v[228:229], v[228:229], v[252:253]
	v_pk_mul_f32 v[230:231], v[230:231], v[234:235]
	v_pk_mul_f32 v[96:97], v[96:97], v[228:229]
	v_lshlrev_b32_e32 v229, 16, v238
	v_add_f32_e32 v3, 1.0, v3
	v_pk_mul_f32 v[94:95], v[94:95], v[230:231]
	v_rcp_f32_e32 v230, v3
	v_add_f32_e32 v3, v126, v229
	v_mul_f32_e32 v3, 0xbfb8aa3b, v3
	v_exp_f32_e32 v3, v3
	v_and_b32_e32 v225, 0xffff0000, v236
	s_mov_b64 s[26:27], 0x2c0000
	v_lshl_add_u64 v[212:213], v[192:193], 0, s[26:27]
	v_add_f32_e32 v3, 1.0, v3
	v_rcp_f32_e32 v234, v3
	v_add_f32_e32 v3, v143, v225
	v_mul_f32_e32 v3, 0xbfb8aa3b, v3
	v_exp_f32_e32 v3, v3
	s_mov_b32 s26, 0x2c0000
	v_add_co_u32_e32 v150, vcc, s26, v192
	s_mov_b64 s[26:27], 0x2c2000
	s_nop 0
	v_addc_co_u32_e32 v151, vcc, 0, v193, vcc
	v_lshl_add_u64 v[214:215], v[192:193], 0, s[26:27]
	s_mov_b32 s26, 0x2c2000
	v_and_b32_e32 v233, 0xffff0000, v238
	s_waitcnt vmcnt(2)
	v_and_b32_e32 v231, 0xffff0000, v240
	v_add_f32_e32 v3, 1.0, v3
	v_add_co_u32_e32 v152, vcc, s26, v192
	v_add_f32_e32 v225, v147, v231
	v_rcp_f32_e32 v231, v3
	v_add_f32_e32 v3, v127, v233
	v_addc_co_u32_e32 v153, vcc, 0, v193, vcc
	v_mul_f32_e32 v3, 0xbfb8aa3b, v3
	global_load_dwordx4 v[154:157], v[150:151], off
	s_nop 0
	global_load_dwordx4 v[150:153], v[152:153], off
	v_exp_f32_e32 v3, v3
	v_lshlrev_b32_e32 v232, 16, v242
	v_add_f32_e32 v229, v130, v232
	v_lshlrev_b32_e32 v227, 16, v237
	v_and_b32_e32 v235, 0xffff0000, v242
	v_mul_f32_e32 v229, 0xbfb8aa3b, v229
	v_mul_f32_e32 v225, 0xbfb8aa3b, v225
	v_add_f32_e32 v3, 1.0, v3
	v_exp_f32_e32 v232, v229
	v_exp_f32_e32 v229, v225
	v_add_f32_e32 v225, v131, v235
	v_rcp_f32_e32 v235, v3
	v_add_f32_e32 v3, v144, v227
	v_mul_f32_e32 v3, 0xbfb8aa3b, v3
	v_exp_f32_e32 v3, v3
	v_lshlrev_b32_e32 v236, 16, v241
	v_mul_f32_e32 v225, 0xbfb8aa3b, v225
	v_exp_f32_e32 v233, v225
	v_add_f32_e32 v225, v148, v236
	v_lshlrev_b32_e32 v245, 16, v239
	v_lshlrev_b32_e32 v228, 16, v240
	v_lshlrev_b32_e32 v240, 16, v243
	v_mul_f32_e32 v225, 0xbfb8aa3b, v225
	v_add_f32_e32 v3, 1.0, v3
	v_and_b32_e32 v237, 0xffff0000, v237
	v_exp_f32_e32 v236, v225
	v_rcp_f32_e32 v238, v3
	v_add_f32_e32 v3, v128, v245
	v_add_f32_e32 v225, v132, v240
	v_and_b32_e32 v246, 0xffff0000, v239
	v_and_b32_e32 v239, 0xffff0000, v241
	v_mul_f32_e32 v3, 0xbfb8aa3b, v3
	v_mul_f32_e32 v225, 0xbfb8aa3b, v225
	v_add_f32_e32 v227, v145, v237
	v_exp_f32_e32 v3, v3
	v_exp_f32_e32 v240, v225
	v_add_f32_e32 v225, v149, v239
	v_mul_f32_e32 v227, 0xbfb8aa3b, v227
	v_exp_f32_e32 v227, v227
	v_mul_f32_e32 v225, 0xbfb8aa3b, v225
	v_exp_f32_e32 v237, v225
	v_add_f32_e32 v225, v129, v246
	v_mul_f32_e32 v225, 0xbfb8aa3b, v225
	v_add_f32_e32 v3, 1.0, v3
	v_exp_f32_e32 v225, v225
	v_and_b32_e32 v241, 0xffff0000, v243
	v_rcp_f32_e32 v242, v3
	v_add_f32_e32 v3, 1.0, v227
	v_rcp_f32_e32 v239, v3
	v_add_f32_e32 v3, v133, v241
	v_add_f32_e32 v228, v146, v228
	v_mul_f32_e32 v3, 0xbfb8aa3b, v3
	v_mul_f32_e32 v228, 0xbfb8aa3b, v228
	v_exp_f32_e32 v241, v3
	v_add_f32_e32 v3, 1.0, v225
	v_exp_f32_e32 v228, v228
	v_rcp_f32_e32 v243, v3
	s_waitcnt vmcnt(3)
	v_lshlrev_b32_e32 v3, 16, v162
	v_add_f32_e32 v3, v142, v3
	v_mul_f32_e32 v3, 0xbfb8aa3b, v3
	v_exp_f32_e32 v3, v3
	v_pk_add_f32 v[236:237], v[236:237], 1.0 op_sel_hi:[1,0]
	v_pk_add_f32 v[228:229], v[228:229], 1.0 op_sel_hi:[1,0]
	v_and_b32_e32 v225, 0xffff0000, v162
	v_pk_mul_f32 v[228:229], v[228:229], v[230:231]
	v_pk_mul_f32 v[230:231], v[236:237], v[238:239]
	v_pk_mul_f32 v[90:91], v[90:91], v[228:229]
	v_pk_mul_f32 v[92:93], v[92:93], v[230:231]
	v_pk_add_f32 v[228:229], v[240:241], 1.0 op_sel_hi:[1,0]
	v_pk_add_f32 v[230:231], v[232:233], 1.0 op_sel_hi:[1,0]
	v_pk_mul_f32 v[228:229], v[228:229], v[242:243]
	v_pk_mul_f32 v[230:231], v[230:231], v[234:235]
	v_lshlrev_b32_e32 v162, 16, v164
	v_add_f32_e32 v3, 1.0, v3
	v_pk_mul_f32 v[88:89], v[88:89], v[228:229]
	v_pk_mul_f32 v[86:87], v[86:87], v[230:231]
	s_waitcnt vmcnt(2)
; __device__ __forceinline__ void unpack8(const u32x4 w, float (&v)[8]) { v[0] = bf_lo(w.x); v[1] = bf_hi(w.x); v[2] = bf_lo(w.y); v[3] = bf_hi(w.y); v[4] = bf_lo(w.z); v[5] = bf_hi(w.z); v[6] = bf_lo(w.w); v[7] = bf_hi(w.w); }
;     __device__ __forceinline__ void after(int te, f32x4 (&acc)[2][2][4][2], const Unit& u, int wr, int wc, int fr, int fq) const {
;     ...
;                     for (int m = 0; m < 4; ++m) { const size_t r = (size_t)(row0 + ai * HALF + m * 16); gs[m] = *(const u32x4*)(proj + r * LDP + PGS + c); ga[m] = *(const u32x4*)(proj + r * LDP + PGA + c); }
; #pragma unroll
;                     for (int m = 0; m < 4; ++m) { float vs[8], va[8]; unpack8(gs[m], vs); unpack8(ga[m], va);
; #pragma unroll
;                         for (int e = 0; e < 4; ++e) {
;                             acc[ai][bj][m][0][e] *= (1.f + __expf(-(va[e] + a0[e]))) * __builtin_amdgcn_rcpf(1.f + __expf(-(vs[e] + s0[e])));
;                             acc[ai][bj][m][1][e] *= (1.f + __expf(-(va[4 + e] + a1[e]))) * __builtin_amdgcn_rcpf(1.f + __expf(-(vs[4 + e] + s1[e]))); } }
	v_lshlrev_b32_e32 v228, 16, v159
	v_and_b32_e32 v234, 0xffff0000, v159
	v_lshlrev_b32_e32 v159, 16, v160
	v_and_b32_e32 v230, 0xffff0000, v160
	v_rcp_f32_e32 v160, v3
	v_add_f32_e32 v3, v126, v162
	v_mul_f32_e32 v3, 0xbfb8aa3b, v3
	v_exp_f32_e32 v3, v3
	v_lshlrev_b32_e32 v227, 16, v163
	v_and_b32_e32 v229, 0xffff0000, v163
	v_and_b32_e32 v163, 0xffff0000, v164
	v_lshlrev_b32_e32 v164, 16, v158
	v_add_f32_e32 v3, 1.0, v3
	v_lshlrev_b32_e32 v231, 16, v165
	v_and_b32_e32 v233, 0xffff0000, v165
	v_and_b32_e32 v165, 0xffff0000, v158
	v_add_f32_e32 v158, v146, v164
	v_rcp_f32_e32 v164, v3
	v_add_f32_e32 v3, v143, v225
	v_mul_f32_e32 v3, 0xbfb8aa3b, v3
	v_exp_f32_e32 v3, v3
	v_lshlrev_b32_e32 v232, 16, v161
	v_and_b32_e32 v235, 0xffff0000, v161
	v_add_f32_e32 v159, v130, v159
	v_add_f32_e32 v3, 1.0, v3
	v_rcp_f32_e32 v161, v3
	v_add_f32_e32 v3, v127, v163
	v_mul_f32_e32 v3, 0xbfb8aa3b, v3
	v_exp_f32_e32 v3, v3
	v_mul_f32_e32 v159, 0xbfb8aa3b, v159
	v_exp_f32_e32 v162, v159
	v_add_f32_e32 v159, v147, v165
	v_add_f32_e32 v3, 1.0, v3
	v_rcp_f32_e32 v165, v3
	v_add_f32_e32 v3, v144, v227
	v_mul_f32_e32 v3, 0xbfb8aa3b, v3
	v_exp_f32_e32 v3, v3
	v_add_f32_e32 v163, v131, v230
	v_add_f32_e32 v225, v148, v228
	v_add_f32_e32 v227, v145, v229
	v_add_f32_e32 v3, 1.0, v3
	v_rcp_f32_e32 v230, v3
	v_add_f32_e32 v3, v128, v231
	v_mul_f32_e32 v3, 0xbfb8aa3b, v3
	v_mul_f32_e32 v225, 0xbfb8aa3b, v225
	v_exp_f32_e32 v3, v3
	v_mul_f32_e32 v227, 0xbfb8aa3b, v227
	v_exp_f32_e32 v228, v225
	v_add_f32_e32 v225, v132, v232
	v_exp_f32_e32 v227, v227
	v_mul_f32_e32 v225, 0xbfb8aa3b, v225
	v_exp_f32_e32 v232, v225
	v_add_f32_e32 v225, v149, v234
	v_mul_f32_e32 v158, 0xbfb8aa3b, v158
	v_mul_f32_e32 v159, 0xbfb8aa3b, v159
	v_add_f32_e32 v3, 1.0, v3
	v_mul_f32_e32 v225, 0xbfb8aa3b, v225
	v_exp_f32_e32 v158, v158
	v_exp_f32_e32 v159, v159
	v_exp_f32_e32 v229, v225
	v_rcp_f32_e32 v234, v3
	v_add_f32_e32 v3, 1.0, v227
	v_rcp_f32_e32 v231, v3
	v_pk_add_f32 v[228:229], v[228:229], 1.0 op_sel_hi:[1,0]
	v_pk_add_f32 v[158:159], v[158:159], 1.0 op_sel_hi:[1,0]
	v_add_f32_e32 v3, v133, v235
	v_pk_mul_f32 v[158:159], v[158:159], v[160:161]
	v_pk_mul_f32 v[160:161], v[228:229], v[230:231]
	v_mul_f32_e32 v3, 0xbfb8aa3b, v3
	v_pk_mul_f32 v[84:85], v[84:85], v[160:161]
	v_add_f32_e32 v160, v129, v233
	v_mul_f32_e32 v160, 0xbfb8aa3b, v160
	v_exp_f32_e32 v160, v160
	v_exp_f32_e32 v233, v3
	s_waitcnt vmcnt(1)
	v_lshlrev_b32_e32 v225, 16, v155
	v_and_b32_e32 v227, 0xffff0000, v155
	v_add_f32_e32 v3, 1.0, v160
	v_rcp_f32_e32 v235, v3
	v_lshlrev_b32_e32 v3, 16, v154
	v_add_f32_e32 v3, v142, v3
	v_mul_f32_e32 v3, 0xbfb8aa3b, v3
	v_exp_f32_e32 v3, v3
	v_lshlrev_b32_e32 v155, 16, v156
	v_and_b32_e32 v236, 0xffff0000, v156
	s_waitcnt vmcnt(0)
	v_lshlrev_b32_e32 v156, 16, v150
	v_add_f32_e32 v3, 1.0, v3
	v_mul_f32_e32 v163, 0xbfb8aa3b, v163
	v_add_f32_e32 v142, v146, v156
	v_rcp_f32_e32 v146, v3
	v_add_f32_e32 v3, v126, v155
	v_exp_f32_e32 v163, v163
	v_mul_f32_e32 v3, 0xbfb8aa3b, v3
	v_exp_f32_e32 v3, v3
	v_pk_mul_f32 v[82:83], v[82:83], v[158:159]
	v_pk_add_f32 v[158:159], v[232:233], 1.0 op_sel_hi:[1,0]
	v_pk_add_f32 v[160:161], v[162:163], 1.0 op_sel_hi:[1,0]
	v_pk_mul_f32 v[158:159], v[158:159], v[234:235]
	v_pk_mul_f32 v[160:161], v[160:161], v[164:165]
	v_and_b32_e32 v150, 0xffff0000, v150
	v_lshlrev_b32_e32 v239, 16, v151
	v_and_b32_e32 v240, 0xffff0000, v151
	v_lshlrev_b32_e32 v151, 16, v152
	global_load_dwordx4 v[228:231], v[192:193], off offset:256
	global_load_dwordx4 v[232:235], v[202:203], off offset:256
	v_add_f32_e32 v3, 1.0, v3
	v_pk_mul_f32 v[80:81], v[80:81], v[158:159]
	v_pk_mul_f32 v[78:79], v[78:79], v[160:161]
	v_and_b32_e32 v241, 0xffff0000, v152
	v_lshlrev_b32_e32 v242, 16, v153
	v_and_b32_e32 v243, 0xffff0000, v153
	v_add_f32_e32 v126, v130, v151
	v_rcp_f32_e32 v130, v3
	v_add_f32_e32 v3, v147, v150
	global_load_dwordx4 v[150:153], v[196:197], off offset:528
	global_load_dwordx4 v[158:161], v[196:197], off offset:512
	v_and_b32_e32 v154, 0xffff0000, v154
	v_lshlrev_b32_e32 v237, 16, v157
	v_and_b32_e32 v238, 0xffff0000, v157
	v_add_f32_e32 v143, v143, v154
	global_load_dwordx4 v[154:157], v[198:199], off offset:528
	global_load_dwordx4 v[162:165], v[198:199], off offset:512
	v_mul_f32_e32 v143, 0xbfb8aa3b, v143
	v_exp_f32_e32 v147, v143
	v_mul_f32_e32 v3, 0xbfb8aa3b, v3
	v_exp_f32_e32 v143, v3
	v_add_f32_e32 v145, v145, v227
	v_add_f32_e32 v3, 1.0, v147
	v_rcp_f32_e32 v147, v3
	v_add_f32_e32 v3, v127, v236
	v_mul_f32_e32 v3, 0xbfb8aa3b, v3
	v_exp_f32_e32 v3, v3
	v_add_f32_e32 v127, v131, v241
	v_mul_f32_e32 v145, 0xbfb8aa3b, v145
	v_add_f32_e32 v129, v129, v238
	v_add_f32_e32 v3, 1.0, v3
	v_rcp_f32_e32 v131, v3
	v_add_f32_e32 v3, v144, v225
	v_mul_f32_e32 v3, 0xbfb8aa3b, v3
	v_exp_f32_e32 v3, v3
	v_add_f32_e32 v144, v148, v239
	v_mul_f32_e32 v129, 0xbfb8aa3b, v129
	v_mul_f32_e32 v142, 0xbfb8aa3b, v142
	v_add_f32_e32 v3, 1.0, v3
	v_rcp_f32_e32 v148, v3
	v_add_f32_e32 v3, v128, v237
	v_mul_f32_e32 v3, 0xbfb8aa3b, v3
	v_exp_f32_e32 v3, v3
	v_add_f32_e32 v128, v132, v242
	v_add_f32_e32 v132, v149, v240
	v_exp_f32_e32 v149, v145
	v_add_f32_e32 v3, 1.0, v3
	v_mul_f32_e32 v132, 0xbfb8aa3b, v132
	v_exp_f32_e32 v145, v132
	v_rcp_f32_e32 v132, v3
	v_add_f32_e32 v3, 1.0, v149
	v_rcp_f32_e32 v149, v3
	v_add_f32_e32 v3, v133, v243
	v_exp_f32_e32 v133, v129
	v_mul_f32_e32 v126, 0xbfb8aa3b, v126
	v_mul_f32_e32 v127, 0xbfb8aa3b, v127
	v_mul_f32_e32 v144, 0xbfb8aa3b, v144
	v_mul_f32_e32 v128, 0xbfb8aa3b, v128
	v_mul_f32_e32 v3, 0xbfb8aa3b, v3
	v_exp_f32_e32 v142, v142
	v_exp_f32_e32 v126, v126
	v_exp_f32_e32 v127, v127
	v_exp_f32_e32 v144, v144
	v_exp_f32_e32 v128, v128
	v_exp_f32_e32 v129, v3
	v_add_f32_e32 v3, 1.0, v133
	v_rcp_f32_e32 v133, v3
	v_pk_add_f32 v[144:145], v[144:145], 1.0 op_sel_hi:[1,0]
	v_pk_add_f32 v[142:143], v[142:143], 1.0 op_sel_hi:[1,0]
	v_pk_add_f32 v[128:129], v[128:129], 1.0 op_sel_hi:[1,0]
	v_pk_add_f32 v[126:127], v[126:127], 1.0 op_sel_hi:[1,0]
	v_pk_mul_f32 v[142:143], v[142:143], v[146:147]
	v_pk_mul_f32 v[144:145], v[144:145], v[148:149]
	v_pk_mul_f32 v[126:127], v[126:127], v[130:131]
	v_pk_mul_f32 v[128:129], v[128:129], v[132:133]
	v_pk_mul_f32 v[76:77], v[76:77], v[144:145]
	v_pk_mul_f32 v[74:75], v[74:75], v[142:143]
	v_pk_mul_f32 v[72:73], v[72:73], v[128:129]
	v_pk_mul_f32 v[70:71], v[70:71], v[126:127]
	global_load_dwordx4 v[196:199], v[4:5], off offset:256
	global_load_dwordx4 v[236:239], v[186:187], off offset:256
	global_load_dwordx4 v[146:149], v[188:189], off offset:256
	global_load_dwordx4 v[142:145], v[190:191], off offset:256
	global_load_dwordx4 v[130:133], v[194:195], off offset:256
	global_load_dwordx4 v[126:129], v[200:201], off offset:256
	s_waitcnt vmcnt(11)
; __device__ __forceinline__ void unpack8(const u32x4 w, float (&v)[8]) { v[0] = bf_lo(w.x); v[1] = bf_hi(w.x); v[2] = bf_lo(w.y); v[3] = bf_hi(w.y); v[4] = bf_lo(w.z); v[5] = bf_hi(w.z); v[6] = bf_lo(w.w); v[7] = bf_hi(w.w); }
;     __device__ __forceinline__ void after(int te, f32x4 (&acc)[2][2][4][2], const Unit& u, int wr, int wc, int fr, int fq) const {
;     ...
;                     for (int m = 0; m < 4; ++m) { const size_t r = (size_t)(row0 + ai * HALF + m * 16); gs[m] = *(const u32x4*)(proj + r * LDP + PGS + c); ga[m] = *(const u32x4*)(proj + r * LDP + PGA + c); }
; #pragma unroll
;                     for (int m = 0; m < 4; ++m) { float vs[8], va[8]; unpack8(gs[m], vs); unpack8(ga[m], va);
; #pragma unroll
;                         for (int e = 0; e < 4; ++e) {
;                             acc[ai][bj][m][0][e] *= (1.f + __expf(-(va[e] + a0[e]))) * __builtin_amdgcn_rcpf(1.f + __expf(-(vs[e] + s0[e])));
;                             acc[ai][bj][m][1][e] *= (1.f + __expf(-(va[4 + e] + a1[e]))) * __builtin_amdgcn_rcpf(1.f + __expf(-(vs[4 + e] + s1[e]))); } }
	v_lshlrev_b32_e32 v3, 16, v228
	v_lshlrev_b32_e32 v187, 16, v230
	v_and_b32_e32 v5, 0xffff0000, v228
	s_waitcnt vmcnt(10)
	v_lshlrev_b32_e32 v188, 16, v234
	v_and_b32_e32 v189, 0xffff0000, v230
	v_lshlrev_b32_e32 v192, 16, v229
	v_and_b32_e32 v191, 0xffff0000, v232
	v_lshlrev_b32_e32 v195, 16, v231
	v_lshlrev_b32_e32 v194, 16, v233
	v_and_b32_e32 v193, 0xffff0000, v229
	v_lshlrev_b32_e32 v203, 16, v235
	s_waitcnt vmcnt(8)
	v_add_f32_e32 v3, v158, v3
	v_mul_f32_e32 v3, 0xbfb8aa3b, v3
	v_exp_f32_e32 v3, v3
	v_add_f32_e32 v193, v161, v193
	v_mul_f32_e32 v193, 0xbfb8aa3b, v193
	v_lshlrev_b32_e32 v4, 16, v232
	v_add_f32_e32 v3, 1.0, v3
	v_rcp_f32_e32 v186, v3
	v_add_f32_e32 v3, v150, v187
	v_mul_f32_e32 v3, 0xbfb8aa3b, v3
	v_exp_f32_e32 v3, v3
	s_waitcnt vmcnt(7)
	v_add_f32_e32 v187, v154, v188
	v_mul_f32_e32 v187, 0xbfb8aa3b, v187
	v_exp_f32_e32 v188, v187
	v_add_f32_e32 v3, 1.0, v3
	v_rcp_f32_e32 v190, v3
	v_add_f32_e32 v3, v159, v5
	v_mul_f32_e32 v3, 0xbfb8aa3b, v3
	v_exp_f32_e32 v3, v3
	s_waitcnt vmcnt(6)
	v_add_f32_e32 v5, v163, v191
	v_and_b32_e32 v202, 0xffff0000, v233
	v_and_b32_e32 v200, 0xffff0000, v234
	v_add_f32_e32 v3, 1.0, v3
	v_rcp_f32_e32 v187, v3
	v_add_f32_e32 v3, v151, v189
	v_mul_f32_e32 v3, 0xbfb8aa3b, v3
	v_exp_f32_e32 v3, v3
	v_add_f32_e32 v4, v162, v4
	v_add_f32_e32 v189, v155, v200
	v_mul_f32_e32 v4, 0xbfb8aa3b, v4
	v_add_f32_e32 v3, 1.0, v3
	v_rcp_f32_e32 v191, v3
	v_add_f32_e32 v3, v160, v192
	v_mul_f32_e32 v3, 0xbfb8aa3b, v3
	v_exp_f32_e32 v3, v3
	v_add_f32_e32 v192, v164, v194
	v_mul_f32_e32 v5, 0xbfb8aa3b, v5
	v_mul_f32_e32 v192, 0xbfb8aa3b, v192
	v_add_f32_e32 v3, 1.0, v3
	v_rcp_f32_e32 v194, v3
	v_add_f32_e32 v3, v152, v195
	v_mul_f32_e32 v3, 0xbfb8aa3b, v3
	v_exp_f32_e32 v3, v3
	v_add_f32_e32 v195, v156, v203
	v_exp_f32_e32 v203, v193
	v_mul_f32_e32 v195, 0xbfb8aa3b, v195
	v_exp_f32_e32 v200, v195
	v_add_f32_e32 v195, v165, v202
	v_add_f32_e32 v3, 1.0, v3
	v_mul_f32_e32 v193, 0xbfb8aa3b, v195
	v_exp_f32_e32 v4, v4
	v_exp_f32_e32 v5, v5
	v_exp_f32_e32 v192, v192
	v_exp_f32_e32 v193, v193
	v_rcp_f32_e32 v202, v3
	v_add_f32_e32 v3, 1.0, v203
	v_rcp_f32_e32 v195, v3
	v_pk_add_f32 v[192:193], v[192:193], 1.0 op_sel_hi:[1,0]
	v_pk_add_f32 v[4:5], v[4:5], 1.0 op_sel_hi:[1,0]
	v_and_b32_e32 v201, 0xffff0000, v231
	v_pk_mul_f32 v[4:5], v[4:5], v[186:187]
	v_pk_mul_f32 v[186:187], v[192:193], v[194:195]
	v_and_b32_e32 v225, 0xffff0000, v235
	v_pk_mul_f32 v[68:69], v[68:69], v[186:187]
	v_add_f32_e32 v186, v153, v201
	v_mul_f32_e32 v186, 0xbfb8aa3b, v186
	v_exp_f32_e32 v186, v186
	v_add_f32_e32 v3, v157, v225
	v_mul_f32_e32 v3, 0xbfb8aa3b, v3
	v_exp_f32_e32 v201, v3
	v_add_f32_e32 v3, 1.0, v186
	v_mul_f32_e32 v189, 0xbfb8aa3b, v189
	v_rcp_f32_e32 v203, v3
	s_waitcnt vmcnt(5)
	v_lshlrev_b32_e32 v3, 16, v196
	v_exp_f32_e32 v189, v189
	v_add_f32_e32 v3, v158, v3
	v_mul_f32_e32 v3, 0xbfb8aa3b, v3
	v_exp_f32_e32 v3, v3
	v_pk_add_f32 v[186:187], v[188:189], 1.0 op_sel_hi:[1,0]
	v_pk_mul_f32 v[66:67], v[66:67], v[4:5]
	v_pk_mul_f32 v[186:187], v[186:187], v[190:191]
	v_add_f32_e32 v3, 1.0, v3
	v_pk_mul_f32 v[62:63], v[62:63], v[186:187]
	v_lshlrev_b32_e32 v187, 16, v198
	v_rcp_f32_e32 v186, v3
	v_add_f32_e32 v3, v150, v187
	v_mul_f32_e32 v3, 0xbfb8aa3b, v3
	v_exp_f32_e32 v3, v3
	v_pk_add_f32 v[4:5], v[200:201], 1.0 op_sel_hi:[1,0]
	s_waitcnt vmcnt(4)
	v_lshlrev_b32_e32 v188, 16, v238
	v_pk_mul_f32 v[4:5], v[4:5], v[202:203]
	v_add_f32_e32 v3, 1.0, v3
	v_pk_mul_f32 v[64:65], v[64:65], v[4:5]
	v_and_b32_e32 v5, 0xffff0000, v196
	v_rcp_f32_e32 v190, v3
	v_add_f32_e32 v3, v159, v5
	v_mul_f32_e32 v3, 0xbfb8aa3b, v3
	v_exp_f32_e32 v3, v3
	v_add_f32_e32 v187, v154, v188
	v_and_b32_e32 v189, 0xffff0000, v198
	v_mul_f32_e32 v187, 0xbfb8aa3b, v187
	v_add_f32_e32 v3, 1.0, v3
	v_exp_f32_e32 v188, v187
	v_rcp_f32_e32 v187, v3
	v_add_f32_e32 v3, v151, v189
	v_mul_f32_e32 v3, 0xbfb8aa3b, v3
	v_exp_f32_e32 v3, v3
	v_lshlrev_b32_e32 v192, 16, v197
	v_and_b32_e32 v191, 0xffff0000, v236
	v_add_f32_e32 v5, v163, v191
	v_add_f32_e32 v3, 1.0, v3
	v_rcp_f32_e32 v191, v3
	v_add_f32_e32 v3, v160, v192
	v_mul_f32_e32 v3, 0xbfb8aa3b, v3
	v_exp_f32_e32 v3, v3
	v_lshlrev_b32_e32 v195, 16, v199
	v_lshlrev_b32_e32 v194, 16, v237
	v_and_b32_e32 v193, 0xffff0000, v197
	v_add_f32_e32 v3, 1.0, v3
	v_add_f32_e32 v192, v164, v194
	v_rcp_f32_e32 v194, v3
	v_add_f32_e32 v3, v152, v195
	v_mul_f32_e32 v3, 0xbfb8aa3b, v3
	v_add_f32_e32 v193, v161, v193
	v_and_b32_e32 v197, 0xffff0000, v199
	v_lshlrev_b32_e32 v199, 16, v239
	v_exp_f32_e32 v3, v3
	v_mul_f32_e32 v193, 0xbfb8aa3b, v193
	v_add_f32_e32 v195, v156, v199
	v_exp_f32_e32 v199, v193
	v_lshlrev_b32_e32 v4, 16, v236
	v_and_b32_e32 v198, 0xffff0000, v237
	v_and_b32_e32 v196, 0xffff0000, v238
	v_mul_f32_e32 v195, 0xbfb8aa3b, v195
	v_add_f32_e32 v4, v162, v4
	v_add_f32_e32 v189, v155, v196
	v_exp_f32_e32 v196, v195
	v_add_f32_e32 v195, v165, v198
	v_mul_f32_e32 v4, 0xbfb8aa3b, v4
	v_mul_f32_e32 v5, 0xbfb8aa3b, v5
	v_mul_f32_e32 v192, 0xbfb8aa3b, v192
	v_add_f32_e32 v3, 1.0, v3
	v_mul_f32_e32 v193, 0xbfb8aa3b, v195
	v_exp_f32_e32 v4, v4
	v_exp_f32_e32 v5, v5
	v_exp_f32_e32 v192, v192
	v_exp_f32_e32 v193, v193
	v_rcp_f32_e32 v198, v3
	v_add_f32_e32 v3, 1.0, v199
	v_rcp_f32_e32 v195, v3
	v_pk_add_f32 v[192:193], v[192:193], 1.0 op_sel_hi:[1,0]
	v_pk_add_f32 v[4:5], v[4:5], 1.0 op_sel_hi:[1,0]
	v_and_b32_e32 v200, 0xffff0000, v239
	v_pk_mul_f32 v[4:5], v[4:5], v[186:187]
	v_pk_mul_f32 v[186:187], v[192:193], v[194:195]
	v_add_f32_e32 v3, v157, v200
	v_pk_mul_f32 v[60:61], v[60:61], v[186:187]
	v_add_f32_e32 v186, v153, v197
	v_mul_f32_e32 v186, 0xbfb8aa3b, v186
	v_exp_f32_e32 v186, v186
	v_mul_f32_e32 v3, 0xbfb8aa3b, v3
	v_exp_f32_e32 v197, v3
	v_mul_f32_e32 v189, 0xbfb8aa3b, v189
	v_add_f32_e32 v3, 1.0, v186
	v_rcp_f32_e32 v199, v3
	s_waitcnt vmcnt(3)
; __device__ __forceinline__ void unpack8(const u32x4 w, float (&v)[8]) { v[0] = bf_lo(w.x); v[1] = bf_hi(w.x); v[2] = bf_lo(w.y); v[3] = bf_hi(w.y); v[4] = bf_lo(w.z); v[5] = bf_hi(w.z); v[6] = bf_lo(w.w); v[7] = bf_hi(w.w); }
;     __device__ __forceinline__ void after(int te, f32x4 (&acc)[2][2][4][2], const Unit& u, int wr, int wc, int fr, int fq) const {
;     ...
;                     for (int m = 0; m < 4; ++m) { const size_t r = (size_t)(row0 + ai * HALF + m * 16); gs[m] = *(const u32x4*)(proj + r * LDP + PGS + c); ga[m] = *(const u32x4*)(proj + r * LDP + PGA + c); }
; #pragma unroll
;                     for (int m = 0; m < 4; ++m) { float vs[8], va[8]; unpack8(gs[m], vs); unpack8(ga[m], va);
; #pragma unroll
;                         for (int e = 0; e < 4; ++e) {
;                             acc[ai][bj][m][0][e] *= (1.f + __expf(-(va[e] + a0[e]))) * __builtin_amdgcn_rcpf(1.f + __expf(-(vs[e] + s0[e])));
;                             acc[ai][bj][m][1][e] *= (1.f + __expf(-(va[4 + e] + a1[e]))) * __builtin_amdgcn_rcpf(1.f + __expf(-(vs[4 + e] + s1[e]))); } }
	v_lshlrev_b32_e32 v3, 16, v146
	v_add_f32_e32 v3, v158, v3
	v_exp_f32_e32 v189, v189
	v_mul_f32_e32 v3, 0xbfb8aa3b, v3
	v_exp_f32_e32 v3, v3
	v_pk_mul_f32 v[58:59], v[58:59], v[4:5]
	v_pk_add_f32 v[4:5], v[196:197], 1.0 op_sel_hi:[1,0]
	v_pk_add_f32 v[186:187], v[188:189], 1.0 op_sel_hi:[1,0]
	v_pk_mul_f32 v[4:5], v[4:5], v[198:199]
	v_pk_mul_f32 v[186:187], v[186:187], v[190:191]
	v_pk_mul_f32 v[56:57], v[56:57], v[4:5]
	v_and_b32_e32 v5, 0xffff0000, v146
	v_lshlrev_b32_e32 v146, 16, v148
	v_add_f32_e32 v3, 1.0, v3
	v_pk_mul_f32 v[54:55], v[54:55], v[186:187]
	v_lshlrev_b32_e32 v186, 16, v147
	v_and_b32_e32 v187, 0xffff0000, v147
	v_and_b32_e32 v147, 0xffff0000, v148
	s_waitcnt vmcnt(2)
	v_lshlrev_b32_e32 v4, 16, v142
	v_and_b32_e32 v148, 0xffff0000, v142
	v_rcp_f32_e32 v142, v3
	v_add_f32_e32 v3, v150, v146
	v_mul_f32_e32 v3, 0xbfb8aa3b, v3
	v_exp_f32_e32 v3, v3
	v_lshlrev_b32_e32 v188, 16, v149
	v_and_b32_e32 v189, 0xffff0000, v149
	v_lshlrev_b32_e32 v149, 16, v143
	v_add_f32_e32 v3, 1.0, v3
	v_rcp_f32_e32 v146, v3
	v_add_f32_e32 v3, v159, v5
	v_mul_f32_e32 v3, 0xbfb8aa3b, v3
	v_exp_f32_e32 v3, v3
	v_and_b32_e32 v190, 0xffff0000, v143
	v_lshlrev_b32_e32 v143, 16, v144
	v_add_f32_e32 v143, v154, v143
	v_mul_f32_e32 v143, 0xbfb8aa3b, v143
	v_add_f32_e32 v3, 1.0, v3
	v_and_b32_e32 v191, 0xffff0000, v144
	v_exp_f32_e32 v144, v143
	v_rcp_f32_e32 v143, v3
	v_add_f32_e32 v3, v151, v147
	v_mul_f32_e32 v3, 0xbfb8aa3b, v3
	v_exp_f32_e32 v3, v3
	v_add_f32_e32 v187, v161, v187
	v_lshlrev_b32_e32 v192, 16, v145
	v_mul_f32_e32 v187, 0xbfb8aa3b, v187
	v_add_f32_e32 v3, 1.0, v3
	v_rcp_f32_e32 v147, v3
	v_add_f32_e32 v3, v160, v186
	v_mul_f32_e32 v3, 0xbfb8aa3b, v3
	v_exp_f32_e32 v3, v3
	v_add_f32_e32 v5, v163, v148
	v_add_f32_e32 v148, v164, v149
	v_add_f32_e32 v149, v156, v192
	v_add_f32_e32 v3, 1.0, v3
	v_rcp_f32_e32 v186, v3
	v_add_f32_e32 v3, v152, v188
	v_mul_f32_e32 v3, 0xbfb8aa3b, v3
	v_exp_f32_e32 v3, v3
	v_exp_f32_e32 v187, v187
	v_mul_f32_e32 v149, 0xbfb8aa3b, v149
	v_add_f32_e32 v4, v162, v4
	v_exp_f32_e32 v188, v149
	v_add_f32_e32 v149, v165, v190
	v_mul_f32_e32 v4, 0xbfb8aa3b, v4
	v_mul_f32_e32 v5, 0xbfb8aa3b, v5
	v_mul_f32_e32 v148, 0xbfb8aa3b, v148
	v_add_f32_e32 v3, 1.0, v3
	v_mul_f32_e32 v149, 0xbfb8aa3b, v149
	v_exp_f32_e32 v4, v4
	v_exp_f32_e32 v5, v5
	v_exp_f32_e32 v148, v148
	v_exp_f32_e32 v149, v149
	v_rcp_f32_e32 v190, v3
	v_add_f32_e32 v3, 1.0, v187
	v_rcp_f32_e32 v187, v3
	v_pk_add_f32 v[148:149], v[148:149], 1.0 op_sel_hi:[1,0]
	v_pk_add_f32 v[4:5], v[4:5], 1.0 op_sel_hi:[1,0]
	v_and_b32_e32 v193, 0xffff0000, v145
	v_pk_mul_f32 v[4:5], v[4:5], v[142:143]
	v_pk_mul_f32 v[142:143], v[148:149], v[186:187]
	v_add_f32_e32 v3, v157, v193
	v_pk_mul_f32 v[52:53], v[52:53], v[142:143]
	v_add_f32_e32 v142, v153, v189
	v_mul_f32_e32 v142, 0xbfb8aa3b, v142
	v_mul_f32_e32 v3, 0xbfb8aa3b, v3
	v_exp_f32_e32 v142, v142
	v_exp_f32_e32 v189, v3
	v_pk_mul_f32 v[50:51], v[50:51], v[4:5]
	v_add_f32_e32 v3, 1.0, v142
	v_pk_add_f32 v[4:5], v[188:189], 1.0 op_sel_hi:[1,0]
	global_load_dwordx4 v[186:189], v[218:219], off offset:256
	v_add_f32_e32 v145, v155, v191
	v_rcp_f32_e32 v191, v3
	s_waitcnt vmcnt(2)
	v_lshlrev_b32_e32 v3, 16, v130
	v_mul_f32_e32 v145, 0xbfb8aa3b, v145
	v_add_f32_e32 v3, v158, v3
	v_exp_f32_e32 v145, v145
	v_mul_f32_e32 v3, 0xbfb8aa3b, v3
	v_exp_f32_e32 v3, v3
	v_pk_mul_f32 v[4:5], v[4:5], v[190:191]
	v_pk_add_f32 v[142:143], v[144:145], 1.0 op_sel_hi:[1,0]
	v_pk_mul_f32 v[48:49], v[48:49], v[4:5]
	v_pk_mul_f32 v[142:143], v[142:143], v[146:147]
	v_and_b32_e32 v5, 0xffff0000, v130
	v_lshlrev_b32_e32 v130, 16, v132
	v_add_f32_e32 v3, 1.0, v3
	v_pk_mul_f32 v[46:47], v[46:47], v[142:143]
	v_lshlrev_b32_e32 v142, 16, v131
	v_and_b32_e32 v143, 0xffff0000, v131
	v_and_b32_e32 v131, 0xffff0000, v132
	s_waitcnt vmcnt(1)
	v_lshlrev_b32_e32 v4, 16, v126
	v_and_b32_e32 v132, 0xffff0000, v126
	v_rcp_f32_e32 v126, v3
	v_add_f32_e32 v3, v150, v130
	v_mul_f32_e32 v3, 0xbfb8aa3b, v3
	v_exp_f32_e32 v3, v3
	global_load_dwordx4 v[190:193], v[216:217], off offset:256
	v_lshlrev_b32_e32 v144, 16, v133
	v_and_b32_e32 v145, 0xffff0000, v133
	v_add_f32_e32 v3, 1.0, v3
	v_rcp_f32_e32 v130, v3
	v_add_f32_e32 v3, v159, v5
	v_mul_f32_e32 v3, 0xbfb8aa3b, v3
	v_exp_f32_e32 v3, v3
	v_lshlrev_b32_e32 v133, 16, v127
	v_and_b32_e32 v146, 0xffff0000, v127
	v_lshlrev_b32_e32 v127, 16, v128
	v_add_f32_e32 v127, v154, v127
	v_mul_f32_e32 v127, 0xbfb8aa3b, v127
	v_add_f32_e32 v3, 1.0, v3
	v_and_b32_e32 v147, 0xffff0000, v128
	v_exp_f32_e32 v128, v127
	v_rcp_f32_e32 v127, v3
	v_add_f32_e32 v3, v151, v131
	v_mul_f32_e32 v3, 0xbfb8aa3b, v3
	v_exp_f32_e32 v3, v3
	v_add_f32_e32 v143, v161, v143
	v_lshlrev_b32_e32 v148, 16, v129
	v_mul_f32_e32 v143, 0xbfb8aa3b, v143
	v_add_f32_e32 v3, 1.0, v3
	v_rcp_f32_e32 v131, v3
	v_add_f32_e32 v3, v160, v142
	v_mul_f32_e32 v3, 0xbfb8aa3b, v3
	v_exp_f32_e32 v3, v3
	v_add_f32_e32 v5, v163, v132
	v_add_f32_e32 v132, v164, v133
	v_add_f32_e32 v133, v156, v148
	v_add_f32_e32 v3, 1.0, v3
	v_rcp_f32_e32 v142, v3
	v_add_f32_e32 v3, v152, v144
	v_mul_f32_e32 v3, 0xbfb8aa3b, v3
	v_exp_f32_e32 v3, v3
	v_exp_f32_e32 v143, v143
	v_mul_f32_e32 v133, 0xbfb8aa3b, v133
	v_add_f32_e32 v4, v162, v4
	v_exp_f32_e32 v144, v133
	v_add_f32_e32 v133, v165, v146
	v_mul_f32_e32 v4, 0xbfb8aa3b, v4
	v_mul_f32_e32 v5, 0xbfb8aa3b, v5
	v_mul_f32_e32 v132, 0xbfb8aa3b, v132
	v_add_f32_e32 v3, 1.0, v3
	v_mul_f32_e32 v133, 0xbfb8aa3b, v133
	v_exp_f32_e32 v4, v4
	v_exp_f32_e32 v5, v5
	v_exp_f32_e32 v132, v132
	v_exp_f32_e32 v133, v133
	v_rcp_f32_e32 v146, v3
	v_add_f32_e32 v3, 1.0, v143
	v_rcp_f32_e32 v143, v3
	v_pk_add_f32 v[132:133], v[132:133], 1.0 op_sel_hi:[1,0]
	v_pk_add_f32 v[4:5], v[4:5], 1.0 op_sel_hi:[1,0]
	v_and_b32_e32 v149, 0xffff0000, v129
	v_pk_mul_f32 v[4:5], v[4:5], v[126:127]
	v_pk_mul_f32 v[126:127], v[132:133], v[142:143]
	v_add_f32_e32 v129, v155, v147
	v_pk_mul_f32 v[44:45], v[44:45], v[126:127]
	v_add_f32_e32 v126, v153, v145
	v_mul_f32_e32 v126, 0xbfb8aa3b, v126
	v_exp_f32_e32 v126, v126
	v_mul_f32_e32 v129, 0xbfb8aa3b, v129
	v_add_f32_e32 v3, v157, v149
	v_exp_f32_e32 v129, v129
	v_mul_f32_e32 v3, 0xbfb8aa3b, v3
	v_exp_f32_e32 v145, v3
	v_add_f32_e32 v3, 1.0, v126
	v_rcp_f32_e32 v147, v3
	v_pk_add_f32 v[126:127], v[128:129], 1.0 op_sel_hi:[1,0]
	v_pk_mul_f32 v[42:43], v[42:43], v[4:5]
	v_pk_add_f32 v[4:5], v[144:145], 1.0 op_sel_hi:[1,0]
	v_pk_mul_f32 v[126:127], v[126:127], v[130:131]
	v_pk_mul_f32 v[4:5], v[4:5], v[146:147]
	v_pk_mul_f32 v[38:39], v[38:39], v[126:127]
	global_load_dwordx4 v[194:197], v[204:205], off offset:256
	global_load_dwordx4 v[198:201], v[206:207], off offset:256
	global_load_dwordx4 v[146:149], v[208:209], off offset:256
	global_load_dwordx4 v[142:145], v[210:211], off offset:256
	global_load_dwordx4 v[130:133], v[212:213], off offset:256
	global_load_dwordx4 v[126:129], v[214:215], off offset:256
	s_waitcnt vmcnt(7)
; __device__ __forceinline__ void unpack8(const u32x4 w, float (&v)[8]) { v[0] = bf_lo(w.x); v[1] = bf_hi(w.x); v[2] = bf_lo(w.y); v[3] = bf_hi(w.y); v[4] = bf_lo(w.z); v[5] = bf_hi(w.z); v[6] = bf_lo(w.w); v[7] = bf_hi(w.w); }
;     __device__ __forceinline__ void after(int te, f32x4 (&acc)[2][2][4][2], const Unit& u, int wr, int wc, int fr, int fq) const {
;     ...
;                     for (int m = 0; m < 4; ++m) { const size_t r = (size_t)(row0 + ai * HALF + m * 16); gs[m] = *(const u32x4*)(proj + r * LDP + PGS + c); ga[m] = *(const u32x4*)(proj + r * LDP + PGA + c); }
; #pragma unroll
;                     for (int m = 0; m < 4; ++m) { float vs[8], va[8]; unpack8(gs[m], vs); unpack8(ga[m], va);
; #pragma unroll
;                         for (int e = 0; e < 4; ++e) {
;                             acc[ai][bj][m][0][e] *= (1.f + __expf(-(va[e] + a0[e]))) * __builtin_amdgcn_rcpf(1.f + __expf(-(vs[e] + s0[e])));
;                             acc[ai][bj][m][1][e] *= (1.f + __expf(-(va[4 + e] + a1[e]))) * __builtin_amdgcn_rcpf(1.f + __expf(-(vs[4 + e] + s1[e]))); } }
	v_lshlrev_b32_e32 v3, 16, v186
	v_add_f32_e32 v3, v158, v3
	v_mul_f32_e32 v3, 0xbfb8aa3b, v3
	v_exp_f32_e32 v3, v3
	v_lshlrev_b32_e32 v202, 16, v187
	v_and_b32_e32 v203, 0xffff0000, v187
	v_lshlrev_b32_e32 v187, 16, v188
	v_add_f32_e32 v3, 1.0, v3
	v_pk_mul_f32 v[40:41], v[40:41], v[4:5]
	v_and_b32_e32 v5, 0xffff0000, v186
	v_rcp_f32_e32 v186, v3
	v_add_f32_e32 v3, v150, v187
	v_mul_f32_e32 v3, 0xbfb8aa3b, v3
	v_exp_f32_e32 v3, v3
	v_lshlrev_b32_e32 v205, 16, v189
	v_and_b32_e32 v207, 0xffff0000, v189
	s_waitcnt vmcnt(6)
	v_lshlrev_b32_e32 v4, 16, v190
	v_add_f32_e32 v3, 1.0, v3
	v_and_b32_e32 v189, 0xffff0000, v190
	v_rcp_f32_e32 v190, v3
	v_add_f32_e32 v3, v159, v5
	v_mul_f32_e32 v3, 0xbfb8aa3b, v3
	v_exp_f32_e32 v3, v3
	v_and_b32_e32 v204, 0xffff0000, v188
	v_lshlrev_b32_e32 v188, 16, v192
	v_add_f32_e32 v187, v154, v188
	v_mul_f32_e32 v187, 0xbfb8aa3b, v187
	v_add_f32_e32 v3, 1.0, v3
	v_exp_f32_e32 v188, v187
	v_rcp_f32_e32 v187, v3
	v_add_f32_e32 v3, v151, v204
	v_mul_f32_e32 v3, 0xbfb8aa3b, v3
	v_exp_f32_e32 v3, v3
	v_lshlrev_b32_e32 v206, 16, v191
	v_and_b32_e32 v208, 0xffff0000, v191
	v_and_b32_e32 v191, 0xffff0000, v192
	v_add_f32_e32 v3, 1.0, v3
	v_add_f32_e32 v5, v163, v189
	v_add_f32_e32 v189, v155, v191
	v_rcp_f32_e32 v191, v3
	v_add_f32_e32 v3, v160, v202
	v_mul_f32_e32 v3, 0xbfb8aa3b, v3
	v_exp_f32_e32 v3, v3
	v_add_f32_e32 v203, v161, v203
	v_lshlrev_b32_e32 v209, 16, v193
	v_mul_f32_e32 v203, 0xbfb8aa3b, v203
	v_add_f32_e32 v3, 1.0, v3
	v_rcp_f32_e32 v202, v3
	v_add_f32_e32 v3, v152, v205
	v_mul_f32_e32 v3, 0xbfb8aa3b, v3
	v_exp_f32_e32 v3, v3
	v_and_b32_e32 v210, 0xffff0000, v193
	v_add_f32_e32 v193, v156, v209
	v_exp_f32_e32 v203, v203
	v_mul_f32_e32 v193, 0xbfb8aa3b, v193
	v_add_f32_e32 v4, v162, v4
	v_add_f32_e32 v192, v164, v206
	v_exp_f32_e32 v204, v193
	v_add_f32_e32 v193, v165, v208
	v_mul_f32_e32 v4, 0xbfb8aa3b, v4
	v_mul_f32_e32 v5, 0xbfb8aa3b, v5
	v_mul_f32_e32 v192, 0xbfb8aa3b, v192
	v_add_f32_e32 v3, 1.0, v3
	v_mul_f32_e32 v193, 0xbfb8aa3b, v193
	v_exp_f32_e32 v4, v4
	v_exp_f32_e32 v5, v5
	v_exp_f32_e32 v192, v192
	v_exp_f32_e32 v193, v193
	v_rcp_f32_e32 v206, v3
	v_add_f32_e32 v3, 1.0, v203
	v_rcp_f32_e32 v203, v3
	v_pk_add_f32 v[192:193], v[192:193], 1.0 op_sel_hi:[1,0]
	v_pk_add_f32 v[4:5], v[4:5], 1.0 op_sel_hi:[1,0]
	v_add_f32_e32 v3, v157, v210
	v_pk_mul_f32 v[4:5], v[4:5], v[186:187]
	v_pk_mul_f32 v[186:187], v[192:193], v[202:203]
	v_mul_f32_e32 v3, 0xbfb8aa3b, v3
	v_pk_mul_f32 v[36:37], v[36:37], v[186:187]
	v_add_f32_e32 v186, v153, v207
	v_mul_f32_e32 v186, 0xbfb8aa3b, v186
	v_exp_f32_e32 v186, v186
	v_exp_f32_e32 v205, v3
	v_mul_f32_e32 v189, 0xbfb8aa3b, v189
	v_exp_f32_e32 v189, v189
	v_add_f32_e32 v3, 1.0, v186
	v_rcp_f32_e32 v207, v3
	s_waitcnt vmcnt(5)
	v_lshlrev_b32_e32 v3, 16, v194
	v_add_f32_e32 v3, v158, v3
	v_mul_f32_e32 v3, 0xbfb8aa3b, v3
	v_exp_f32_e32 v3, v3
	v_pk_add_f32 v[186:187], v[188:189], 1.0 op_sel_hi:[1,0]
	v_pk_mul_f32 v[34:35], v[34:35], v[4:5]
	v_pk_mul_f32 v[186:187], v[186:187], v[190:191]
	v_add_f32_e32 v3, 1.0, v3
	v_pk_mul_f32 v[30:31], v[30:31], v[186:187]
	v_lshlrev_b32_e32 v187, 16, v196
	v_rcp_f32_e32 v186, v3
	v_add_f32_e32 v3, v150, v187
	v_mul_f32_e32 v3, 0xbfb8aa3b, v3
	v_exp_f32_e32 v3, v3
	v_pk_add_f32 v[4:5], v[204:205], 1.0 op_sel_hi:[1,0]
	s_waitcnt vmcnt(4)
	v_lshlrev_b32_e32 v188, 16, v200
	v_pk_mul_f32 v[4:5], v[4:5], v[206:207]
	v_add_f32_e32 v3, 1.0, v3
	v_pk_mul_f32 v[32:33], v[32:33], v[4:5]
	v_and_b32_e32 v5, 0xffff0000, v194
	v_rcp_f32_e32 v190, v3
	v_add_f32_e32 v3, v159, v5
	v_mul_f32_e32 v3, 0xbfb8aa3b, v3
	v_exp_f32_e32 v3, v3
	v_add_f32_e32 v187, v154, v188
	v_and_b32_e32 v189, 0xffff0000, v196
	v_mul_f32_e32 v187, 0xbfb8aa3b, v187
	v_add_f32_e32 v3, 1.0, v3
	v_exp_f32_e32 v188, v187
	v_rcp_f32_e32 v187, v3
	v_add_f32_e32 v3, v151, v189
	v_mul_f32_e32 v3, 0xbfb8aa3b, v3
	v_exp_f32_e32 v3, v3
	v_lshlrev_b32_e32 v192, 16, v195
	v_and_b32_e32 v191, 0xffff0000, v198
	v_add_f32_e32 v5, v163, v191
	v_add_f32_e32 v3, 1.0, v3
	v_rcp_f32_e32 v191, v3
	v_add_f32_e32 v3, v160, v192
	v_mul_f32_e32 v3, 0xbfb8aa3b, v3
	v_exp_f32_e32 v3, v3
	v_and_b32_e32 v193, 0xffff0000, v195
	v_lshlrev_b32_e32 v195, 16, v197
	v_lshlrev_b32_e32 v194, 16, v199
	v_add_f32_e32 v3, 1.0, v3
	v_add_f32_e32 v192, v164, v194
	v_rcp_f32_e32 v194, v3
	v_add_f32_e32 v3, v152, v195
	v_mul_f32_e32 v3, 0xbfb8aa3b, v3
	v_add_f32_e32 v193, v161, v193
	v_lshlrev_b32_e32 v4, 16, v198
	v_and_b32_e32 v198, 0xffff0000, v199
	v_lshlrev_b32_e32 v199, 16, v201
	v_exp_f32_e32 v3, v3
	v_mul_f32_e32 v193, 0xbfb8aa3b, v193
	v_add_f32_e32 v195, v156, v199
	v_exp_f32_e32 v199, v193
	v_and_b32_e32 v196, 0xffff0000, v200
	v_mul_f32_e32 v195, 0xbfb8aa3b, v195
	v_add_f32_e32 v4, v162, v4
	v_add_f32_e32 v189, v155, v196
	v_exp_f32_e32 v196, v195
	v_add_f32_e32 v195, v165, v198
	v_mul_f32_e32 v4, 0xbfb8aa3b, v4
	v_mul_f32_e32 v5, 0xbfb8aa3b, v5
	v_mul_f32_e32 v192, 0xbfb8aa3b, v192
	v_add_f32_e32 v3, 1.0, v3
	v_mul_f32_e32 v193, 0xbfb8aa3b, v195
	v_exp_f32_e32 v4, v4
	v_exp_f32_e32 v5, v5
	v_exp_f32_e32 v192, v192
	v_exp_f32_e32 v193, v193
	v_rcp_f32_e32 v198, v3
	v_add_f32_e32 v3, 1.0, v199
	v_rcp_f32_e32 v195, v3
	v_pk_add_f32 v[192:193], v[192:193], 1.0 op_sel_hi:[1,0]
	v_pk_add_f32 v[4:5], v[4:5], 1.0 op_sel_hi:[1,0]
	v_and_b32_e32 v197, 0xffff0000, v197
	v_pk_mul_f32 v[4:5], v[4:5], v[186:187]
	v_pk_mul_f32 v[186:187], v[192:193], v[194:195]
	v_and_b32_e32 v200, 0xffff0000, v201
	v_pk_mul_f32 v[28:29], v[28:29], v[186:187]
	v_add_f32_e32 v186, v153, v197
	v_mul_f32_e32 v186, 0xbfb8aa3b, v186
	v_exp_f32_e32 v186, v186
	v_add_f32_e32 v3, v157, v200
	v_mul_f32_e32 v3, 0xbfb8aa3b, v3
	v_exp_f32_e32 v197, v3
	v_add_f32_e32 v3, 1.0, v186
	v_rcp_f32_e32 v199, v3
	s_waitcnt vmcnt(3)
; __device__ __forceinline__ void unpack8(const u32x4 w, float (&v)[8]) { v[0] = bf_lo(w.x); v[1] = bf_hi(w.x); v[2] = bf_lo(w.y); v[3] = bf_hi(w.y); v[4] = bf_lo(w.z); v[5] = bf_hi(w.z); v[6] = bf_lo(w.w); v[7] = bf_hi(w.w); }
;     __device__ __forceinline__ void after(int te, f32x4 (&acc)[2][2][4][2], const Unit& u, int wr, int wc, int fr, int fq) const {
;     ...
;                     for (int m = 0; m < 4; ++m) { const size_t r = (size_t)(row0 + ai * HALF + m * 16); gs[m] = *(const u32x4*)(proj + r * LDP + PGS + c); ga[m] = *(const u32x4*)(proj + r * LDP + PGA + c); }
; #pragma unroll
;                     for (int m = 0; m < 4; ++m) { float vs[8], va[8]; unpack8(gs[m], vs); unpack8(ga[m], va);
; #pragma unroll
;                         for (int e = 0; e < 4; ++e) {
;                             acc[ai][bj][m][0][e] *= (1.f + __expf(-(va[e] + a0[e]))) * __builtin_amdgcn_rcpf(1.f + __expf(-(vs[e] + s0[e])));
;                             acc[ai][bj][m][1][e] *= (1.f + __expf(-(va[4 + e] + a1[e]))) * __builtin_amdgcn_rcpf(1.f + __expf(-(vs[4 + e] + s1[e]))); } }
	v_lshlrev_b32_e32 v3, 16, v146
	v_mul_f32_e32 v189, 0xbfb8aa3b, v189
	v_add_f32_e32 v3, v158, v3
	v_exp_f32_e32 v189, v189
	v_mul_f32_e32 v3, 0xbfb8aa3b, v3
	v_exp_f32_e32 v3, v3
	v_pk_mul_f32 v[26:27], v[26:27], v[4:5]
	v_pk_add_f32 v[4:5], v[196:197], 1.0 op_sel_hi:[1,0]
	v_pk_add_f32 v[186:187], v[188:189], 1.0 op_sel_hi:[1,0]
	v_pk_mul_f32 v[4:5], v[4:5], v[198:199]
	v_pk_mul_f32 v[186:187], v[186:187], v[190:191]
	v_pk_mul_f32 v[24:25], v[24:25], v[4:5]
	v_and_b32_e32 v5, 0xffff0000, v146
	v_lshlrev_b32_e32 v146, 16, v148
	v_add_f32_e32 v3, 1.0, v3
	v_pk_mul_f32 v[22:23], v[22:23], v[186:187]
	v_lshlrev_b32_e32 v186, 16, v147
	v_and_b32_e32 v187, 0xffff0000, v147
	v_and_b32_e32 v147, 0xffff0000, v148
	s_waitcnt vmcnt(2)
	v_lshlrev_b32_e32 v4, 16, v142
	v_and_b32_e32 v148, 0xffff0000, v142
	v_rcp_f32_e32 v142, v3
	v_add_f32_e32 v3, v150, v146
	v_mul_f32_e32 v3, 0xbfb8aa3b, v3
	v_exp_f32_e32 v3, v3
	v_lshlrev_b32_e32 v188, 16, v149
	v_and_b32_e32 v189, 0xffff0000, v149
	v_lshlrev_b32_e32 v149, 16, v143
	v_add_f32_e32 v3, 1.0, v3
	v_rcp_f32_e32 v146, v3
	v_add_f32_e32 v3, v159, v5
	v_mul_f32_e32 v3, 0xbfb8aa3b, v3
	v_exp_f32_e32 v3, v3
	v_and_b32_e32 v190, 0xffff0000, v143
	v_lshlrev_b32_e32 v143, 16, v144
	v_add_f32_e32 v143, v154, v143
	v_mul_f32_e32 v143, 0xbfb8aa3b, v143
	v_add_f32_e32 v3, 1.0, v3
	v_and_b32_e32 v191, 0xffff0000, v144
	v_exp_f32_e32 v144, v143
	v_rcp_f32_e32 v143, v3
	v_add_f32_e32 v3, v151, v147
	v_mul_f32_e32 v3, 0xbfb8aa3b, v3
	v_exp_f32_e32 v3, v3
	v_add_f32_e32 v187, v161, v187
	v_lshlrev_b32_e32 v192, 16, v145
	v_mul_f32_e32 v187, 0xbfb8aa3b, v187
	v_add_f32_e32 v3, 1.0, v3
	v_rcp_f32_e32 v147, v3
	v_add_f32_e32 v3, v160, v186
	v_mul_f32_e32 v3, 0xbfb8aa3b, v3
	v_exp_f32_e32 v3, v3
	v_add_f32_e32 v5, v163, v148
	v_add_f32_e32 v148, v164, v149
	v_add_f32_e32 v149, v156, v192
	v_add_f32_e32 v3, 1.0, v3
	v_rcp_f32_e32 v186, v3
	v_add_f32_e32 v3, v152, v188
	v_mul_f32_e32 v3, 0xbfb8aa3b, v3
	v_exp_f32_e32 v3, v3
	v_exp_f32_e32 v187, v187
	v_mul_f32_e32 v149, 0xbfb8aa3b, v149
	v_add_f32_e32 v4, v162, v4
	v_exp_f32_e32 v188, v149
	v_add_f32_e32 v149, v165, v190
	v_mul_f32_e32 v4, 0xbfb8aa3b, v4
	v_mul_f32_e32 v5, 0xbfb8aa3b, v5
	v_mul_f32_e32 v148, 0xbfb8aa3b, v148
	v_add_f32_e32 v3, 1.0, v3
	v_mul_f32_e32 v149, 0xbfb8aa3b, v149
	v_exp_f32_e32 v4, v4
	v_exp_f32_e32 v5, v5
	v_exp_f32_e32 v148, v148
	v_exp_f32_e32 v149, v149
	v_rcp_f32_e32 v190, v3
	v_add_f32_e32 v3, 1.0, v187
	v_rcp_f32_e32 v187, v3
	v_pk_add_f32 v[148:149], v[148:149], 1.0 op_sel_hi:[1,0]
	v_pk_add_f32 v[4:5], v[4:5], 1.0 op_sel_hi:[1,0]
	v_and_b32_e32 v193, 0xffff0000, v145
	v_pk_mul_f32 v[4:5], v[4:5], v[142:143]
	v_pk_mul_f32 v[142:143], v[148:149], v[186:187]
	v_add_f32_e32 v3, v157, v193
	v_pk_mul_f32 v[20:21], v[20:21], v[142:143]
	v_add_f32_e32 v142, v153, v189
	v_mul_f32_e32 v142, 0xbfb8aa3b, v142
	v_exp_f32_e32 v142, v142
	v_mul_f32_e32 v3, 0xbfb8aa3b, v3
	v_exp_f32_e32 v189, v3
	v_add_f32_e32 v145, v155, v191
	v_add_f32_e32 v3, 1.0, v142
	v_rcp_f32_e32 v191, v3
	s_waitcnt vmcnt(1)
	v_lshlrev_b32_e32 v3, 16, v130
	v_mul_f32_e32 v145, 0xbfb8aa3b, v145
	v_add_f32_e32 v3, v158, v3
	v_exp_f32_e32 v145, v145
	v_mul_f32_e32 v3, 0xbfb8aa3b, v3
	v_exp_f32_e32 v3, v3
	v_pk_mul_f32 v[18:19], v[18:19], v[4:5]
	v_pk_add_f32 v[4:5], v[188:189], 1.0 op_sel_hi:[1,0]
	v_pk_add_f32 v[142:143], v[144:145], 1.0 op_sel_hi:[1,0]
	v_pk_mul_f32 v[4:5], v[4:5], v[190:191]
	v_pk_mul_f32 v[142:143], v[142:143], v[146:147]
	v_pk_mul_f32 v[16:17], v[16:17], v[4:5]
	v_and_b32_e32 v5, 0xffff0000, v130
	v_lshlrev_b32_e32 v130, 16, v132
	v_add_f32_e32 v3, 1.0, v3
	v_pk_mul_f32 v[14:15], v[14:15], v[142:143]
	v_lshlrev_b32_e32 v142, 16, v131
	v_and_b32_e32 v143, 0xffff0000, v131
	v_and_b32_e32 v131, 0xffff0000, v132
	s_waitcnt vmcnt(0)
	v_lshlrev_b32_e32 v4, 16, v126
	v_and_b32_e32 v132, 0xffff0000, v126
	v_rcp_f32_e32 v126, v3
	v_add_f32_e32 v3, v150, v130
	v_mul_f32_e32 v3, 0xbfb8aa3b, v3
	v_exp_f32_e32 v3, v3
	v_lshlrev_b32_e32 v144, 16, v133
	v_and_b32_e32 v145, 0xffff0000, v133
	v_lshlrev_b32_e32 v133, 16, v127
	v_add_f32_e32 v3, 1.0, v3
	v_rcp_f32_e32 v130, v3
	v_add_f32_e32 v3, v159, v5
	v_mul_f32_e32 v3, 0xbfb8aa3b, v3
	v_exp_f32_e32 v3, v3
	v_and_b32_e32 v146, 0xffff0000, v127
	v_lshlrev_b32_e32 v127, 16, v128
	v_add_f32_e32 v127, v154, v127
	v_mul_f32_e32 v127, 0xbfb8aa3b, v127
	v_add_f32_e32 v3, 1.0, v3
	v_and_b32_e32 v147, 0xffff0000, v128
	v_exp_f32_e32 v128, v127
	v_rcp_f32_e32 v127, v3
	v_add_f32_e32 v3, v151, v131
	v_mul_f32_e32 v3, 0xbfb8aa3b, v3
	v_exp_f32_e32 v3, v3
	v_add_f32_e32 v143, v161, v143
	v_lshlrev_b32_e32 v148, 16, v129
	v_mul_f32_e32 v143, 0xbfb8aa3b, v143
	v_add_f32_e32 v3, 1.0, v3
	v_rcp_f32_e32 v131, v3
	v_add_f32_e32 v3, v160, v142
	v_mul_f32_e32 v3, 0xbfb8aa3b, v3
	v_exp_f32_e32 v3, v3
	v_add_f32_e32 v5, v163, v132
	v_add_f32_e32 v132, v164, v133
	v_add_f32_e32 v133, v156, v148
	v_add_f32_e32 v3, 1.0, v3
	v_rcp_f32_e32 v142, v3
	v_add_f32_e32 v3, v152, v144
	v_mul_f32_e32 v3, 0xbfb8aa3b, v3
	v_exp_f32_e32 v3, v3
	v_exp_f32_e32 v143, v143
	v_mul_f32_e32 v133, 0xbfb8aa3b, v133
	v_add_f32_e32 v4, v162, v4
	v_exp_f32_e32 v144, v133
	v_add_f32_e32 v133, v165, v146
	v_mul_f32_e32 v4, 0xbfb8aa3b, v4
	v_mul_f32_e32 v5, 0xbfb8aa3b, v5
	v_mul_f32_e32 v132, 0xbfb8aa3b, v132
	v_add_f32_e32 v3, 1.0, v3
	v_mul_f32_e32 v133, 0xbfb8aa3b, v133
	v_exp_f32_e32 v4, v4
	v_exp_f32_e32 v5, v5
	v_exp_f32_e32 v132, v132
	v_exp_f32_e32 v133, v133
	v_rcp_f32_e32 v146, v3
	v_add_f32_e32 v3, 1.0, v143
	v_rcp_f32_e32 v143, v3
	v_pk_add_f32 v[132:133], v[132:133], 1.0 op_sel_hi:[1,0]
	v_pk_add_f32 v[4:5], v[4:5], 1.0 op_sel_hi:[1,0]
	v_and_b32_e32 v149, 0xffff0000, v129
	v_pk_mul_f32 v[4:5], v[4:5], v[126:127]
	v_pk_mul_f32 v[126:127], v[132:133], v[142:143]
	v_add_f32_e32 v129, v155, v147
	v_pk_mul_f32 v[12:13], v[12:13], v[126:127]
	v_add_f32_e32 v126, v153, v145
	v_mul_f32_e32 v126, 0xbfb8aa3b, v126
	v_exp_f32_e32 v126, v126
	v_add_f32_e32 v3, v157, v149
	v_mul_f32_e32 v129, 0xbfb8aa3b, v129
	v_mul_f32_e32 v3, 0xbfb8aa3b, v3
	v_exp_f32_e32 v129, v129
	v_exp_f32_e32 v145, v3
	v_add_f32_e32 v3, 1.0, v126
	v_rcp_f32_e32 v147, v3
	v_pk_mul_f32 v[10:11], v[10:11], v[4:5]
	v_pk_add_f32 v[4:5], v[144:145], 1.0 op_sel_hi:[1,0]
	v_pk_add_f32 v[126:127], v[128:129], 1.0 op_sel_hi:[1,0]
	v_pk_mul_f32 v[4:5], v[4:5], v[146:147]
	v_pk_mul_f32 v[126:127], v[126:127], v[130:131]
	v_pk_mul_f32 v[8:9], v[8:9], v[4:5]
	v_pk_mul_f32 v[6:7], v[6:7], v[126:127]

; #define PG8_STAGE(bufoff, gbase, voff) do { _Pragma("unroll") for (int _i = 0; _i < 2; ++_i) \
;         __builtin_amdgcn_global_load_lds((const unsigned*)((const char*)(gbase) + (voff)[_i]), (LAS unsigned*)(lds + (bufoff) + ldsw + _i * 8192), 16, 0, 0); } while (0)
; #define PG8_LDA(dst, b, h) do { _Pragma("unroll") for (int m = 0; m < 4; ++m) _Pragma("unroll") for (int k = 0; k < 2; ++k) dst[m][k] = *(const LAS bf16x8*)(lds + PG8_SA(b, h) + aoff + m * 2048 + k * 1024); } while (0)
; #define PG8_LDB(dst, b, h) do { _Pragma("unroll") for (int n = 0; n < 2; ++n) _Pragma("unroll") for (int k = 0; k < 2; ++k) dst[n][k] = *(const LAS bf16x8*)(lds + PG8_SB(b, h) + boff + n * 2048 + k * 1024); } while (0)
; #define PG8_MMA(ai, bj, At, Bt) do { __builtin_amdgcn_s_setprio(1); _Pragma("unroll") for (int m = 0; m < 4; ++m) _Pragma("unroll") for (int n = 0; n < 2; ++n) _Pragma("unroll") for (int k = 0; k < 2; ++k) \
;         acc[ai][bj][m][n] = __builtin_amdgcn_mfma_f32_16x16x32_bf16(Bt[n][k], At[m][k], acc[ai][bj][m][n], 0, 0, 0); __builtin_amdgcn_s_setprio(0); } while (0)
; #define PG8_WAIT_V(n) asm volatile("s_waitcnt vmcnt(" #n ")" ::: "memory")
; template <class Epi, class Sched, bool ALIGN_EPI, class Hook = NoHook>
; __device__ __forceinline__ void gemm_phase(LAS unsigned char* lds, const Gemm g, const Sched& S, const Epi& E, const Hook& H = Hook()) {
;     ...
;             PG8_LDB(B0, 0, 0); PG8_LDB(B1, 0, 1); PG8_SCHED; PG8_LDA(At, 0, 0); PG8_STAGE(PG8_SA(1, 1), a1 + hA, voffA);
;             PG8_WAIT_V(8); PG8_WAIT_L(0); PG8_BAR; PG8_MMA(0, 0, At, B0); PG8_MMA(0, 1, At, B1); PG8_BAR; PG8_SCHED;
;             PG8_LDA(At, 0, 1); PG8_STAGE(PG8_SB(0, 0), b2, voffB); PG8_STAGE(PG8_SB(0, 1), b2 + hB, voffB); PG8_STAGE(PG8_SA(0, 0), a2, voffA);
;             PG8_WAIT_V(8); PG8_WAIT_L(0); PG8_BAR; PG8_MMA(1, 0, At, B0); PG8_MMA(1, 1, At, B1); PG8_BAR; PG8_SCHED;
;             PG8_LDB(B0, 1, 0); PG8_LDB(B1, 1, 1); PG8_SCHED; PG8_LDA(At, 1, 0); PG8_STAGE(PG8_SA(0, 1), a2 + hA, voffA);
;             PG8_WAIT_V(8); PG8_WAIT_L(0); PG8_BAR; PG8_MMA(0, 0, At, B0); PG8_MMA(0, 1, At, B1); PG8_BAR; PG8_SCHED;
;             PG8_LDA(At, 1, 1); PG8_STAGE(PG8_SB(1, 0), b3, voffB); PG8_STAGE(PG8_SB(1, 1), b3 + hB, voffB); PG8_STAGE(PG8_SA(1, 0), a3, voffA);
;             PG8_WAIT_V(8); PG8_WAIT_L(0); PG8_BAR; PG8_MMA(1, 0, At, B0); PG8_MMA(1, 1, At, B1); PG8_BAR; PG8_SCHED;
.LBB0_850:
	ds_read_b128 v[146:149], v1
	ds_read_b128 v[150:153], v1 offset:1024
	s_add_u32 s20, s6, 0x87c00080
	s_addc_u32 s21, s7, -1
	s_cmp_lg_u32 s42, 60
	s_cselect_b32 s20, s20, 0
	s_cselect_b32 s21, s21, 0
	s_add_u32 s22, s2, s20
	s_addc_u32 s23, s3, s21
	s_add_u32 s20, s14, s20
	s_addc_u32 s21, s15, s21
	s_mov_b32 m0, s43
	ds_read_b128 v[154:157], v1 offset:2048
	ds_read_b128 v[158:161], v1 offset:3072
	ds_read_b128 v[162:165], v142
	ds_read_b128 v[166:169], v142 offset:1024
	ds_read_b128 v[170:173], v142 offset:2048
	ds_read_b128 v[174:177], v142 offset:3072
	v_lshl_add_u64 v[178:179], v[138:139], 0, s[6:7]
	global_load_lds_dwordx4 v[178:179], off
	ds_read_b128 v[186:189], v143
	ds_read_b128 v[190:193], v143 offset:1024
	ds_read_b128 v[194:197], v143 offset:2048
	ds_read_b128 v[198:201], v143 offset:3072
	ds_read_b128 v[202:205], v143 offset:4096
	ds_read_b128 v[206:209], v143 offset:5120
	ds_read_b128 v[210:213], v143 offset:6144
	ds_read_b128 v[214:217], v143 offset:7168
	v_lshl_add_u64 v[178:179], v[140:141], 0, s[6:7]
	s_mov_b32 m0, s44
	s_nop 0
	global_load_lds_dwordx4 v[178:179], off
	s_waitcnt vmcnt(8) lgkmcnt(0)
	s_barrier
	s_setprio 1
	v_mfma_f32_16x16x32_bf16 v[54:57], v[146:149], v[186:189], v[54:57]
	v_mfma_f32_16x16x32_bf16 v[34:37], v[154:157], v[186:189], v[34:37]
	v_mfma_f32_16x16x32_bf16 v[42:45], v[146:149], v[194:197], v[42:45]
	v_mfma_f32_16x16x32_bf16 v[30:33], v[154:157], v[194:197], v[30:33]
	v_mfma_f32_16x16x32_bf16 v[62:65], v[146:149], v[202:205], v[62:65]
	v_mfma_f32_16x16x32_bf16 v[50:53], v[154:157], v[202:205], v[50:53]
	v_mfma_f32_16x16x32_bf16 v[78:81], v[146:149], v[210:213], v[78:81]
	v_mfma_f32_16x16x32_bf16 v[70:73], v[154:157], v[210:213], v[70:73]
	v_mfma_f32_16x16x32_bf16 v[54:57], v[150:153], v[190:193], v[54:57]
	v_mfma_f32_16x16x32_bf16 v[34:37], v[158:161], v[190:193], v[34:37]
	v_mfma_f32_16x16x32_bf16 v[42:45], v[150:153], v[198:201], v[42:45]
	v_mfma_f32_16x16x32_bf16 v[30:33], v[158:161], v[198:201], v[30:33]
	v_mfma_f32_16x16x32_bf16 v[62:65], v[150:153], v[206:209], v[62:65]
	v_mfma_f32_16x16x32_bf16 v[50:53], v[158:161], v[206:209], v[50:53]
	v_mfma_f32_16x16x32_bf16 v[78:81], v[150:153], v[214:217], v[78:81]
	v_mfma_f32_16x16x32_bf16 v[70:73], v[158:161], v[214:217], v[70:73]
	s_setprio 0
	s_setprio 1
	v_mfma_f32_16x16x32_bf16 v[10:13], v[162:165], v[186:189], v[10:13]
	v_mfma_f32_16x16x32_bf16 v[2:5], v[170:173], v[186:189], v[2:5]
	v_mfma_f32_16x16x32_bf16 v[14:17], v[162:165], v[194:197], v[14:17]
	v_mfma_f32_16x16x32_bf16 v[6:9], v[170:173], v[194:197], v[6:9]
	v_mfma_f32_16x16x32_bf16 v[22:25], v[162:165], v[202:205], v[22:25]
	v_mfma_f32_16x16x32_bf16 v[18:21], v[170:173], v[202:205], v[18:21]
	v_mfma_f32_16x16x32_bf16 v[38:41], v[162:165], v[210:213], v[38:41]
	v_mfma_f32_16x16x32_bf16 v[26:29], v[170:173], v[210:213], v[26:29]
	v_mfma_f32_16x16x32_bf16 v[10:13], v[166:169], v[190:193], v[10:13]
	v_mfma_f32_16x16x32_bf16 v[2:5], v[174:177], v[190:193], v[2:5]
	v_mfma_f32_16x16x32_bf16 v[14:17], v[166:169], v[198:201], v[14:17]
	v_mfma_f32_16x16x32_bf16 v[6:9], v[174:177], v[198:201], v[6:9]
	v_mfma_f32_16x16x32_bf16 v[22:25], v[166:169], v[206:209], v[22:25]
	v_mfma_f32_16x16x32_bf16 v[18:21], v[174:177], v[206:209], v[18:21]
	v_mfma_f32_16x16x32_bf16 v[38:41], v[166:169], v[214:217], v[38:41]
	v_mfma_f32_16x16x32_bf16 v[26:29], v[174:177], v[214:217], v[26:29]
	s_barrier
	s_setprio 0
	s_mov_b32 m0, s45
	s_add_u32 s54, s20, 0x100000
	ds_read_b128 v[186:189], v143 offset:16384
	ds_read_b128 v[190:193], v143 offset:17408
	global_load_lds_dwordx4 v132, s[20:21]
	ds_read_b128 v[194:197], v143 offset:18432
	s_mov_b32 m0, s46
	s_addc_u32 s55, s21, 0
	global_load_lds_dwordx4 v136, s[20:21]
	ds_read_b128 v[198:201], v143 offset:19456
	s_mov_b32 m0, s47
	ds_read_b128 v[202:205], v143 offset:20480
	global_load_lds_dwordx4 v132, s[54:55]
	s_mov_b32 m0, s48
	ds_read_b128 v[206:209], v143 offset:21504
	global_load_lds_dwordx4 v136, s[54:55]
	s_add_u32 s58, s22, s4
	s_addc_u32 s59, s23, s5
	s_mov_b32 m0, s28
	ds_read_b128 v[210:213], v143 offset:22528
	global_load_lds_dwordx4 v130, s[22:23]
	s_mov_b32 m0, s29
	ds_read_b128 v[214:217], v143 offset:23552
	global_load_lds_dwordx4 v134, s[22:23]
	s_waitcnt vmcnt(8) lgkmcnt(0)
	s_barrier
	s_setprio 1
	v_mfma_f32_16x16x32_bf16 v[94:97], v[146:149], v[186:189], v[94:97]
	v_mfma_f32_16x16x32_bf16 v[86:89], v[154:157], v[186:189], v[86:89]
	v_mfma_f32_16x16x32_bf16 v[102:105], v[146:149], v[194:197], v[102:105]
	v_mfma_f32_16x16x32_bf16 v[98:101], v[154:157], v[194:197], v[98:101]
	v_mfma_f32_16x16x32_bf16 v[110:113], v[146:149], v[202:205], v[110:113]
	v_mfma_f32_16x16x32_bf16 v[106:109], v[154:157], v[202:205], v[106:109]
	v_mfma_f32_16x16x32_bf16 v[126:129], v[146:149], v[210:213], v[126:129]
	v_mfma_f32_16x16x32_bf16 v[122:125], v[154:157], v[210:213], v[122:125]
	v_mfma_f32_16x16x32_bf16 v[94:97], v[150:153], v[190:193], v[94:97]
	v_mfma_f32_16x16x32_bf16 v[86:89], v[158:161], v[190:193], v[86:89]
	v_mfma_f32_16x16x32_bf16 v[102:105], v[150:153], v[198:201], v[102:105]
	v_mfma_f32_16x16x32_bf16 v[98:101], v[158:161], v[198:201], v[98:101]
	v_mfma_f32_16x16x32_bf16 v[110:113], v[150:153], v[206:209], v[110:113]
	v_mfma_f32_16x16x32_bf16 v[106:109], v[158:161], v[206:209], v[106:109]
	v_mfma_f32_16x16x32_bf16 v[126:129], v[150:153], v[214:217], v[126:129]
	v_mfma_f32_16x16x32_bf16 v[122:125], v[158:161], v[214:217], v[122:125]
	s_setprio 0
	s_setprio 1
	v_mfma_f32_16x16x32_bf16 v[58:61], v[162:165], v[186:189], v[58:61]
	v_mfma_f32_16x16x32_bf16 v[46:49], v[170:173], v[186:189], v[46:49]
	v_mfma_f32_16x16x32_bf16 v[74:77], v[162:165], v[194:197], v[74:77]
	v_mfma_f32_16x16x32_bf16 v[66:69], v[170:173], v[194:197], v[66:69]
	v_mfma_f32_16x16x32_bf16 v[90:93], v[162:165], v[202:205], v[90:93]
	v_mfma_f32_16x16x32_bf16 v[82:85], v[170:173], v[202:205], v[82:85]
	v_mfma_f32_16x16x32_bf16 v[118:121], v[162:165], v[210:213], v[118:121]
	v_mfma_f32_16x16x32_bf16 v[114:117], v[170:173], v[210:213], v[114:117]
	v_mfma_f32_16x16x32_bf16 v[58:61], v[166:169], v[190:193], v[58:61]
	v_mfma_f32_16x16x32_bf16 v[46:49], v[174:177], v[190:193], v[46:49]
	v_mfma_f32_16x16x32_bf16 v[74:77], v[166:169], v[198:201], v[74:77]
	v_mfma_f32_16x16x32_bf16 v[66:69], v[174:177], v[198:201], v[66:69]
	v_mfma_f32_16x16x32_bf16 v[90:93], v[166:169], v[206:209], v[90:93]
	v_mfma_f32_16x16x32_bf16 v[82:85], v[174:177], v[206:209], v[82:85]
	v_mfma_f32_16x16x32_bf16 v[118:121], v[166:169], v[214:217], v[118:121]
	v_mfma_f32_16x16x32_bf16 v[114:117], v[174:177], v[214:217], v[114:117]
	s_barrier
; #define PG8_STAGE(bufoff, gbase, voff) do { _Pragma("unroll") for (int _i = 0; _i < 2; ++_i) \
;         __builtin_amdgcn_global_load_lds((const unsigned*)((const char*)(gbase) + (voff)[_i]), (LAS unsigned*)(lds + (bufoff) + ldsw + _i * 8192), 16, 0, 0); } while (0)
; #define PG8_LDA(dst, b, h) do { _Pragma("unroll") for (int m = 0; m < 4; ++m) _Pragma("unroll") for (int k = 0; k < 2; ++k) dst[m][k] = *(const LAS bf16x8*)(lds + PG8_SA(b, h) + aoff + m * 2048 + k * 1024); } while (0)
; #define PG8_LDB(dst, b, h) do { _Pragma("unroll") for (int n = 0; n < 2; ++n) _Pragma("unroll") for (int k = 0; k < 2; ++k) dst[n][k] = *(const LAS bf16x8*)(lds + PG8_SB(b, h) + boff + n * 2048 + k * 1024); } while (0)
; #define PG8_MMA(ai, bj, At, Bt) do { __builtin_amdgcn_s_setprio(1); _Pragma("unroll") for (int m = 0; m < 4; ++m) _Pragma("unroll") for (int n = 0; n < 2; ++n) _Pragma("unroll") for (int k = 0; k < 2; ++k) \
;         acc[ai][bj][m][n] = __builtin_amdgcn_mfma_f32_16x16x32_bf16(Bt[n][k], At[m][k], acc[ai][bj][m][n], 0, 0, 0); __builtin_amdgcn_s_setprio(0); } while (0)
; #define PG8_WAIT_V(n) asm volatile("s_waitcnt vmcnt(" #n ")" ::: "memory")
; template <class Epi, class Sched, bool ALIGN_EPI, class Hook = NoHook>
; __device__ __forceinline__ void gemm_phase(LAS unsigned char* lds, const Gemm g, const Sched& S, const Epi& E, const Hook& H = Hook()) {
;     ...
;             PG8_LDB(B0, 0, 0); PG8_LDB(B1, 0, 1); PG8_SCHED; PG8_LDA(At, 0, 0); PG8_STAGE(PG8_SA(1, 1), a1 + hA, voffA);
;             PG8_WAIT_V(8); PG8_WAIT_L(0); PG8_BAR; PG8_MMA(0, 0, At, B0); PG8_MMA(0, 1, At, B1); PG8_BAR; PG8_SCHED;
;             PG8_LDA(At, 0, 1); PG8_STAGE(PG8_SB(0, 0), b2, voffB); PG8_STAGE(PG8_SB(0, 1), b2 + hB, voffB); PG8_STAGE(PG8_SA(0, 0), a2, voffA);
;             PG8_WAIT_V(8); PG8_WAIT_L(0); PG8_BAR; PG8_MMA(1, 0, At, B0); PG8_MMA(1, 1, At, B1); PG8_BAR; PG8_SCHED;
;             PG8_LDB(B0, 1, 0); PG8_LDB(B1, 1, 1); PG8_SCHED; PG8_LDA(At, 1, 0); PG8_STAGE(PG8_SA(0, 1), a2 + hA, voffA);
;             PG8_WAIT_V(8); PG8_WAIT_L(0); PG8_BAR; PG8_MMA(0, 0, At, B0); PG8_MMA(0, 1, At, B1); PG8_BAR; PG8_SCHED;
;             PG8_LDA(At, 1, 1); PG8_STAGE(PG8_SB(1, 0), b3, voffB); PG8_STAGE(PG8_SB(1, 1), b3 + hB, voffB); PG8_STAGE(PG8_SA(1, 0), a3, voffA);
;             PG8_WAIT_V(8); PG8_WAIT_L(0); PG8_BAR; PG8_MMA(1, 0, At, B0); PG8_MMA(1, 1, At, B1); PG8_BAR; PG8_SCHED;
	s_setprio 0
	ds_read_b128 v[146:149], v144
	ds_read_b128 v[150:153], v144 offset:1024
	s_add_u32 s22, s22, 0x100000
	s_addc_u32 s23, s23, 0
	s_mov_b32 m0, s38
	ds_read_b128 v[154:157], v144 offset:2048
	global_load_lds_dwordx4 v130, s[22:23]
	ds_read_b128 v[158:161], v144 offset:3072
	ds_read_b128 v[162:165], v145
	ds_read_b128 v[166:169], v145 offset:1024
	ds_read_b128 v[170:173], v145 offset:2048
	ds_read_b128 v[174:177], v145 offset:3072
	ds_read_b128 v[186:189], v143 offset:32768
	s_mov_b32 m0, s39
	ds_read_b128 v[190:193], v143 offset:33792
	global_load_lds_dwordx4 v134, s[22:23]
	ds_read_b128 v[194:197], v143 offset:34816
	ds_read_b128 v[198:201], v143 offset:35840
	ds_read_b128 v[202:205], v143 offset:36864
	ds_read_b128 v[206:209], v143 offset:37888
	ds_read_b128 v[210:213], v143 offset:38912
	ds_read_b128 v[214:217], v143 offset:39936
	s_waitcnt vmcnt(8) lgkmcnt(0)
	s_barrier
	s_setprio 1
	v_mfma_f32_16x16x32_bf16 v[54:57], v[146:149], v[186:189], v[54:57]
	v_mfma_f32_16x16x32_bf16 v[34:37], v[154:157], v[186:189], v[34:37]
	v_mfma_f32_16x16x32_bf16 v[42:45], v[146:149], v[194:197], v[42:45]
	v_mfma_f32_16x16x32_bf16 v[30:33], v[154:157], v[194:197], v[30:33]
	v_mfma_f32_16x16x32_bf16 v[62:65], v[146:149], v[202:205], v[62:65]
	v_mfma_f32_16x16x32_bf16 v[50:53], v[154:157], v[202:205], v[50:53]
	v_mfma_f32_16x16x32_bf16 v[78:81], v[146:149], v[210:213], v[78:81]
	v_mfma_f32_16x16x32_bf16 v[70:73], v[154:157], v[210:213], v[70:73]
	v_mfma_f32_16x16x32_bf16 v[54:57], v[150:153], v[190:193], v[54:57]
	v_mfma_f32_16x16x32_bf16 v[34:37], v[158:161], v[190:193], v[34:37]
	v_mfma_f32_16x16x32_bf16 v[42:45], v[150:153], v[198:201], v[42:45]
	v_mfma_f32_16x16x32_bf16 v[30:33], v[158:161], v[198:201], v[30:33]
	v_mfma_f32_16x16x32_bf16 v[62:65], v[150:153], v[206:209], v[62:65]
	v_mfma_f32_16x16x32_bf16 v[50:53], v[158:161], v[206:209], v[50:53]
	v_mfma_f32_16x16x32_bf16 v[78:81], v[150:153], v[214:217], v[78:81]
	v_mfma_f32_16x16x32_bf16 v[70:73], v[158:161], v[214:217], v[70:73]
	s_setprio 0
	s_setprio 1
	v_mfma_f32_16x16x32_bf16 v[10:13], v[162:165], v[186:189], v[10:13]
	v_mfma_f32_16x16x32_bf16 v[2:5], v[170:173], v[186:189], v[2:5]
	v_mfma_f32_16x16x32_bf16 v[14:17], v[162:165], v[194:197], v[14:17]
	v_mfma_f32_16x16x32_bf16 v[6:9], v[170:173], v[194:197], v[6:9]
	v_mfma_f32_16x16x32_bf16 v[22:25], v[162:165], v[202:205], v[22:25]
	v_mfma_f32_16x16x32_bf16 v[18:21], v[170:173], v[202:205], v[18:21]
	v_mfma_f32_16x16x32_bf16 v[38:41], v[162:165], v[210:213], v[38:41]
	v_mfma_f32_16x16x32_bf16 v[26:29], v[170:173], v[210:213], v[26:29]
	v_mfma_f32_16x16x32_bf16 v[10:13], v[166:169], v[190:193], v[10:13]
	v_mfma_f32_16x16x32_bf16 v[2:5], v[174:177], v[190:193], v[2:5]
	v_mfma_f32_16x16x32_bf16 v[14:17], v[166:169], v[198:201], v[14:17]
	v_mfma_f32_16x16x32_bf16 v[6:9], v[174:177], v[198:201], v[6:9]
	v_mfma_f32_16x16x32_bf16 v[22:25], v[166:169], v[206:209], v[22:25]
	v_mfma_f32_16x16x32_bf16 v[18:21], v[174:177], v[206:209], v[18:21]
	v_mfma_f32_16x16x32_bf16 v[38:41], v[166:169], v[214:217], v[38:41]
	v_mfma_f32_16x16x32_bf16 v[26:29], v[174:177], v[214:217], v[26:29]
	s_barrier
	s_setprio 0
	s_mov_b32 m0, s49
	s_add_u32 s56, s20, s4
	s_addc_u32 s57, s21, s5
	s_add_u32 s20, s20, 0x100080
	ds_read_b128 v[186:189], v143 offset:49152
	ds_read_b128 v[190:193], v143 offset:50176
	global_load_lds_dwordx4 v132, s[56:57]
	ds_read_b128 v[194:197], v143 offset:51200
	s_mov_b32 m0, s50
	s_addc_u32 s21, s21, 0
	global_load_lds_dwordx4 v136, s[56:57]
	ds_read_b128 v[198:201], v143 offset:52224
	s_mov_b32 m0, s51
	ds_read_b128 v[202:205], v143 offset:53248
	global_load_lds_dwordx4 v132, s[20:21]
	s_mov_b32 m0, s52
	ds_read_b128 v[206:209], v143 offset:54272
	global_load_lds_dwordx4 v136, s[20:21]
	s_mov_b32 m0, s40
	ds_read_b128 v[210:213], v143 offset:55296
	global_load_lds_dwordx4 v130, s[58:59]
	s_mov_b32 m0, s41
	s_nop 0
	global_load_lds_dwordx4 v134, s[58:59]
	s_add_i32 s42, s42, 2
	s_add_u32 s6, s6, 0x100
	s_addc_u32 s7, s7, 0
	s_cmp_gt_u32 s42, 61
	ds_read_b128 v[214:217], v143 offset:56320
	s_waitcnt vmcnt(8) lgkmcnt(0)
	s_barrier
	s_setprio 1
	v_mfma_f32_16x16x32_bf16 v[94:97], v[146:149], v[186:189], v[94:97]
	v_mfma_f32_16x16x32_bf16 v[86:89], v[154:157], v[186:189], v[86:89]
	v_mfma_f32_16x16x32_bf16 v[102:105], v[146:149], v[194:197], v[102:105]
	v_mfma_f32_16x16x32_bf16 v[98:101], v[154:157], v[194:197], v[98:101]
	v_mfma_f32_16x16x32_bf16 v[110:113], v[146:149], v[202:205], v[110:113]
	v_mfma_f32_16x16x32_bf16 v[106:109], v[154:157], v[202:205], v[106:109]
	v_mfma_f32_16x16x32_bf16 v[126:129], v[146:149], v[210:213], v[126:129]
	v_mfma_f32_16x16x32_bf16 v[122:125], v[154:157], v[210:213], v[122:125]
	v_mfma_f32_16x16x32_bf16 v[94:97], v[150:153], v[190:193], v[94:97]
	v_mfma_f32_16x16x32_bf16 v[86:89], v[158:161], v[190:193], v[86:89]
	v_mfma_f32_16x16x32_bf16 v[102:105], v[150:153], v[198:201], v[102:105]
	v_mfma_f32_16x16x32_bf16 v[98:101], v[158:161], v[198:201], v[98:101]
	v_mfma_f32_16x16x32_bf16 v[110:113], v[150:153], v[206:209], v[110:113]
	v_mfma_f32_16x16x32_bf16 v[106:109], v[158:161], v[206:209], v[106:109]
	v_mfma_f32_16x16x32_bf16 v[126:129], v[150:153], v[214:217], v[126:129]
	v_mfma_f32_16x16x32_bf16 v[122:125], v[158:161], v[214:217], v[122:125]
	s_setprio 0
	s_setprio 1
	v_mfma_f32_16x16x32_bf16 v[58:61], v[162:165], v[186:189], v[58:61]
	v_mfma_f32_16x16x32_bf16 v[46:49], v[170:173], v[186:189], v[46:49]
	v_mfma_f32_16x16x32_bf16 v[74:77], v[162:165], v[194:197], v[74:77]
	v_mfma_f32_16x16x32_bf16 v[66:69], v[170:173], v[194:197], v[66:69]
	v_mfma_f32_16x16x32_bf16 v[90:93], v[162:165], v[202:205], v[90:93]
	v_mfma_f32_16x16x32_bf16 v[82:85], v[170:173], v[202:205], v[82:85]
	v_mfma_f32_16x16x32_bf16 v[118:121], v[162:165], v[210:213], v[118:121]
	v_mfma_f32_16x16x32_bf16 v[114:117], v[170:173], v[210:213], v[114:117]
	v_mfma_f32_16x16x32_bf16 v[58:61], v[166:169], v[190:193], v[58:61]
	v_mfma_f32_16x16x32_bf16 v[46:49], v[174:177], v[190:193], v[46:49]
	v_mfma_f32_16x16x32_bf16 v[74:77], v[166:169], v[198:201], v[74:77]
	v_mfma_f32_16x16x32_bf16 v[66:69], v[174:177], v[198:201], v[66:69]
	v_mfma_f32_16x16x32_bf16 v[90:93], v[166:169], v[206:209], v[90:93]
	v_mfma_f32_16x16x32_bf16 v[82:85], v[174:177], v[206:209], v[82:85]
	v_mfma_f32_16x16x32_bf16 v[118:121], v[166:169], v[214:217], v[118:121]
	v_mfma_f32_16x16x32_bf16 v[114:117], v[174:177], v[214:217], v[114:117]
	s_barrier
	s_setprio 0
	s_cbranch_scc0 .LBB0_850
	s_cmpk_lt_u32 s26, 0x100
	s_cbranch_scc0 .LBB0_853
	s_barrier

; #define PG8_STAGE(bufoff, gbase, voff) do { _Pragma("unroll") for (int _i = 0; _i < 2; ++_i) \
;         __builtin_amdgcn_global_load_lds((const unsigned*)((const char*)(gbase) + (voff)[_i]), (LAS unsigned*)(lds + (bufoff) + ldsw + _i * 8192), 16, 0, 0); } while (0)
; #define PG8_LDA(dst, b, h) do { _Pragma("unroll") for (int m = 0; m < 4; ++m) _Pragma("unroll") for (int k = 0; k < 2; ++k) dst[m][k] = *(const LAS bf16x8*)(lds + PG8_SA(b, h) + aoff + m * 2048 + k * 1024); } while (0)
; #define PG8_LDB(dst, b, h) do { _Pragma("unroll") for (int n = 0; n < 2; ++n) _Pragma("unroll") for (int k = 0; k < 2; ++k) dst[n][k] = *(const LAS bf16x8*)(lds + PG8_SB(b, h) + boff + n * 2048 + k * 1024); } while (0)
; #define PG8_MMA(ai, bj, At, Bt) do { __builtin_amdgcn_s_setprio(1); _Pragma("unroll") for (int m = 0; m < 4; ++m) _Pragma("unroll") for (int n = 0; n < 2; ++n) _Pragma("unroll") for (int k = 0; k < 2; ++k) \
;         acc[ai][bj][m][n] = __builtin_amdgcn_mfma_f32_16x16x32_bf16(Bt[n][k], At[m][k], acc[ai][bj][m][n], 0, 0, 0); __builtin_amdgcn_s_setprio(0); } while (0)
; #define PG8_WAIT_V(n) asm volatile("s_waitcnt vmcnt(" #n ")" ::: "memory")
; template <class Epi, class Sched, bool ALIGN_EPI, class Hook = NoHook>
; __device__ __forceinline__ void gemm_phase(LAS unsigned char* lds, const Gemm g, const Sched& S, const Epi& E, const Hook& H = Hook()) {
;     ...
;             PG8_LDB(B0, 0, 0); PG8_LDB(B1, 0, 1); PG8_SCHED; PG8_LDA(At, 0, 0); PG8_STAGE(PG8_SA(1, 1), a1 + hA, voffA);
;             PG8_WAIT_V(8); PG8_WAIT_L(0); PG8_BAR; PG8_MMA(0, 0, At, B0); PG8_MMA(0, 1, At, B1); PG8_BAR; PG8_SCHED;
;             PG8_LDA(At, 0, 1); PG8_STAGE(PG8_SB(0, 0), b2, voffB); PG8_STAGE(PG8_SB(0, 1), b2 + hB, voffB); PG8_STAGE(PG8_SA(0, 0), a2, voffA);
;             PG8_WAIT_V(8); PG8_WAIT_L(0); PG8_BAR; PG8_MMA(1, 0, At, B0); PG8_MMA(1, 1, At, B1); PG8_BAR; PG8_SCHED;
;             PG8_LDB(B0, 1, 0); PG8_LDB(B1, 1, 1); PG8_SCHED; PG8_LDA(At, 1, 0); PG8_STAGE(PG8_SA(0, 1), a2 + hA, voffA);
;             PG8_WAIT_V(8); PG8_WAIT_L(0); PG8_BAR; PG8_MMA(0, 0, At, B0); PG8_MMA(0, 1, At, B1); PG8_BAR; PG8_SCHED;
;             PG8_LDA(At, 1, 1); PG8_STAGE(PG8_SB(1, 0), b3, voffB); PG8_STAGE(PG8_SB(1, 1), b3 + hB, voffB); PG8_STAGE(PG8_SA(1, 0), a3, voffA);
;             PG8_WAIT_V(8); PG8_WAIT_L(0); PG8_BAR; PG8_MMA(1, 0, At, B0); PG8_MMA(1, 1, At, B1); PG8_BAR; PG8_SCHED;
.LBB0_896:
	ds_read_b128 v[146:149], v140
	ds_read_b128 v[150:153], v140 offset:1024
	s_add_u32 s10, s6, 0x87c00080
	s_addc_u32 s11, s7, -1
	s_cmp_lg_u32 s18, 60
	s_cselect_b32 s10, s10, 0
	s_cselect_b32 s11, s11, 0
	s_add_u32 s16, s2, s10
	s_addc_u32 s17, s3, s11
	s_add_u32 s10, s14, s10
	s_addc_u32 s11, s15, s11
	s_mov_b32 m0, s19
	ds_read_b128 v[154:157], v140 offset:2048
	ds_read_b128 v[158:161], v140 offset:3072
	ds_read_b128 v[162:165], v141
	ds_read_b128 v[166:169], v141 offset:1024
	ds_read_b128 v[170:173], v141 offset:2048
	ds_read_b128 v[174:177], v141 offset:3072
	v_lshl_add_u64 v[178:179], v[136:137], 0, s[6:7]
	global_load_lds_dwordx4 v[178:179], off
	ds_read_b128 v[186:189], v142
	ds_read_b128 v[190:193], v142 offset:1024
	ds_read_b128 v[194:197], v142 offset:2048
	ds_read_b128 v[198:201], v142 offset:3072
	ds_read_b128 v[202:205], v142 offset:4096
	ds_read_b128 v[206:209], v142 offset:5120
	ds_read_b128 v[210:213], v142 offset:6144
	ds_read_b128 v[214:217], v142 offset:7168
	v_lshl_add_u64 v[178:179], v[138:139], 0, s[6:7]
	s_mov_b32 m0, s31
	s_nop 0
	global_load_lds_dwordx4 v[178:179], off
	s_waitcnt vmcnt(8) lgkmcnt(0)
	s_barrier
	s_setprio 1
	v_mfma_f32_16x16x32_bf16 v[54:57], v[146:149], v[186:189], v[54:57]
	v_mfma_f32_16x16x32_bf16 v[34:37], v[154:157], v[186:189], v[34:37]
	v_mfma_f32_16x16x32_bf16 v[42:45], v[146:149], v[194:197], v[42:45]
	v_mfma_f32_16x16x32_bf16 v[30:33], v[154:157], v[194:197], v[30:33]
	v_mfma_f32_16x16x32_bf16 v[62:65], v[146:149], v[202:205], v[62:65]
	v_mfma_f32_16x16x32_bf16 v[50:53], v[154:157], v[202:205], v[50:53]
	v_mfma_f32_16x16x32_bf16 v[78:81], v[146:149], v[210:213], v[78:81]
	v_mfma_f32_16x16x32_bf16 v[70:73], v[154:157], v[210:213], v[70:73]
	v_mfma_f32_16x16x32_bf16 v[54:57], v[150:153], v[190:193], v[54:57]
	v_mfma_f32_16x16x32_bf16 v[34:37], v[158:161], v[190:193], v[34:37]
	v_mfma_f32_16x16x32_bf16 v[42:45], v[150:153], v[198:201], v[42:45]
	v_mfma_f32_16x16x32_bf16 v[30:33], v[158:161], v[198:201], v[30:33]
	v_mfma_f32_16x16x32_bf16 v[62:65], v[150:153], v[206:209], v[62:65]
	v_mfma_f32_16x16x32_bf16 v[50:53], v[158:161], v[206:209], v[50:53]
	v_mfma_f32_16x16x32_bf16 v[78:81], v[150:153], v[214:217], v[78:81]
	v_mfma_f32_16x16x32_bf16 v[70:73], v[158:161], v[214:217], v[70:73]
	s_setprio 0
	s_setprio 1
	v_mfma_f32_16x16x32_bf16 v[10:13], v[162:165], v[186:189], v[10:13]
	v_mfma_f32_16x16x32_bf16 v[2:5], v[170:173], v[186:189], v[2:5]
	v_mfma_f32_16x16x32_bf16 v[14:17], v[162:165], v[194:197], v[14:17]
	v_mfma_f32_16x16x32_bf16 v[6:9], v[170:173], v[194:197], v[6:9]
	v_mfma_f32_16x16x32_bf16 v[22:25], v[162:165], v[202:205], v[22:25]
	v_mfma_f32_16x16x32_bf16 v[18:21], v[170:173], v[202:205], v[18:21]
	v_mfma_f32_16x16x32_bf16 v[38:41], v[162:165], v[210:213], v[38:41]
	v_mfma_f32_16x16x32_bf16 v[26:29], v[170:173], v[210:213], v[26:29]
	v_mfma_f32_16x16x32_bf16 v[10:13], v[166:169], v[190:193], v[10:13]
	v_mfma_f32_16x16x32_bf16 v[2:5], v[174:177], v[190:193], v[2:5]
	v_mfma_f32_16x16x32_bf16 v[14:17], v[166:169], v[198:201], v[14:17]
	v_mfma_f32_16x16x32_bf16 v[6:9], v[174:177], v[198:201], v[6:9]
	v_mfma_f32_16x16x32_bf16 v[22:25], v[166:169], v[206:209], v[22:25]
	v_mfma_f32_16x16x32_bf16 v[18:21], v[174:177], v[206:209], v[18:21]
	v_mfma_f32_16x16x32_bf16 v[38:41], v[166:169], v[214:217], v[38:41]
	v_mfma_f32_16x16x32_bf16 v[26:29], v[174:177], v[214:217], v[26:29]
	s_barrier
	s_setprio 0
	s_mov_b32 m0, s33
	s_add_u32 s46, s10, 0x100000
	ds_read_b128 v[186:189], v142 offset:16384
	ds_read_b128 v[190:193], v142 offset:17408
	global_load_lds_dwordx4 v180, s[10:11]
	ds_read_b128 v[194:197], v142 offset:18432
	s_mov_b32 m0, s34
	s_addc_u32 s47, s11, 0
	global_load_lds_dwordx4 v134, s[10:11]
	ds_read_b128 v[198:201], v142 offset:19456
	s_mov_b32 m0, s35
	ds_read_b128 v[202:205], v142 offset:20480
	global_load_lds_dwordx4 v180, s[46:47]
	s_mov_b32 m0, s42
	ds_read_b128 v[206:209], v142 offset:21504
	global_load_lds_dwordx4 v134, s[46:47]
	s_add_u32 s50, s16, s4
	s_addc_u32 s51, s17, s5
	s_mov_b32 m0, s27
	ds_read_b128 v[210:213], v142 offset:22528
	global_load_lds_dwordx4 v130, s[16:17]
	s_mov_b32 m0, s28
	ds_read_b128 v[214:217], v142 offset:23552
	global_load_lds_dwordx4 v132, s[16:17]
	s_waitcnt vmcnt(8) lgkmcnt(0)
	s_barrier
	s_setprio 1
	v_mfma_f32_16x16x32_bf16 v[94:97], v[146:149], v[186:189], v[94:97]
	v_mfma_f32_16x16x32_bf16 v[86:89], v[154:157], v[186:189], v[86:89]
	v_mfma_f32_16x16x32_bf16 v[102:105], v[146:149], v[194:197], v[102:105]
	v_mfma_f32_16x16x32_bf16 v[98:101], v[154:157], v[194:197], v[98:101]
	v_mfma_f32_16x16x32_bf16 v[110:113], v[146:149], v[202:205], v[110:113]
	v_mfma_f32_16x16x32_bf16 v[106:109], v[154:157], v[202:205], v[106:109]
	v_mfma_f32_16x16x32_bf16 v[126:129], v[146:149], v[210:213], v[126:129]
	v_mfma_f32_16x16x32_bf16 v[122:125], v[154:157], v[210:213], v[122:125]
	v_mfma_f32_16x16x32_bf16 v[94:97], v[150:153], v[190:193], v[94:97]
	v_mfma_f32_16x16x32_bf16 v[86:89], v[158:161], v[190:193], v[86:89]
	v_mfma_f32_16x16x32_bf16 v[102:105], v[150:153], v[198:201], v[102:105]
	v_mfma_f32_16x16x32_bf16 v[98:101], v[158:161], v[198:201], v[98:101]
	v_mfma_f32_16x16x32_bf16 v[110:113], v[150:153], v[206:209], v[110:113]
	v_mfma_f32_16x16x32_bf16 v[106:109], v[158:161], v[206:209], v[106:109]
	v_mfma_f32_16x16x32_bf16 v[126:129], v[150:153], v[214:217], v[126:129]
	v_mfma_f32_16x16x32_bf16 v[122:125], v[158:161], v[214:217], v[122:125]
	s_setprio 0
	s_setprio 1
	v_mfma_f32_16x16x32_bf16 v[58:61], v[162:165], v[186:189], v[58:61]
	v_mfma_f32_16x16x32_bf16 v[46:49], v[170:173], v[186:189], v[46:49]
	v_mfma_f32_16x16x32_bf16 v[74:77], v[162:165], v[194:197], v[74:77]
	v_mfma_f32_16x16x32_bf16 v[66:69], v[170:173], v[194:197], v[66:69]
	v_mfma_f32_16x16x32_bf16 v[90:93], v[162:165], v[202:205], v[90:93]
	v_mfma_f32_16x16x32_bf16 v[82:85], v[170:173], v[202:205], v[82:85]
	v_mfma_f32_16x16x32_bf16 v[118:121], v[162:165], v[210:213], v[118:121]
	v_mfma_f32_16x16x32_bf16 v[114:117], v[170:173], v[210:213], v[114:117]
	v_mfma_f32_16x16x32_bf16 v[58:61], v[166:169], v[190:193], v[58:61]
	v_mfma_f32_16x16x32_bf16 v[46:49], v[174:177], v[190:193], v[46:49]
	v_mfma_f32_16x16x32_bf16 v[74:77], v[166:169], v[198:201], v[74:77]
	v_mfma_f32_16x16x32_bf16 v[66:69], v[174:177], v[198:201], v[66:69]
	v_mfma_f32_16x16x32_bf16 v[90:93], v[166:169], v[206:209], v[90:93]
	v_mfma_f32_16x16x32_bf16 v[82:85], v[174:177], v[206:209], v[82:85]
	v_mfma_f32_16x16x32_bf16 v[118:121], v[166:169], v[214:217], v[118:121]
	v_mfma_f32_16x16x32_bf16 v[114:117], v[174:177], v[214:217], v[114:117]
	s_barrier
; #define PG8_STAGE(bufoff, gbase, voff) do { _Pragma("unroll") for (int _i = 0; _i < 2; ++_i) \
;         __builtin_amdgcn_global_load_lds((const unsigned*)((const char*)(gbase) + (voff)[_i]), (LAS unsigned*)(lds + (bufoff) + ldsw + _i * 8192), 16, 0, 0); } while (0)
; #define PG8_LDA(dst, b, h) do { _Pragma("unroll") for (int m = 0; m < 4; ++m) _Pragma("unroll") for (int k = 0; k < 2; ++k) dst[m][k] = *(const LAS bf16x8*)(lds + PG8_SA(b, h) + aoff + m * 2048 + k * 1024); } while (0)
; #define PG8_LDB(dst, b, h) do { _Pragma("unroll") for (int n = 0; n < 2; ++n) _Pragma("unroll") for (int k = 0; k < 2; ++k) dst[n][k] = *(const LAS bf16x8*)(lds + PG8_SB(b, h) + boff + n * 2048 + k * 1024); } while (0)
; #define PG8_MMA(ai, bj, At, Bt) do { __builtin_amdgcn_s_setprio(1); _Pragma("unroll") for (int m = 0; m < 4; ++m) _Pragma("unroll") for (int n = 0; n < 2; ++n) _Pragma("unroll") for (int k = 0; k < 2; ++k) \
;         acc[ai][bj][m][n] = __builtin_amdgcn_mfma_f32_16x16x32_bf16(Bt[n][k], At[m][k], acc[ai][bj][m][n], 0, 0, 0); __builtin_amdgcn_s_setprio(0); } while (0)
; #define PG8_WAIT_V(n) asm volatile("s_waitcnt vmcnt(" #n ")" ::: "memory")
; template <class Epi, class Sched, bool ALIGN_EPI, class Hook = NoHook>
; __device__ __forceinline__ void gemm_phase(LAS unsigned char* lds, const Gemm g, const Sched& S, const Epi& E, const Hook& H = Hook()) {
;     ...
;             PG8_LDB(B0, 0, 0); PG8_LDB(B1, 0, 1); PG8_SCHED; PG8_LDA(At, 0, 0); PG8_STAGE(PG8_SA(1, 1), a1 + hA, voffA);
;             PG8_WAIT_V(8); PG8_WAIT_L(0); PG8_BAR; PG8_MMA(0, 0, At, B0); PG8_MMA(0, 1, At, B1); PG8_BAR; PG8_SCHED;
;             PG8_LDA(At, 0, 1); PG8_STAGE(PG8_SB(0, 0), b2, voffB); PG8_STAGE(PG8_SB(0, 1), b2 + hB, voffB); PG8_STAGE(PG8_SA(0, 0), a2, voffA);
;             PG8_WAIT_V(8); PG8_WAIT_L(0); PG8_BAR; PG8_MMA(1, 0, At, B0); PG8_MMA(1, 1, At, B1); PG8_BAR; PG8_SCHED;
;             PG8_LDB(B0, 1, 0); PG8_LDB(B1, 1, 1); PG8_SCHED; PG8_LDA(At, 1, 0); PG8_STAGE(PG8_SA(0, 1), a2 + hA, voffA);
;             PG8_WAIT_V(8); PG8_WAIT_L(0); PG8_BAR; PG8_MMA(0, 0, At, B0); PG8_MMA(0, 1, At, B1); PG8_BAR; PG8_SCHED;
;             PG8_LDA(At, 1, 1); PG8_STAGE(PG8_SB(1, 0), b3, voffB); PG8_STAGE(PG8_SB(1, 1), b3 + hB, voffB); PG8_STAGE(PG8_SA(1, 0), a3, voffA);
;             PG8_WAIT_V(8); PG8_WAIT_L(0); PG8_BAR; PG8_MMA(1, 0, At, B0); PG8_MMA(1, 1, At, B1); PG8_BAR; PG8_SCHED;
	s_setprio 0
	ds_read_b128 v[146:149], v143
	ds_read_b128 v[150:153], v143 offset:1024
	s_add_u32 s16, s16, 0x100000
	s_addc_u32 s17, s17, 0
	s_mov_b32 m0, s29
	ds_read_b128 v[154:157], v143 offset:2048
	global_load_lds_dwordx4 v130, s[16:17]
	ds_read_b128 v[158:161], v143 offset:3072
	ds_read_b128 v[162:165], v144
	ds_read_b128 v[166:169], v144 offset:1024
	ds_read_b128 v[170:173], v144 offset:2048
	ds_read_b128 v[174:177], v144 offset:3072
	ds_read_b128 v[186:189], v142 offset:32768
	s_mov_b32 m0, s39
	ds_read_b128 v[190:193], v142 offset:33792
	global_load_lds_dwordx4 v132, s[16:17]
	ds_read_b128 v[194:197], v142 offset:34816
	ds_read_b128 v[198:201], v142 offset:35840
	ds_read_b128 v[202:205], v142 offset:36864
	ds_read_b128 v[206:209], v142 offset:37888
	ds_read_b128 v[210:213], v142 offset:38912
	ds_read_b128 v[214:217], v142 offset:39936
	s_waitcnt vmcnt(8) lgkmcnt(0)
	s_barrier
	s_setprio 1
	v_mfma_f32_16x16x32_bf16 v[54:57], v[146:149], v[186:189], v[54:57]
	v_mfma_f32_16x16x32_bf16 v[34:37], v[154:157], v[186:189], v[34:37]
	v_mfma_f32_16x16x32_bf16 v[42:45], v[146:149], v[194:197], v[42:45]
	v_mfma_f32_16x16x32_bf16 v[30:33], v[154:157], v[194:197], v[30:33]
	v_mfma_f32_16x16x32_bf16 v[62:65], v[146:149], v[202:205], v[62:65]
	v_mfma_f32_16x16x32_bf16 v[50:53], v[154:157], v[202:205], v[50:53]
	v_mfma_f32_16x16x32_bf16 v[78:81], v[146:149], v[210:213], v[78:81]
	v_mfma_f32_16x16x32_bf16 v[70:73], v[154:157], v[210:213], v[70:73]
	v_mfma_f32_16x16x32_bf16 v[54:57], v[150:153], v[190:193], v[54:57]
	v_mfma_f32_16x16x32_bf16 v[34:37], v[158:161], v[190:193], v[34:37]
	v_mfma_f32_16x16x32_bf16 v[42:45], v[150:153], v[198:201], v[42:45]
	v_mfma_f32_16x16x32_bf16 v[30:33], v[158:161], v[198:201], v[30:33]
	v_mfma_f32_16x16x32_bf16 v[62:65], v[150:153], v[206:209], v[62:65]
	v_mfma_f32_16x16x32_bf16 v[50:53], v[158:161], v[206:209], v[50:53]
	v_mfma_f32_16x16x32_bf16 v[78:81], v[150:153], v[214:217], v[78:81]
	v_mfma_f32_16x16x32_bf16 v[70:73], v[158:161], v[214:217], v[70:73]
	s_setprio 0
	s_setprio 1
	v_mfma_f32_16x16x32_bf16 v[10:13], v[162:165], v[186:189], v[10:13]
	v_mfma_f32_16x16x32_bf16 v[2:5], v[170:173], v[186:189], v[2:5]
	v_mfma_f32_16x16x32_bf16 v[14:17], v[162:165], v[194:197], v[14:17]
	v_mfma_f32_16x16x32_bf16 v[6:9], v[170:173], v[194:197], v[6:9]
	v_mfma_f32_16x16x32_bf16 v[22:25], v[162:165], v[202:205], v[22:25]
	v_mfma_f32_16x16x32_bf16 v[18:21], v[170:173], v[202:205], v[18:21]
	v_mfma_f32_16x16x32_bf16 v[38:41], v[162:165], v[210:213], v[38:41]
	v_mfma_f32_16x16x32_bf16 v[26:29], v[170:173], v[210:213], v[26:29]
	v_mfma_f32_16x16x32_bf16 v[10:13], v[166:169], v[190:193], v[10:13]
	v_mfma_f32_16x16x32_bf16 v[2:5], v[174:177], v[190:193], v[2:5]
	v_mfma_f32_16x16x32_bf16 v[14:17], v[166:169], v[198:201], v[14:17]
	v_mfma_f32_16x16x32_bf16 v[6:9], v[174:177], v[198:201], v[6:9]
	v_mfma_f32_16x16x32_bf16 v[22:25], v[166:169], v[206:209], v[22:25]
	v_mfma_f32_16x16x32_bf16 v[18:21], v[174:177], v[206:209], v[18:21]
	v_mfma_f32_16x16x32_bf16 v[38:41], v[166:169], v[214:217], v[38:41]
	v_mfma_f32_16x16x32_bf16 v[26:29], v[174:177], v[214:217], v[26:29]
	s_barrier
	s_setprio 0
	s_mov_b32 m0, s36
	s_add_u32 s48, s10, s4
	s_addc_u32 s49, s11, s5
	s_add_u32 s10, s10, 0x100080
	ds_read_b128 v[186:189], v142 offset:49152
	ds_read_b128 v[190:193], v142 offset:50176
	global_load_lds_dwordx4 v180, s[48:49]
	ds_read_b128 v[194:197], v142 offset:51200
	s_mov_b32 m0, s43
	s_addc_u32 s11, s11, 0
	global_load_lds_dwordx4 v134, s[48:49]
	ds_read_b128 v[198:201], v142 offset:52224
	s_mov_b32 m0, s37
	ds_read_b128 v[202:205], v142 offset:53248
	global_load_lds_dwordx4 v180, s[10:11]
	s_mov_b32 m0, s44
	ds_read_b128 v[206:209], v142 offset:54272
	global_load_lds_dwordx4 v134, s[10:11]
	s_mov_b32 m0, s40
	ds_read_b128 v[210:213], v142 offset:55296
	global_load_lds_dwordx4 v130, s[50:51]
	s_mov_b32 m0, s41
	s_nop 0
	global_load_lds_dwordx4 v132, s[50:51]
	s_add_i32 s18, s18, 2
	s_add_u32 s6, s6, 0x100
	s_addc_u32 s7, s7, 0
	s_cmp_gt_u32 s18, 61
	ds_read_b128 v[214:217], v142 offset:56320
	s_waitcnt vmcnt(8) lgkmcnt(0)
	s_barrier
	s_setprio 1
	v_mfma_f32_16x16x32_bf16 v[94:97], v[146:149], v[186:189], v[94:97]
	v_mfma_f32_16x16x32_bf16 v[86:89], v[154:157], v[186:189], v[86:89]
	v_mfma_f32_16x16x32_bf16 v[102:105], v[146:149], v[194:197], v[102:105]
	v_mfma_f32_16x16x32_bf16 v[98:101], v[154:157], v[194:197], v[98:101]
	v_mfma_f32_16x16x32_bf16 v[110:113], v[146:149], v[202:205], v[110:113]
	v_mfma_f32_16x16x32_bf16 v[106:109], v[154:157], v[202:205], v[106:109]
	v_mfma_f32_16x16x32_bf16 v[126:129], v[146:149], v[210:213], v[126:129]
	v_mfma_f32_16x16x32_bf16 v[122:125], v[154:157], v[210:213], v[122:125]
	v_mfma_f32_16x16x32_bf16 v[94:97], v[150:153], v[190:193], v[94:97]
	v_mfma_f32_16x16x32_bf16 v[86:89], v[158:161], v[190:193], v[86:89]
	v_mfma_f32_16x16x32_bf16 v[102:105], v[150:153], v[198:201], v[102:105]
	v_mfma_f32_16x16x32_bf16 v[98:101], v[158:161], v[198:201], v[98:101]
	v_mfma_f32_16x16x32_bf16 v[110:113], v[150:153], v[206:209], v[110:113]
	v_mfma_f32_16x16x32_bf16 v[106:109], v[158:161], v[206:209], v[106:109]
	v_mfma_f32_16x16x32_bf16 v[126:129], v[150:153], v[214:217], v[126:129]
	v_mfma_f32_16x16x32_bf16 v[122:125], v[158:161], v[214:217], v[122:125]
	s_setprio 0
	s_setprio 1
	v_mfma_f32_16x16x32_bf16 v[58:61], v[162:165], v[186:189], v[58:61]
	v_mfma_f32_16x16x32_bf16 v[46:49], v[170:173], v[186:189], v[46:49]
	v_mfma_f32_16x16x32_bf16 v[74:77], v[162:165], v[194:197], v[74:77]
	v_mfma_f32_16x16x32_bf16 v[66:69], v[170:173], v[194:197], v[66:69]
	v_mfma_f32_16x16x32_bf16 v[90:93], v[162:165], v[202:205], v[90:93]
	v_mfma_f32_16x16x32_bf16 v[82:85], v[170:173], v[202:205], v[82:85]
	v_mfma_f32_16x16x32_bf16 v[118:121], v[162:165], v[210:213], v[118:121]
	v_mfma_f32_16x16x32_bf16 v[114:117], v[170:173], v[210:213], v[114:117]
	v_mfma_f32_16x16x32_bf16 v[58:61], v[166:169], v[190:193], v[58:61]
	v_mfma_f32_16x16x32_bf16 v[46:49], v[174:177], v[190:193], v[46:49]
	v_mfma_f32_16x16x32_bf16 v[74:77], v[166:169], v[198:201], v[74:77]
	v_mfma_f32_16x16x32_bf16 v[66:69], v[174:177], v[198:201], v[66:69]
	v_mfma_f32_16x16x32_bf16 v[90:93], v[166:169], v[206:209], v[90:93]
	v_mfma_f32_16x16x32_bf16 v[82:85], v[174:177], v[206:209], v[82:85]
	v_mfma_f32_16x16x32_bf16 v[118:121], v[166:169], v[214:217], v[118:121]
	v_mfma_f32_16x16x32_bf16 v[114:117], v[174:177], v[214:217], v[114:117]
	s_barrier
	s_setprio 0
	s_cbranch_scc0 .LBB0_896
	s_cmpk_lt_u32 s22, 0x100
	s_cbranch_scc0 .LBB0_899
	s_barrier

; #define PG8_STAGE(bufoff, gbase, voff) do { _Pragma("unroll") for (int _i = 0; _i < 2; ++_i) \
;         __builtin_amdgcn_global_load_lds((const unsigned*)((const char*)(gbase) + (voff)[_i]), (LAS unsigned*)(lds + (bufoff) + ldsw + _i * 8192), 16, 0, 0); } while (0)
; #define PG8_LDA(dst, b, h) do { _Pragma("unroll") for (int m = 0; m < 4; ++m) _Pragma("unroll") for (int k = 0; k < 2; ++k) dst[m][k] = *(const LAS bf16x8*)(lds + PG8_SA(b, h) + aoff + m * 2048 + k * 1024); } while (0)
; #define PG8_LDB(dst, b, h) do { _Pragma("unroll") for (int n = 0; n < 2; ++n) _Pragma("unroll") for (int k = 0; k < 2; ++k) dst[n][k] = *(const LAS bf16x8*)(lds + PG8_SB(b, h) + boff + n * 2048 + k * 1024); } while (0)
; #define PG8_MMA(ai, bj, At, Bt) do { __builtin_amdgcn_s_setprio(1); _Pragma("unroll") for (int m = 0; m < 4; ++m) _Pragma("unroll") for (int n = 0; n < 2; ++n) _Pragma("unroll") for (int k = 0; k < 2; ++k) \
;         acc[ai][bj][m][n] = __builtin_amdgcn_mfma_f32_16x16x32_bf16(Bt[n][k], At[m][k], acc[ai][bj][m][n], 0, 0, 0); __builtin_amdgcn_s_setprio(0); } while (0)
; #define PG8_WAIT_V(n) asm volatile("s_waitcnt vmcnt(" #n ")" ::: "memory")
; template <class Epi, class Sched, bool ALIGN_EPI, class Hook = NoHook>
; __device__ __forceinline__ void gemm_phase(LAS unsigned char* lds, const Gemm g, const Sched& S, const Epi& E, const Hook& H = Hook()) {
;     ...
;             PG8_LDB(B0, 0, 0); PG8_LDB(B1, 0, 1); PG8_SCHED; PG8_LDA(At, 0, 0); PG8_STAGE(PG8_SA(1, 1), a1 + hA, voffA);
;             PG8_WAIT_V(8); PG8_WAIT_L(0); PG8_BAR; PG8_MMA(0, 0, At, B0); PG8_MMA(0, 1, At, B1); PG8_BAR; PG8_SCHED;
;             PG8_LDA(At, 0, 1); PG8_STAGE(PG8_SB(0, 0), b2, voffB); PG8_STAGE(PG8_SB(0, 1), b2 + hB, voffB); PG8_STAGE(PG8_SA(0, 0), a2, voffA);
;             PG8_WAIT_V(8); PG8_WAIT_L(0); PG8_BAR; PG8_MMA(1, 0, At, B0); PG8_MMA(1, 1, At, B1); PG8_BAR; PG8_SCHED;
;             PG8_LDB(B0, 1, 0); PG8_LDB(B1, 1, 1); PG8_SCHED; PG8_LDA(At, 1, 0); PG8_STAGE(PG8_SA(0, 1), a2 + hA, voffA);
;             PG8_WAIT_V(8); PG8_WAIT_L(0); PG8_BAR; PG8_MMA(0, 0, At, B0); PG8_MMA(0, 1, At, B1); PG8_BAR; PG8_SCHED;
;             PG8_LDA(At, 1, 1); PG8_STAGE(PG8_SB(1, 0), b3, voffB); PG8_STAGE(PG8_SB(1, 1), b3 + hB, voffB); PG8_STAGE(PG8_SA(1, 0), a3, voffA);
;             PG8_WAIT_V(8); PG8_WAIT_L(0); PG8_BAR; PG8_MMA(1, 0, At, B0); PG8_MMA(1, 1, At, B1); PG8_BAR; PG8_SCHED;
.LBB0_1001:
	ds_read_b128 v[106:109], v246
	ds_read_b128 v[110:113], v246 offset:1024
	s_add_u32 s42, s6, 0x100
	s_addc_u32 s43, s7, 0
	s_cmp_eq_u32 s70, 60
	s_cselect_b32 s47, s35, s43
	s_cselect_b32 s46, s66, s42
	s_cselect_b32 s45, s31, s69
	s_cselect_b32 s44, s67, s68
	s_add_i32 m0, s51, 0xc000
	ds_read_b128 v[114:117], v246 offset:2048
	global_load_lds_dwordx4 v236, s[6:7]
	ds_read_b128 v[118:121], v246 offset:3072
	ds_read_b128 v[122:125], v247
	ds_read_b128 v[126:129], v247 offset:1024
	ds_read_b128 v[130:133], v247 offset:2048
	ds_read_b128 v[134:137], v247 offset:3072
	ds_read_b128 v[138:141], v248
	s_add_i32 m0, s51, 0xe000
	ds_read_b128 v[142:145], v248 offset:1024
	global_load_lds_dwordx4 v238, s[6:7]
	ds_read_b128 v[146:149], v248 offset:2048
	ds_read_b128 v[150:153], v248 offset:3072
	ds_read_b128 v[154:157], v248 offset:4096
	ds_read_b128 v[158:161], v248 offset:5120
	ds_read_b128 v[162:165], v248 offset:6144
	ds_read_b128 v[170:173], v248 offset:7168
	s_waitcnt vmcnt(8) lgkmcnt(0)
	s_barrier
	s_setprio 1
	v_mfma_f32_16x16x32_bf16 v[190:193], v[106:109], v[138:141], v[190:193]
	v_mfma_f32_16x16x32_bf16 v[178:181], v[114:117], v[138:141], v[178:181]
	v_mfma_f32_16x16x32_bf16 v[182:185], v[106:109], v[146:149], v[182:185]
	v_mfma_f32_16x16x32_bf16 v[98:101], v[114:117], v[146:149], v[98:101]
	v_mfma_f32_16x16x32_bf16 v[102:105], v[106:109], v[154:157], v[102:105]
	v_mfma_f32_16x16x32_bf16 v[86:89], v[114:117], v[154:157], v[86:89]
	v_mfma_f32_16x16x32_bf16 v[78:81], v[106:109], v[162:165], v[78:81]
	v_mfma_f32_16x16x32_bf16 v[70:73], v[114:117], v[162:165], v[70:73]
	v_mfma_f32_16x16x32_bf16 v[190:193], v[110:113], v[142:145], v[190:193]
	v_mfma_f32_16x16x32_bf16 v[178:181], v[118:121], v[142:145], v[178:181]
	v_mfma_f32_16x16x32_bf16 v[182:185], v[110:113], v[150:153], v[182:185]
	v_mfma_f32_16x16x32_bf16 v[98:101], v[118:121], v[150:153], v[98:101]
	v_mfma_f32_16x16x32_bf16 v[102:105], v[110:113], v[158:161], v[102:105]
	v_mfma_f32_16x16x32_bf16 v[86:89], v[118:121], v[158:161], v[86:89]
	v_mfma_f32_16x16x32_bf16 v[78:81], v[110:113], v[170:173], v[78:81]
	v_mfma_f32_16x16x32_bf16 v[70:73], v[118:121], v[170:173], v[70:73]
	s_setprio 0
	s_setprio 1
	v_mfma_f32_16x16x32_bf16 v[186:189], v[122:125], v[138:141], v[186:189]
	v_mfma_f32_16x16x32_bf16 v[138:141], v[130:133], v[138:141], v[174:177]
	v_mfma_f32_16x16x32_bf16 v[94:97], v[130:133], v[146:149], v[94:97]
	v_mfma_f32_16x16x32_bf16 v[90:93], v[122:125], v[154:157], v[90:93]
	v_mfma_f32_16x16x32_bf16 v[82:85], v[130:133], v[154:157], v[82:85]
	v_mfma_f32_16x16x32_bf16 v[74:77], v[122:125], v[162:165], v[74:77]
	v_mfma_f32_16x16x32_bf16 v[66:69], v[130:133], v[162:165], v[66:69]
	v_mfma_f32_16x16x32_bf16 v[186:189], v[126:129], v[142:145], v[186:189]
	v_mfma_f32_16x16x32_bf16 v[138:141], v[134:137], v[142:145], v[138:141]
	v_mfma_f32_16x16x32_bf16 v[142:145], v[122:125], v[146:149], v[166:169]
	v_mfma_f32_16x16x32_bf16 v[94:97], v[134:137], v[150:153], v[94:97]
	v_mfma_f32_16x16x32_bf16 v[90:93], v[126:129], v[158:161], v[90:93]
	v_mfma_f32_16x16x32_bf16 v[82:85], v[134:137], v[158:161], v[82:85]
	v_mfma_f32_16x16x32_bf16 v[74:77], v[126:129], v[170:173], v[74:77]
	v_mfma_f32_16x16x32_bf16 v[66:69], v[134:137], v[170:173], v[66:69]
	v_mfma_f32_16x16x32_bf16 v[142:145], v[126:129], v[150:153], v[142:145]
	s_barrier
	s_setprio 0
	s_add_i32 s6, s63, s29
	s_mov_b32 m0, s6
	ds_read_b128 v[146:149], v248 offset:16384
	ds_read_b128 v[150:153], v248 offset:17408
	global_load_lds_dwordx4 v232, s[44:45]
	ds_read_b128 v[154:157], v248 offset:18432
	s_add_i32 m0, s6, 0x2000
	s_add_u32 s6, s44, 0x100000
	s_addc_u32 s7, s45, 0
	s_add_i32 s71, s64, s29
	global_load_lds_dwordx4 v228, s[44:45]
	ds_read_b128 v[158:161], v248 offset:19456
	s_mov_b32 m0, s71
	ds_read_b128 v[162:165], v248 offset:20480
	global_load_lds_dwordx4 v232, s[6:7]
	s_add_i32 m0, s71, 0x2000
	ds_read_b128 v[166:169], v248 offset:21504
	global_load_lds_dwordx4 v228, s[6:7]
	s_mov_b32 m0, s51
	ds_read_b128 v[170:173], v248 offset:22528
	global_load_lds_dwordx4 v234, s[46:47]
	s_mov_b32 m0, s52
	ds_read_b128 v[174:177], v248 offset:23552
	global_load_lds_dwordx4 v230, s[46:47]
	s_waitcnt vmcnt(8) lgkmcnt(0)
	s_barrier
	s_setprio 1
	v_mfma_f32_16x16x32_bf16 v[62:65], v[106:109], v[146:149], v[62:65]
	v_mfma_f32_16x16x32_bf16 v[54:57], v[114:117], v[146:149], v[54:57]
	v_mfma_f32_16x16x32_bf16 v[46:49], v[106:109], v[154:157], v[46:49]
	v_mfma_f32_16x16x32_bf16 v[22:25], v[114:117], v[154:157], v[22:25]
	v_mfma_f32_16x16x32_bf16 v[42:45], v[106:109], v[162:165], v[42:45]
	v_mfma_f32_16x16x32_bf16 v[10:13], v[114:117], v[162:165], v[10:13]
	v_mfma_f32_16x16x32_bf16 v[38:41], v[106:109], v[170:173], v[38:41]
	v_mfma_f32_16x16x32_bf16 v[14:17], v[114:117], v[170:173], v[14:17]
	v_mfma_f32_16x16x32_bf16 v[62:65], v[110:113], v[150:153], v[62:65]
	v_mfma_f32_16x16x32_bf16 v[54:57], v[118:121], v[150:153], v[54:57]
	v_mfma_f32_16x16x32_bf16 v[46:49], v[110:113], v[158:161], v[46:49]
	v_mfma_f32_16x16x32_bf16 v[22:25], v[118:121], v[158:161], v[22:25]
	v_mfma_f32_16x16x32_bf16 v[42:45], v[110:113], v[166:169], v[42:45]
	v_mfma_f32_16x16x32_bf16 v[10:13], v[118:121], v[166:169], v[10:13]
	v_mfma_f32_16x16x32_bf16 v[38:41], v[110:113], v[174:177], v[38:41]
	v_mfma_f32_16x16x32_bf16 v[14:17], v[118:121], v[174:177], v[14:17]
	s_setprio 0
	s_setprio 1
	v_mfma_f32_16x16x32_bf16 v[58:61], v[122:125], v[146:149], v[58:61]
	v_mfma_f32_16x16x32_bf16 v[50:53], v[130:133], v[146:149], v[50:53]
	v_mfma_f32_16x16x32_bf16 v[34:37], v[122:125], v[154:157], v[34:37]
	v_mfma_f32_16x16x32_bf16 v[18:21], v[130:133], v[154:157], v[18:21]
	v_mfma_f32_16x16x32_bf16 v[30:33], v[122:125], v[162:165], v[30:33]
	v_mfma_f32_16x16x32_bf16 v[2:5], v[130:133], v[162:165], v[2:5]
	v_mfma_f32_16x16x32_bf16 v[26:29], v[122:125], v[170:173], v[26:29]
	v_mfma_f32_16x16x32_bf16 v[6:9], v[130:133], v[170:173], v[6:9]
	v_mfma_f32_16x16x32_bf16 v[58:61], v[126:129], v[150:153], v[58:61]
	v_mfma_f32_16x16x32_bf16 v[50:53], v[134:137], v[150:153], v[50:53]
	v_mfma_f32_16x16x32_bf16 v[34:37], v[126:129], v[158:161], v[34:37]
	v_mfma_f32_16x16x32_bf16 v[18:21], v[134:137], v[158:161], v[18:21]
	v_mfma_f32_16x16x32_bf16 v[30:33], v[126:129], v[166:169], v[30:33]
	v_mfma_f32_16x16x32_bf16 v[2:5], v[134:137], v[166:169], v[2:5]
	v_mfma_f32_16x16x32_bf16 v[26:29], v[126:129], v[174:177], v[26:29]
	v_mfma_f32_16x16x32_bf16 v[6:9], v[134:137], v[174:177], v[6:9]
	s_barrier
; #define PG8_STAGE(bufoff, gbase, voff) do { _Pragma("unroll") for (int _i = 0; _i < 2; ++_i) \
;         __builtin_amdgcn_global_load_lds((const unsigned*)((const char*)(gbase) + (voff)[_i]), (LAS unsigned*)(lds + (bufoff) + ldsw + _i * 8192), 16, 0, 0); } while (0)
; #define PG8_LDA(dst, b, h) do { _Pragma("unroll") for (int m = 0; m < 4; ++m) _Pragma("unroll") for (int k = 0; k < 2; ++k) dst[m][k] = *(const LAS bf16x8*)(lds + PG8_SA(b, h) + aoff + m * 2048 + k * 1024); } while (0)
; #define PG8_LDB(dst, b, h) do { _Pragma("unroll") for (int n = 0; n < 2; ++n) _Pragma("unroll") for (int k = 0; k < 2; ++k) dst[n][k] = *(const LAS bf16x8*)(lds + PG8_SB(b, h) + boff + n * 2048 + k * 1024); } while (0)
; #define PG8_MMA(ai, bj, At, Bt) do { __builtin_amdgcn_s_setprio(1); _Pragma("unroll") for (int m = 0; m < 4; ++m) _Pragma("unroll") for (int n = 0; n < 2; ++n) _Pragma("unroll") for (int k = 0; k < 2; ++k) \
;         acc[ai][bj][m][n] = __builtin_amdgcn_mfma_f32_16x16x32_bf16(Bt[n][k], At[m][k], acc[ai][bj][m][n], 0, 0, 0); __builtin_amdgcn_s_setprio(0); } while (0)
; #define PG8_WAIT_V(n) asm volatile("s_waitcnt vmcnt(" #n ")" ::: "memory")
; template <class Epi, class Sched, bool ALIGN_EPI, class Hook = NoHook>
; __device__ __forceinline__ void gemm_phase(LAS unsigned char* lds, const Gemm g, const Sched& S, const Epi& E, const Hook& H = Hook()) {
;     ...
;             PG8_LDB(B0, 0, 0); PG8_LDB(B1, 0, 1); PG8_SCHED; PG8_LDA(At, 0, 0); PG8_STAGE(PG8_SA(1, 1), a1 + hA, voffA);
;             PG8_WAIT_V(8); PG8_WAIT_L(0); PG8_BAR; PG8_MMA(0, 0, At, B0); PG8_MMA(0, 1, At, B1); PG8_BAR; PG8_SCHED;
;             PG8_LDA(At, 0, 1); PG8_STAGE(PG8_SB(0, 0), b2, voffB); PG8_STAGE(PG8_SB(0, 1), b2 + hB, voffB); PG8_STAGE(PG8_SA(0, 0), a2, voffA);
;             PG8_WAIT_V(8); PG8_WAIT_L(0); PG8_BAR; PG8_MMA(1, 0, At, B0); PG8_MMA(1, 1, At, B1); PG8_BAR; PG8_SCHED;
;             PG8_LDB(B0, 1, 0); PG8_LDB(B1, 1, 1); PG8_SCHED; PG8_LDA(At, 1, 0); PG8_STAGE(PG8_SA(0, 1), a2 + hA, voffA);
;             PG8_WAIT_V(8); PG8_WAIT_L(0); PG8_BAR; PG8_MMA(0, 0, At, B0); PG8_MMA(0, 1, At, B1); PG8_BAR; PG8_SCHED;
;             PG8_LDA(At, 1, 1); PG8_STAGE(PG8_SB(1, 0), b3, voffB); PG8_STAGE(PG8_SB(1, 1), b3 + hB, voffB); PG8_STAGE(PG8_SA(1, 0), a3, voffA);
;             PG8_WAIT_V(8); PG8_WAIT_L(0); PG8_BAR; PG8_MMA(1, 0, At, B0); PG8_MMA(1, 1, At, B1); PG8_BAR; PG8_SCHED;
	s_setprio 0
	s_add_i32 s71, 0, 0x18000
	s_add_i32 s72, 0, 0x1c000
	v_add_u32_e32 v118, s71, v245
	v_add_u32_e32 v134, s72, v245
	ds_read_b128 v[106:109], v118
	ds_read_b128 v[110:113], v118 offset:1024
	s_add_u32 s6, s46, 0x8000
	s_addc_u32 s7, s47, 0
	s_mov_b32 m0, s53
	ds_read_b128 v[114:117], v118 offset:2048
	global_load_lds_dwordx4 v234, s[6:7]
	ds_read_b128 v[118:121], v118 offset:3072
	ds_read_b128 v[122:125], v134
	ds_read_b128 v[126:129], v134 offset:1024
	ds_read_b128 v[130:133], v134 offset:2048
	ds_read_b128 v[134:137], v134 offset:3072
	ds_read_b128 v[146:149], v248 offset:32768
	s_mov_b32 m0, s54
	ds_read_b128 v[150:153], v248 offset:33792
	global_load_lds_dwordx4 v230, s[6:7]
	ds_read_b128 v[154:157], v248 offset:34816
	ds_read_b128 v[158:161], v248 offset:35840
	ds_read_b128 v[162:165], v248 offset:36864
	ds_read_b128 v[170:173], v248 offset:37888
	ds_read_b128 v[194:197], v248 offset:38912
	ds_read_b128 v[198:201], v248 offset:39936
	s_waitcnt vmcnt(8) lgkmcnt(0)
	s_barrier
	s_setprio 1
	v_mfma_f32_16x16x32_bf16 v[166:169], v[106:109], v[146:149], v[190:193]
	v_mfma_f32_16x16x32_bf16 v[190:193], v[110:113], v[150:153], v[166:169]
	v_mfma_f32_16x16x32_bf16 v[166:169], v[114:117], v[146:149], v[178:181]
	v_mfma_f32_16x16x32_bf16 v[178:181], v[118:121], v[150:153], v[166:169]
	v_mfma_f32_16x16x32_bf16 v[166:169], v[106:109], v[154:157], v[182:185]
	v_mfma_f32_16x16x32_bf16 v[98:101], v[114:117], v[154:157], v[98:101]
	v_mfma_f32_16x16x32_bf16 v[102:105], v[106:109], v[162:165], v[102:105]
	v_mfma_f32_16x16x32_bf16 v[86:89], v[114:117], v[162:165], v[86:89]
	v_mfma_f32_16x16x32_bf16 v[78:81], v[106:109], v[194:197], v[78:81]
	v_mfma_f32_16x16x32_bf16 v[70:73], v[114:117], v[194:197], v[70:73]
	v_mfma_f32_16x16x32_bf16 v[182:185], v[110:113], v[158:161], v[166:169]
	v_mfma_f32_16x16x32_bf16 v[98:101], v[118:121], v[158:161], v[98:101]
	v_mfma_f32_16x16x32_bf16 v[102:105], v[110:113], v[170:173], v[102:105]
	v_mfma_f32_16x16x32_bf16 v[86:89], v[118:121], v[170:173], v[86:89]
	v_mfma_f32_16x16x32_bf16 v[78:81], v[110:113], v[198:201], v[78:81]
	v_mfma_f32_16x16x32_bf16 v[70:73], v[118:121], v[198:201], v[70:73]
	s_setprio 0
	s_setprio 1
	v_mfma_f32_16x16x32_bf16 v[138:141], v[130:133], v[146:149], v[138:141]
	v_mfma_f32_16x16x32_bf16 v[166:169], v[122:125], v[146:149], v[186:189]
	v_mfma_f32_16x16x32_bf16 v[174:177], v[134:137], v[150:153], v[138:141]
	v_mfma_f32_16x16x32_bf16 v[138:141], v[122:125], v[154:157], v[142:145]
	v_mfma_f32_16x16x32_bf16 v[94:97], v[130:133], v[154:157], v[94:97]
	v_mfma_f32_16x16x32_bf16 v[90:93], v[122:125], v[162:165], v[90:93]
	v_mfma_f32_16x16x32_bf16 v[82:85], v[130:133], v[162:165], v[82:85]
	v_mfma_f32_16x16x32_bf16 v[74:77], v[122:125], v[194:197], v[74:77]
	v_mfma_f32_16x16x32_bf16 v[66:69], v[130:133], v[194:197], v[66:69]
	v_mfma_f32_16x16x32_bf16 v[186:189], v[126:129], v[150:153], v[166:169]
	v_mfma_f32_16x16x32_bf16 v[166:169], v[126:129], v[158:161], v[138:141]
	v_mfma_f32_16x16x32_bf16 v[94:97], v[134:137], v[158:161], v[94:97]
	v_mfma_f32_16x16x32_bf16 v[90:93], v[126:129], v[170:173], v[90:93]
	v_mfma_f32_16x16x32_bf16 v[82:85], v[134:137], v[170:173], v[82:85]
	v_mfma_f32_16x16x32_bf16 v[74:77], v[126:129], v[198:201], v[74:77]
	v_mfma_f32_16x16x32_bf16 v[66:69], v[134:137], v[198:201], v[66:69]
	s_barrier
	s_setprio 0
	s_add_i32 s6, s71, s29
	s_add_u32 s74, s44, s14
	s_addc_u32 s75, s45, s15
	s_mov_b32 m0, s6
	ds_read_b128 v[138:141], v248 offset:49152
	ds_read_b128 v[142:145], v248 offset:50176
	global_load_lds_dwordx4 v232, s[74:75]
	ds_read_b128 v[146:149], v248 offset:51200
	s_add_i32 m0, s6, 0x2000
	s_add_u32 s6, s44, 0x100080
	s_addc_u32 s7, s45, 0
	s_add_i32 s44, s72, s29
	global_load_lds_dwordx4 v228, s[74:75]
	ds_read_b128 v[150:153], v248 offset:52224
	s_mov_b32 m0, s44
	ds_read_b128 v[154:157], v248 offset:53248
	global_load_lds_dwordx4 v232, s[6:7]
	s_add_i32 m0, s44, 0x2000
	ds_read_b128 v[158:161], v248 offset:54272
	global_load_lds_dwordx4 v228, s[6:7]
	s_add_u32 s78, s46, s14
	s_addc_u32 s79, s47, s15
	s_mov_b32 m0, s57
	ds_read_b128 v[162:165], v248 offset:55296
	global_load_lds_dwordx4 v234, s[78:79]
	s_mov_b32 m0, s58
	s_nop 0
	global_load_lds_dwordx4 v230, s[78:79]
	s_add_i32 s70, s70, 2
	s_add_u32 s68, s68, 0x100
	s_addc_u32 s69, s69, 0
	s_cmp_gt_u32 s70, 61
	s_mov_b64 s[6:7], s[42:43]
	ds_read_b128 v[170:173], v248 offset:56320
	s_waitcnt vmcnt(8) lgkmcnt(0)
	s_barrier
	s_setprio 1
	v_mfma_f32_16x16x32_bf16 v[62:65], v[106:109], v[138:141], v[62:65]
	v_mfma_f32_16x16x32_bf16 v[54:57], v[114:117], v[138:141], v[54:57]
	v_mfma_f32_16x16x32_bf16 v[46:49], v[106:109], v[146:149], v[46:49]
	v_mfma_f32_16x16x32_bf16 v[22:25], v[114:117], v[146:149], v[22:25]
	v_mfma_f32_16x16x32_bf16 v[42:45], v[106:109], v[154:157], v[42:45]
	v_mfma_f32_16x16x32_bf16 v[10:13], v[114:117], v[154:157], v[10:13]
	v_mfma_f32_16x16x32_bf16 v[38:41], v[106:109], v[162:165], v[38:41]
	v_mfma_f32_16x16x32_bf16 v[14:17], v[114:117], v[162:165], v[14:17]
	v_mfma_f32_16x16x32_bf16 v[62:65], v[110:113], v[142:145], v[62:65]
	v_mfma_f32_16x16x32_bf16 v[54:57], v[118:121], v[142:145], v[54:57]
	v_mfma_f32_16x16x32_bf16 v[46:49], v[110:113], v[150:153], v[46:49]
	v_mfma_f32_16x16x32_bf16 v[22:25], v[118:121], v[150:153], v[22:25]
	v_mfma_f32_16x16x32_bf16 v[42:45], v[110:113], v[158:161], v[42:45]
	v_mfma_f32_16x16x32_bf16 v[10:13], v[118:121], v[158:161], v[10:13]
	v_mfma_f32_16x16x32_bf16 v[38:41], v[110:113], v[170:173], v[38:41]
	v_mfma_f32_16x16x32_bf16 v[14:17], v[118:121], v[170:173], v[14:17]
	s_setprio 0
	s_setprio 1
	v_mfma_f32_16x16x32_bf16 v[58:61], v[122:125], v[138:141], v[58:61]
	v_mfma_f32_16x16x32_bf16 v[50:53], v[130:133], v[138:141], v[50:53]
	v_mfma_f32_16x16x32_bf16 v[34:37], v[122:125], v[146:149], v[34:37]
	v_mfma_f32_16x16x32_bf16 v[18:21], v[130:133], v[146:149], v[18:21]
	v_mfma_f32_16x16x32_bf16 v[30:33], v[122:125], v[154:157], v[30:33]
	v_mfma_f32_16x16x32_bf16 v[2:5], v[130:133], v[154:157], v[2:5]
	v_mfma_f32_16x16x32_bf16 v[26:29], v[122:125], v[162:165], v[26:29]
	v_mfma_f32_16x16x32_bf16 v[6:9], v[130:133], v[162:165], v[6:9]
	v_mfma_f32_16x16x32_bf16 v[58:61], v[126:129], v[142:145], v[58:61]
	v_mfma_f32_16x16x32_bf16 v[50:53], v[134:137], v[142:145], v[50:53]
	v_mfma_f32_16x16x32_bf16 v[34:37], v[126:129], v[150:153], v[34:37]
	v_mfma_f32_16x16x32_bf16 v[18:21], v[134:137], v[150:153], v[18:21]
	v_mfma_f32_16x16x32_bf16 v[30:33], v[126:129], v[158:161], v[30:33]
	v_mfma_f32_16x16x32_bf16 v[2:5], v[134:137], v[158:161], v[2:5]
	v_mfma_f32_16x16x32_bf16 v[26:29], v[126:129], v[170:173], v[26:29]
	v_mfma_f32_16x16x32_bf16 v[6:9], v[134:137], v[170:173], v[6:9]
	s_barrier
	s_setprio 0
	s_cbranch_scc0 .LBB0_1001
	s_and_b64 vcc, exec, s[2:3]
	s_cbranch_vccz .LBB0_1004
	s_barrier

; #define PG8_STAGE(bufoff, gbase, voff) do { _Pragma("unroll") for (int _i = 0; _i < 2; ++_i) \
;         __builtin_amdgcn_global_load_lds((const unsigned*)((const char*)(gbase) + (voff)[_i]), (LAS unsigned*)(lds + (bufoff) + ldsw + _i * 8192), 16, 0, 0); } while (0)
; #define PG8_LDA(dst, b, h) do { _Pragma("unroll") for (int m = 0; m < 4; ++m) _Pragma("unroll") for (int k = 0; k < 2; ++k) dst[m][k] = *(const LAS bf16x8*)(lds + PG8_SA(b, h) + aoff + m * 2048 + k * 1024); } while (0)
; #define PG8_LDB(dst, b, h) do { _Pragma("unroll") for (int n = 0; n < 2; ++n) _Pragma("unroll") for (int k = 0; k < 2; ++k) dst[n][k] = *(const LAS bf16x8*)(lds + PG8_SB(b, h) + boff + n * 2048 + k * 1024); } while (0)
; #define PG8_MMA(ai, bj, At, Bt) do { __builtin_amdgcn_s_setprio(1); _Pragma("unroll") for (int m = 0; m < 4; ++m) _Pragma("unroll") for (int n = 0; n < 2; ++n) _Pragma("unroll") for (int k = 0; k < 2; ++k) \
;         acc[ai][bj][m][n] = __builtin_amdgcn_mfma_f32_16x16x32_bf16(Bt[n][k], At[m][k], acc[ai][bj][m][n], 0, 0, 0); __builtin_amdgcn_s_setprio(0); } while (0)
; #define PG8_WAIT_V(n) asm volatile("s_waitcnt vmcnt(" #n ")" ::: "memory")
; template <class Epi, class Sched, bool ALIGN_EPI, class Hook = NoHook>
; __device__ __forceinline__ void gemm_phase(LAS unsigned char* lds, const Gemm g, const Sched& S, const Epi& E, const Hook& H = Hook()) {
;     ...
;             PG8_LDB(B0, 0, 0); PG8_LDB(B1, 0, 1); PG8_SCHED; PG8_LDA(At, 0, 0); PG8_STAGE(PG8_SA(1, 1), a1 + hA, voffA);
;             PG8_WAIT_V(8); PG8_WAIT_L(0); PG8_BAR; PG8_MMA(0, 0, At, B0); PG8_MMA(0, 1, At, B1); PG8_BAR; PG8_SCHED;
;             PG8_LDA(At, 0, 1); PG8_STAGE(PG8_SB(0, 0), b2, voffB); PG8_STAGE(PG8_SB(0, 1), b2 + hB, voffB); PG8_STAGE(PG8_SA(0, 0), a2, voffA);
;             PG8_WAIT_V(8); PG8_WAIT_L(0); PG8_BAR; PG8_MMA(1, 0, At, B0); PG8_MMA(1, 1, At, B1); PG8_BAR; PG8_SCHED;
;             PG8_LDB(B0, 1, 0); PG8_LDB(B1, 1, 1); PG8_SCHED; PG8_LDA(At, 1, 0); PG8_STAGE(PG8_SA(0, 1), a2 + hA, voffA);
;             PG8_WAIT_V(8); PG8_WAIT_L(0); PG8_BAR; PG8_MMA(0, 0, At, B0); PG8_MMA(0, 1, At, B1); PG8_BAR; PG8_SCHED;
;             PG8_LDA(At, 1, 1); PG8_STAGE(PG8_SB(1, 0), b3, voffB); PG8_STAGE(PG8_SB(1, 1), b3 + hB, voffB); PG8_STAGE(PG8_SA(1, 0), a3, voffA);
;             PG8_WAIT_V(8); PG8_WAIT_L(0); PG8_BAR; PG8_MMA(1, 0, At, B0); PG8_MMA(1, 1, At, B1); PG8_BAR; PG8_SCHED;
.LBB0_1360:
	ds_read_b128 v[146:149], v1
	ds_read_b128 v[150:153], v1 offset:1024
	s_add_u32 s14, s4, 0xbb050080
	s_addc_u32 s15, s5, -1
	s_cmpk_lg_i32 s41, 0xa8
	s_cselect_b32 s14, s14, 0
	s_cselect_b32 s15, s15, 0
	s_add_u32 s20, s0, s14
	s_addc_u32 s21, s1, s15
	s_add_u32 s14, s12, s14
	s_addc_u32 s15, s13, s15
	s_mov_b32 m0, s42
	ds_read_b128 v[154:157], v1 offset:2048
	ds_read_b128 v[158:161], v1 offset:3072
	ds_read_b128 v[164:167], v142
	ds_read_b128 v[170:173], v142 offset:1024
	ds_read_b128 v[174:177], v142 offset:2048
	ds_read_b128 v[178:181], v142 offset:3072
	v_lshl_add_u64 v[214:215], v[138:139], 0, s[4:5]
	global_load_lds_dwordx4 v[214:215], off
	ds_read_b128 v[182:185], v143
	ds_read_b128 v[186:189], v143 offset:1024
	ds_read_b128 v[190:193], v143 offset:2048
	ds_read_b128 v[194:197], v143 offset:3072
	ds_read_b128 v[198:201], v143 offset:4096
	ds_read_b128 v[202:205], v143 offset:5120
	ds_read_b128 v[206:209], v143 offset:6144
	ds_read_b128 v[210:213], v143 offset:7168
	v_lshl_add_u64 v[214:215], v[140:141], 0, s[4:5]
	s_mov_b32 m0, s43
	s_nop 0
	global_load_lds_dwordx4 v[214:215], off
	s_waitcnt vmcnt(8) lgkmcnt(0)
	s_barrier
	s_setprio 1
	v_mfma_f32_16x16x32_bf16 v[82:85], v[146:149], v[182:185], v[82:85]
	v_mfma_f32_16x16x32_bf16 v[54:57], v[154:157], v[182:185], v[54:57]
	v_mfma_f32_16x16x32_bf16 v[58:61], v[146:149], v[190:193], v[58:61]
	v_mfma_f32_16x16x32_bf16 v[42:45], v[154:157], v[190:193], v[42:45]
	v_mfma_f32_16x16x32_bf16 v[70:73], v[146:149], v[198:201], v[70:73]
	v_mfma_f32_16x16x32_bf16 v[50:53], v[154:157], v[198:201], v[50:53]
	v_mfma_f32_16x16x32_bf16 v[86:89], v[146:149], v[206:209], v[86:89]
	v_mfma_f32_16x16x32_bf16 v[74:77], v[154:157], v[206:209], v[74:77]
	v_mfma_f32_16x16x32_bf16 v[82:85], v[150:153], v[186:189], v[82:85]
	v_mfma_f32_16x16x32_bf16 v[54:57], v[158:161], v[186:189], v[54:57]
	v_mfma_f32_16x16x32_bf16 v[58:61], v[150:153], v[194:197], v[58:61]
	v_mfma_f32_16x16x32_bf16 v[42:45], v[158:161], v[194:197], v[42:45]
	v_mfma_f32_16x16x32_bf16 v[70:73], v[150:153], v[202:205], v[70:73]
	v_mfma_f32_16x16x32_bf16 v[50:53], v[158:161], v[202:205], v[50:53]
	v_mfma_f32_16x16x32_bf16 v[86:89], v[150:153], v[210:213], v[86:89]
	v_mfma_f32_16x16x32_bf16 v[74:77], v[158:161], v[210:213], v[74:77]
	s_setprio 0
	s_setprio 1
	v_mfma_f32_16x16x32_bf16 v[14:17], v[164:167], v[182:185], v[14:17]
	v_mfma_f32_16x16x32_bf16 v[2:5], v[174:177], v[182:185], v[2:5]
	v_mfma_f32_16x16x32_bf16 v[18:21], v[164:167], v[190:193], v[18:21]
	v_mfma_f32_16x16x32_bf16 v[6:9], v[174:177], v[190:193], v[6:9]
	v_mfma_f32_16x16x32_bf16 v[22:25], v[164:167], v[198:201], v[22:25]
	v_mfma_f32_16x16x32_bf16 v[10:13], v[174:177], v[198:201], v[10:13]
	v_mfma_f32_16x16x32_bf16 v[30:33], v[164:167], v[206:209], v[30:33]
	v_mfma_f32_16x16x32_bf16 v[26:29], v[174:177], v[206:209], v[26:29]
	v_mfma_f32_16x16x32_bf16 v[14:17], v[170:173], v[186:189], v[14:17]
	v_mfma_f32_16x16x32_bf16 v[2:5], v[178:181], v[186:189], v[2:5]
	v_mfma_f32_16x16x32_bf16 v[18:21], v[170:173], v[194:197], v[18:21]
	v_mfma_f32_16x16x32_bf16 v[6:9], v[178:181], v[194:197], v[6:9]
	v_mfma_f32_16x16x32_bf16 v[22:25], v[170:173], v[202:205], v[22:25]
	v_mfma_f32_16x16x32_bf16 v[10:13], v[178:181], v[202:205], v[10:13]
	v_mfma_f32_16x16x32_bf16 v[30:33], v[170:173], v[210:213], v[30:33]
	v_mfma_f32_16x16x32_bf16 v[26:29], v[178:181], v[210:213], v[26:29]
	s_barrier
	s_setprio 0
	s_mov_b32 m0, s44
	s_add_u32 s52, s14, 0x2b0000
	ds_read_b128 v[182:185], v143 offset:16384
	ds_read_b128 v[186:189], v143 offset:17408
	global_load_lds_dwordx4 v132, s[14:15]
	ds_read_b128 v[190:193], v143 offset:18432
	s_mov_b32 m0, s45
	s_addc_u32 s53, s15, 0
	global_load_lds_dwordx4 v136, s[14:15]
	ds_read_b128 v[194:197], v143 offset:19456
	s_mov_b32 m0, s46
	ds_read_b128 v[198:201], v143 offset:20480
	global_load_lds_dwordx4 v132, s[52:53]
	s_mov_b32 m0, s47
	ds_read_b128 v[202:205], v143 offset:21504
	global_load_lds_dwordx4 v136, s[52:53]
	s_add_u32 s56, s20, s2
	s_addc_u32 s57, s21, s3
	s_mov_b32 m0, s25
	ds_read_b128 v[206:209], v143 offset:22528
	global_load_lds_dwordx4 v130, s[20:21]
	s_mov_b32 m0, s27
	ds_read_b128 v[210:213], v143 offset:23552
	global_load_lds_dwordx4 v134, s[20:21]
	s_waitcnt vmcnt(8) lgkmcnt(0)
	s_barrier
	s_setprio 1
	v_mfma_f32_16x16x32_bf16 v[94:97], v[146:149], v[182:185], v[94:97]
	v_mfma_f32_16x16x32_bf16 v[90:93], v[154:157], v[182:185], v[90:93]
	v_mfma_f32_16x16x32_bf16 v[106:109], v[146:149], v[190:193], v[106:109]
	v_mfma_f32_16x16x32_bf16 v[98:101], v[154:157], v[190:193], v[98:101]
	v_mfma_f32_16x16x32_bf16 v[110:113], v[146:149], v[198:201], v[110:113]
	v_mfma_f32_16x16x32_bf16 v[102:105], v[154:157], v[198:201], v[102:105]
	v_mfma_f32_16x16x32_bf16 v[126:129], v[146:149], v[206:209], v[126:129]
	v_mfma_f32_16x16x32_bf16 v[122:125], v[154:157], v[206:209], v[122:125]
	v_mfma_f32_16x16x32_bf16 v[94:97], v[150:153], v[186:189], v[94:97]
	v_mfma_f32_16x16x32_bf16 v[90:93], v[158:161], v[186:189], v[90:93]
	v_mfma_f32_16x16x32_bf16 v[106:109], v[150:153], v[194:197], v[106:109]
	v_mfma_f32_16x16x32_bf16 v[98:101], v[158:161], v[194:197], v[98:101]
	v_mfma_f32_16x16x32_bf16 v[110:113], v[150:153], v[202:205], v[110:113]
	v_mfma_f32_16x16x32_bf16 v[102:105], v[158:161], v[202:205], v[102:105]
	v_mfma_f32_16x16x32_bf16 v[126:129], v[150:153], v[210:213], v[126:129]
	v_mfma_f32_16x16x32_bf16 v[122:125], v[158:161], v[210:213], v[122:125]
	s_setprio 0
	s_setprio 1
	v_mfma_f32_16x16x32_bf16 v[38:41], v[164:167], v[182:185], v[38:41]
	v_mfma_f32_16x16x32_bf16 v[34:37], v[174:177], v[182:185], v[34:37]
	v_mfma_f32_16x16x32_bf16 v[66:69], v[164:167], v[190:193], v[66:69]
	v_mfma_f32_16x16x32_bf16 v[46:49], v[174:177], v[190:193], v[46:49]
	v_mfma_f32_16x16x32_bf16 v[78:81], v[164:167], v[198:201], v[78:81]
	v_mfma_f32_16x16x32_bf16 v[62:65], v[174:177], v[198:201], v[62:65]
	v_mfma_f32_16x16x32_bf16 v[118:121], v[164:167], v[206:209], v[118:121]
	v_mfma_f32_16x16x32_bf16 v[114:117], v[174:177], v[206:209], v[114:117]
	v_mfma_f32_16x16x32_bf16 v[38:41], v[170:173], v[186:189], v[38:41]
	v_mfma_f32_16x16x32_bf16 v[34:37], v[178:181], v[186:189], v[34:37]
	v_mfma_f32_16x16x32_bf16 v[66:69], v[170:173], v[194:197], v[66:69]
	v_mfma_f32_16x16x32_bf16 v[46:49], v[178:181], v[194:197], v[46:49]
	v_mfma_f32_16x16x32_bf16 v[78:81], v[170:173], v[202:205], v[78:81]
	v_mfma_f32_16x16x32_bf16 v[62:65], v[178:181], v[202:205], v[62:65]
	v_mfma_f32_16x16x32_bf16 v[118:121], v[170:173], v[210:213], v[118:121]
	v_mfma_f32_16x16x32_bf16 v[114:117], v[178:181], v[210:213], v[114:117]
	s_barrier
; #define PG8_STAGE(bufoff, gbase, voff) do { _Pragma("unroll") for (int _i = 0; _i < 2; ++_i) \
;         __builtin_amdgcn_global_load_lds((const unsigned*)((const char*)(gbase) + (voff)[_i]), (LAS unsigned*)(lds + (bufoff) + ldsw + _i * 8192), 16, 0, 0); } while (0)
; #define PG8_WAIT_V(n) asm volatile("s_waitcnt vmcnt(" #n ")" ::: "memory")
; #define PG8_WAIT_L(n) asm volatile("s_waitcnt lgkmcnt(" #n ")" ::: "memory")
; #define PG8_BAR __builtin_amdgcn_s_barrier()
; template <class Epi, class Sched, bool ALIGN_EPI, class Hook = NoHook>
; __device__ __forceinline__ void gemm_phase(LAS unsigned char* lds, const Gemm g, const Sched& S, const Epi& E, const Hook& H = Hook()) {
;     ...
;         for (int t = tb; t < te; t += 2) {
;             const bool last = (t == nt - 2);
;             const char* a1 = cA + (size_t)(t + 1) * kstep;
;             const char* a2 = last ? nA : cA + (size_t)(t + 2) * kstep; const char* b2 = last ? nB : cB + (size_t)(t + 2) * kstep;
;             const char* a3 = a2 + kstep; const char* b3 = b2 + kstep;
;             if (last && has_next) S.a_ready(nxt);
;             PG8_LDB(B0, 0, 0); PG8_LDB(B1, 0, 1); PG8_SCHED; PG8_LDA(At, 0, 0); PG8_STAGE(PG8_SA(1, 1), a1 + hA, voffA);
;             PG8_WAIT_V(8); PG8_WAIT_L(0); PG8_BAR; PG8_MMA(0, 0, At, B0); PG8_MMA(0, 1, At, B1); PG8_BAR; PG8_SCHED;
;             PG8_LDA(At, 0, 1); PG8_STAGE(PG8_SB(0, 0), b2, voffB); PG8_STAGE(PG8_SB(0, 1), b2 + hB, voffB); PG8_STAGE(PG8_SA(0, 0), a2, voffA);
;             PG8_WAIT_V(8); PG8_WAIT_L(0); PG8_BAR; PG8_MMA(1, 0, At, B0); PG8_MMA(1, 1, At, B1); PG8_BAR; PG8_SCHED;
;             PG8_LDB(B0, 1, 0); PG8_LDB(B1, 1, 1); PG8_SCHED; PG8_LDA(At, 1, 0); PG8_STAGE(PG8_SA(0, 1), a2 + hA, voffA);
;             PG8_WAIT_V(8); PG8_WAIT_L(0); PG8_BAR; PG8_MMA(0, 0, At, B0); PG8_MMA(0, 1, At, B1); PG8_BAR; PG8_SCHED;
;             PG8_LDA(At, 1, 1); PG8_STAGE(PG8_SB(1, 0), b3, voffB); PG8_STAGE(PG8_SB(1, 1), b3 + hB, voffB); PG8_STAGE(PG8_SA(1, 0), a3, voffA);
;             PG8_WAIT_V(8); PG8_WAIT_L(0); PG8_BAR; PG8_MMA(1, 0, At, B0); PG8_MMA(1, 1, At, B1); PG8_BAR; PG8_SCHED;
;         }
;         if constexpr (Hook::ON) H.after(te, acc, cur, wr, wc, fr, fq);
;         }
;         if constexpr (ALIGN_EPI) { if (wr == 0) PG8_BAR; }
;         if constexpr (!Epi::AFTER_DRAIN) { E(acc, cur, wr, wc, fr, fq); S.done(cur); }
;         if (!has_next) break;
	s_setprio 0
	ds_read_b128 v[146:149], v144
	ds_read_b128 v[150:153], v144 offset:1024
	s_add_u32 s20, s20, 0x2b0000
	s_addc_u32 s21, s21, 0
	s_mov_b32 m0, s28
	ds_read_b128 v[154:157], v144 offset:2048
	global_load_lds_dwordx4 v130, s[20:21]
	ds_read_b128 v[158:161], v144 offset:3072
	ds_read_b128 v[164:167], v145
	ds_read_b128 v[170:173], v145 offset:1024
	ds_read_b128 v[174:177], v145 offset:2048
	ds_read_b128 v[178:181], v145 offset:3072
	ds_read_b128 v[182:185], v143 offset:32768
	s_mov_b32 m0, s38
	ds_read_b128 v[186:189], v143 offset:33792
	global_load_lds_dwordx4 v134, s[20:21]
	ds_read_b128 v[190:193], v143 offset:34816
	ds_read_b128 v[194:197], v143 offset:35840
	ds_read_b128 v[198:201], v143 offset:36864
	ds_read_b128 v[202:205], v143 offset:37888
	ds_read_b128 v[206:209], v143 offset:38912
	ds_read_b128 v[210:213], v143 offset:39936
	s_waitcnt vmcnt(8) lgkmcnt(0)
	s_barrier
	s_setprio 1
	v_mfma_f32_16x16x32_bf16 v[82:85], v[146:149], v[182:185], v[82:85]
	v_mfma_f32_16x16x32_bf16 v[54:57], v[154:157], v[182:185], v[54:57]
	v_mfma_f32_16x16x32_bf16 v[58:61], v[146:149], v[190:193], v[58:61]
	v_mfma_f32_16x16x32_bf16 v[42:45], v[154:157], v[190:193], v[42:45]
	v_mfma_f32_16x16x32_bf16 v[70:73], v[146:149], v[198:201], v[70:73]
	v_mfma_f32_16x16x32_bf16 v[50:53], v[154:157], v[198:201], v[50:53]
	v_mfma_f32_16x16x32_bf16 v[86:89], v[146:149], v[206:209], v[86:89]
	v_mfma_f32_16x16x32_bf16 v[74:77], v[154:157], v[206:209], v[74:77]
	v_mfma_f32_16x16x32_bf16 v[82:85], v[150:153], v[186:189], v[82:85]
	v_mfma_f32_16x16x32_bf16 v[54:57], v[158:161], v[186:189], v[54:57]
	v_mfma_f32_16x16x32_bf16 v[58:61], v[150:153], v[194:197], v[58:61]
	v_mfma_f32_16x16x32_bf16 v[42:45], v[158:161], v[194:197], v[42:45]
	v_mfma_f32_16x16x32_bf16 v[70:73], v[150:153], v[202:205], v[70:73]
	v_mfma_f32_16x16x32_bf16 v[50:53], v[158:161], v[202:205], v[50:53]
	v_mfma_f32_16x16x32_bf16 v[86:89], v[150:153], v[210:213], v[86:89]
	v_mfma_f32_16x16x32_bf16 v[74:77], v[158:161], v[210:213], v[74:77]
	s_setprio 0
	s_setprio 1
	v_mfma_f32_16x16x32_bf16 v[14:17], v[164:167], v[182:185], v[14:17]
	v_mfma_f32_16x16x32_bf16 v[2:5], v[174:177], v[182:185], v[2:5]
	v_mfma_f32_16x16x32_bf16 v[18:21], v[164:167], v[190:193], v[18:21]
	v_mfma_f32_16x16x32_bf16 v[6:9], v[174:177], v[190:193], v[6:9]
	v_mfma_f32_16x16x32_bf16 v[22:25], v[164:167], v[198:201], v[22:25]
	v_mfma_f32_16x16x32_bf16 v[10:13], v[174:177], v[198:201], v[10:13]
	v_mfma_f32_16x16x32_bf16 v[30:33], v[164:167], v[206:209], v[30:33]
	v_mfma_f32_16x16x32_bf16 v[26:29], v[174:177], v[206:209], v[26:29]
	v_mfma_f32_16x16x32_bf16 v[14:17], v[170:173], v[186:189], v[14:17]
	v_mfma_f32_16x16x32_bf16 v[2:5], v[178:181], v[186:189], v[2:5]
	v_mfma_f32_16x16x32_bf16 v[18:21], v[170:173], v[194:197], v[18:21]
	v_mfma_f32_16x16x32_bf16 v[6:9], v[178:181], v[194:197], v[6:9]
	v_mfma_f32_16x16x32_bf16 v[22:25], v[170:173], v[202:205], v[22:25]
	v_mfma_f32_16x16x32_bf16 v[10:13], v[178:181], v[202:205], v[10:13]
	v_mfma_f32_16x16x32_bf16 v[30:33], v[170:173], v[210:213], v[30:33]
	v_mfma_f32_16x16x32_bf16 v[26:29], v[178:181], v[210:213], v[26:29]
	s_barrier
	s_setprio 0
	s_mov_b32 m0, s48
	s_add_u32 s54, s14, s2
	s_addc_u32 s55, s15, s3
	s_add_u32 s14, s14, 0x2b0080
	ds_read_b128 v[182:185], v143 offset:49152
	ds_read_b128 v[186:189], v143 offset:50176
	global_load_lds_dwordx4 v132, s[54:55]
	ds_read_b128 v[190:193], v143 offset:51200
	s_mov_b32 m0, s49
	s_addc_u32 s15, s15, 0
	global_load_lds_dwordx4 v136, s[54:55]
	ds_read_b128 v[194:197], v143 offset:52224
	s_mov_b32 m0, s50
	ds_read_b128 v[198:201], v143 offset:53248
	global_load_lds_dwordx4 v132, s[14:15]
	s_mov_b32 m0, s51
	ds_read_b128 v[202:205], v143 offset:54272
	global_load_lds_dwordx4 v136, s[14:15]
	s_mov_b32 m0, s39
	ds_read_b128 v[206:209], v143 offset:55296
	global_load_lds_dwordx4 v130, s[56:57]
	s_mov_b32 m0, s40
	s_nop 0
	global_load_lds_dwordx4 v134, s[56:57]
	s_add_i32 s41, s41, 2
	s_add_u32 s4, s4, 0x100
	s_addc_u32 s5, s5, 0
	s_cmpk_gt_u32 s41, 0xa9
	ds_read_b128 v[210:213], v143 offset:56320
	s_waitcnt vmcnt(8) lgkmcnt(0)
	s_barrier
	s_setprio 1
	v_mfma_f32_16x16x32_bf16 v[94:97], v[146:149], v[182:185], v[94:97]
	v_mfma_f32_16x16x32_bf16 v[90:93], v[154:157], v[182:185], v[90:93]
	v_mfma_f32_16x16x32_bf16 v[106:109], v[146:149], v[190:193], v[106:109]
	v_mfma_f32_16x16x32_bf16 v[98:101], v[154:157], v[190:193], v[98:101]
	v_mfma_f32_16x16x32_bf16 v[110:113], v[146:149], v[198:201], v[110:113]
	v_mfma_f32_16x16x32_bf16 v[102:105], v[154:157], v[198:201], v[102:105]
	v_mfma_f32_16x16x32_bf16 v[126:129], v[146:149], v[206:209], v[126:129]
	v_mfma_f32_16x16x32_bf16 v[122:125], v[154:157], v[206:209], v[122:125]
	v_mfma_f32_16x16x32_bf16 v[94:97], v[150:153], v[186:189], v[94:97]
	v_mfma_f32_16x16x32_bf16 v[90:93], v[158:161], v[186:189], v[90:93]
	v_mfma_f32_16x16x32_bf16 v[106:109], v[150:153], v[194:197], v[106:109]
	v_mfma_f32_16x16x32_bf16 v[98:101], v[158:161], v[194:197], v[98:101]
	v_mfma_f32_16x16x32_bf16 v[110:113], v[150:153], v[202:205], v[110:113]
	v_mfma_f32_16x16x32_bf16 v[102:105], v[158:161], v[202:205], v[102:105]
	v_mfma_f32_16x16x32_bf16 v[126:129], v[150:153], v[210:213], v[126:129]
	v_mfma_f32_16x16x32_bf16 v[122:125], v[158:161], v[210:213], v[122:125]
	s_setprio 0
	s_setprio 1
	v_mfma_f32_16x16x32_bf16 v[38:41], v[164:167], v[182:185], v[38:41]
	v_mfma_f32_16x16x32_bf16 v[34:37], v[174:177], v[182:185], v[34:37]
	v_mfma_f32_16x16x32_bf16 v[66:69], v[164:167], v[190:193], v[66:69]
	v_mfma_f32_16x16x32_bf16 v[46:49], v[174:177], v[190:193], v[46:49]
	v_mfma_f32_16x16x32_bf16 v[78:81], v[164:167], v[198:201], v[78:81]
	v_mfma_f32_16x16x32_bf16 v[62:65], v[174:177], v[198:201], v[62:65]
	v_mfma_f32_16x16x32_bf16 v[118:121], v[164:167], v[206:209], v[118:121]
	v_mfma_f32_16x16x32_bf16 v[114:117], v[174:177], v[206:209], v[114:117]
	v_mfma_f32_16x16x32_bf16 v[38:41], v[170:173], v[186:189], v[38:41]
	v_mfma_f32_16x16x32_bf16 v[34:37], v[178:181], v[186:189], v[34:37]
	v_mfma_f32_16x16x32_bf16 v[66:69], v[170:173], v[194:197], v[66:69]
	v_mfma_f32_16x16x32_bf16 v[46:49], v[178:181], v[194:197], v[46:49]
	v_mfma_f32_16x16x32_bf16 v[78:81], v[170:173], v[202:205], v[78:81]
	v_mfma_f32_16x16x32_bf16 v[62:65], v[178:181], v[202:205], v[62:65]
	v_mfma_f32_16x16x32_bf16 v[118:121], v[170:173], v[210:213], v[118:121]
	v_mfma_f32_16x16x32_bf16 v[114:117], v[178:181], v[210:213], v[114:117]
	s_barrier
	s_setprio 0
	s_cbranch_scc0 .LBB0_1360
	s_cmpk_lt_u32 s26, 0x100
	s_cbranch_scc0 .LBB0_1363
	s_barrier

;     __host__ __device__ bool next(int i, Unit& u) const { const bool ok = StaticOrder::next(i >> 1, u); if (i & 1) { u.ka = D_INNER; u.nkt = D_ATT / BK; } else { u.ka = 0; u.nkt = D_INNER / BK; } return ok; }
;     __host__ __device__ bool next(int i, Unit& u) const { const long L = (long)i * G + c; if (L >= (long)nM * nS) return false; u.pm = (int)(L % nM); u.pn = 0; u.ka = (int)(L / nM) * kslab; u.nkt = kslab / BK; return true; }
;     __host__ __device__ bool next(int i, Unit& u) const { if (i > 0) return false; const int x = c & 7, j = c >> 3; u.pm = 16 * s + 4 * (x >> 1) + (j & 3); u.pn = 8 * (x & 1) + (j >> 2); u.ka = 0; u.nkt = nkt; return true; }
; #define PG8_WAIT_V(n) asm volatile("s_waitcnt vmcnt(" #n ")" ::: "memory")
; #define PG8_WAIT_L(n) asm volatile("s_waitcnt lgkmcnt(" #n ")" ::: "memory")
; template <class Epi, class Sched, bool ALIGN_EPI, class Hook = NoHook>
; __device__ __forceinline__ void gemm_phase(LAS unsigned char* lds, const Gemm g, const Sched& S, const Epi& E, const Hook& H = Hook()) {
;     ...
;         const bool has_next = S.next(ui + 1, nxt);
;         const char* nA = has_next ? (const char*)g.A + (size_t)nxt.pm * tA + (size_t)nxt.ka * 2 : cA; const char* nB = has_next ? (const char*)g.Bt + (size_t)nxt.pn * 2 * hB + (size_t)nxt.ka * 2 : cB;
;         const int nt = cur.nkt;
;         for (int tb = 0; tb < nt; tb += (Hook::ON ? Hook::SEG : nt)) {
;         const int te = Hook::ON ? tb + Hook::SEG : nt;
;         for (int t = tb; t < te; t += 2) {
;             const bool last = (t == nt - 2);
;             const char* a1 = cA + (size_t)(t + 1) * kstep;
;             const char* a2 = last ? nA : cA + (size_t)(t + 2) * kstep; const char* b2 = last ? nB : cB + (size_t)(t + 2) * kstep;
;             const char* a3 = a2 + kstep; const char* b3 = b2 + kstep;
;             if (last && has_next) S.a_ready(nxt);
;             PG8_LDB(B0, 0, 0); PG8_LDB(B1, 0, 1); PG8_SCHED; PG8_LDA(At, 0, 0); PG8_STAGE(PG8_SA(1, 1), a1 + hA, voffA);
;             PG8_WAIT_V(8); PG8_WAIT_L(0); PG8_BAR; PG8_MMA(0, 0, At, B0); PG8_MMA(0, 1, At, B1); PG8_BAR; PG8_SCHED;
;             PG8_LDA(At, 0, 1); PG8_STAGE(PG8_SB(0, 0), b2, voffB); PG8_STAGE(PG8_SB(0, 1), b2 + hB, voffB); PG8_STAGE(PG8_SA(0, 0), a2, voffA);
;             PG8_WAIT_V(8); PG8_WAIT_L(0); PG8_BAR; PG8_MMA(1, 0, At, B0); PG8_MMA(1, 1, At, B1); PG8_BAR; PG8_SCHED;
.LBB0_1406:
	ds_read_b128 v[146:149], v140
	ds_read_b128 v[150:153], v140 offset:1024
	s_add_u32 s10, s4, 0xbb050080
	s_addc_u32 s11, s5, -1
	s_cmpk_lg_i32 s18, 0xa8
	s_cselect_b32 s10, s10, 0
	s_cselect_b32 s11, s11, 0
	s_add_u32 s16, s0, s10
	s_addc_u32 s17, s1, s11
	s_add_u32 s10, s12, s10
	s_addc_u32 s11, s13, s11
	s_mov_b32 m0, s19
	ds_read_b128 v[154:157], v140 offset:2048
	ds_read_b128 v[158:161], v140 offset:3072
	ds_read_b128 v[170:173], v141
	ds_read_b128 v[174:177], v141 offset:1024
	ds_read_b128 v[178:181], v141 offset:2048
	ds_read_b128 v[182:185], v141 offset:3072
	v_lshl_add_u64 v[218:219], v[136:137], 0, s[4:5]
	global_load_lds_dwordx4 v[218:219], off
	ds_read_b128 v[186:189], v142
	ds_read_b128 v[190:193], v142 offset:1024
	ds_read_b128 v[194:197], v142 offset:2048
	ds_read_b128 v[198:201], v142 offset:3072
	ds_read_b128 v[202:205], v142 offset:4096
	ds_read_b128 v[206:209], v142 offset:5120
	ds_read_b128 v[210:213], v142 offset:6144
	ds_read_b128 v[214:217], v142 offset:7168
	v_lshl_add_u64 v[218:219], v[138:139], 0, s[4:5]
	s_mov_b32 m0, s31
	s_nop 0
	global_load_lds_dwordx4 v[218:219], off
	s_waitcnt vmcnt(8) lgkmcnt(0)
	s_barrier
	s_setprio 1
	v_mfma_f32_16x16x32_bf16 v[82:85], v[146:149], v[186:189], v[82:85]
	v_mfma_f32_16x16x32_bf16 v[54:57], v[154:157], v[186:189], v[54:57]
	v_mfma_f32_16x16x32_bf16 v[58:61], v[146:149], v[194:197], v[58:61]
	v_mfma_f32_16x16x32_bf16 v[42:45], v[154:157], v[194:197], v[42:45]
	v_mfma_f32_16x16x32_bf16 v[70:73], v[146:149], v[202:205], v[70:73]
	v_mfma_f32_16x16x32_bf16 v[50:53], v[154:157], v[202:205], v[50:53]
	v_mfma_f32_16x16x32_bf16 v[86:89], v[146:149], v[210:213], v[86:89]
	v_mfma_f32_16x16x32_bf16 v[74:77], v[154:157], v[210:213], v[74:77]
	v_mfma_f32_16x16x32_bf16 v[82:85], v[150:153], v[190:193], v[82:85]
	v_mfma_f32_16x16x32_bf16 v[54:57], v[158:161], v[190:193], v[54:57]
	v_mfma_f32_16x16x32_bf16 v[58:61], v[150:153], v[198:201], v[58:61]
	v_mfma_f32_16x16x32_bf16 v[42:45], v[158:161], v[198:201], v[42:45]
	v_mfma_f32_16x16x32_bf16 v[70:73], v[150:153], v[206:209], v[70:73]
	v_mfma_f32_16x16x32_bf16 v[50:53], v[158:161], v[206:209], v[50:53]
	v_mfma_f32_16x16x32_bf16 v[86:89], v[150:153], v[214:217], v[86:89]
	v_mfma_f32_16x16x32_bf16 v[74:77], v[158:161], v[214:217], v[74:77]
	s_setprio 0
	s_setprio 1
	v_mfma_f32_16x16x32_bf16 v[14:17], v[170:173], v[186:189], v[14:17]
	v_mfma_f32_16x16x32_bf16 v[2:5], v[178:181], v[186:189], v[2:5]
	v_mfma_f32_16x16x32_bf16 v[18:21], v[170:173], v[194:197], v[18:21]
	v_mfma_f32_16x16x32_bf16 v[6:9], v[178:181], v[194:197], v[6:9]
	v_mfma_f32_16x16x32_bf16 v[22:25], v[170:173], v[202:205], v[22:25]
	v_mfma_f32_16x16x32_bf16 v[10:13], v[178:181], v[202:205], v[10:13]
	v_mfma_f32_16x16x32_bf16 v[30:33], v[170:173], v[210:213], v[30:33]
	v_mfma_f32_16x16x32_bf16 v[26:29], v[178:181], v[210:213], v[26:29]
	v_mfma_f32_16x16x32_bf16 v[14:17], v[174:177], v[190:193], v[14:17]
	v_mfma_f32_16x16x32_bf16 v[2:5], v[182:185], v[190:193], v[2:5]
	v_mfma_f32_16x16x32_bf16 v[18:21], v[174:177], v[198:201], v[18:21]
	v_mfma_f32_16x16x32_bf16 v[6:9], v[182:185], v[198:201], v[6:9]
	v_mfma_f32_16x16x32_bf16 v[22:25], v[174:177], v[206:209], v[22:25]
	v_mfma_f32_16x16x32_bf16 v[10:13], v[182:185], v[206:209], v[10:13]
	v_mfma_f32_16x16x32_bf16 v[30:33], v[174:177], v[214:217], v[30:33]
	v_mfma_f32_16x16x32_bf16 v[26:29], v[182:185], v[214:217], v[26:29]
	s_barrier
	s_setprio 0
	s_mov_b32 m0, s33
	s_add_u32 s46, s10, 0x2b0000
	ds_read_b128 v[186:189], v142 offset:16384
	ds_read_b128 v[190:193], v142 offset:17408
	global_load_lds_dwordx4 v162, s[10:11]
	ds_read_b128 v[194:197], v142 offset:18432
	s_mov_b32 m0, s34
	s_addc_u32 s47, s11, 0
	global_load_lds_dwordx4 v134, s[10:11]
	ds_read_b128 v[198:201], v142 offset:19456
	s_mov_b32 m0, s35
	ds_read_b128 v[202:205], v142 offset:20480
	global_load_lds_dwordx4 v162, s[46:47]
	s_mov_b32 m0, s43
	ds_read_b128 v[206:209], v142 offset:21504
	global_load_lds_dwordx4 v134, s[46:47]
	s_add_u32 s54, s16, s2
	s_addc_u32 s55, s17, s3
	s_mov_b32 m0, s27
	ds_read_b128 v[210:213], v142 offset:22528
	global_load_lds_dwordx4 v130, s[16:17]
	s_mov_b32 m0, s28
	ds_read_b128 v[214:217], v142 offset:23552
	global_load_lds_dwordx4 v132, s[16:17]
	s_waitcnt vmcnt(8) lgkmcnt(0)
	s_barrier
	s_setprio 1
	v_mfma_f32_16x16x32_bf16 v[94:97], v[146:149], v[186:189], v[94:97]
	v_mfma_f32_16x16x32_bf16 v[90:93], v[154:157], v[186:189], v[90:93]
	v_mfma_f32_16x16x32_bf16 v[118:121], v[146:149], v[194:197], v[118:121]
	v_mfma_f32_16x16x32_bf16 v[98:101], v[154:157], v[194:197], v[98:101]
	v_mfma_f32_16x16x32_bf16 v[126:129], v[146:149], v[202:205], v[126:129]
	v_mfma_f32_16x16x32_bf16 v[110:113], v[154:157], v[202:205], v[110:113]
	v_mfma_f32_16x16x32_bf16 v[122:125], v[146:149], v[210:213], v[122:125]
	v_mfma_f32_16x16x32_bf16 v[114:117], v[154:157], v[210:213], v[114:117]
	v_mfma_f32_16x16x32_bf16 v[94:97], v[150:153], v[190:193], v[94:97]
	v_mfma_f32_16x16x32_bf16 v[90:93], v[158:161], v[190:193], v[90:93]
	v_mfma_f32_16x16x32_bf16 v[118:121], v[150:153], v[198:201], v[118:121]
	v_mfma_f32_16x16x32_bf16 v[98:101], v[158:161], v[198:201], v[98:101]
	v_mfma_f32_16x16x32_bf16 v[126:129], v[150:153], v[206:209], v[126:129]
	v_mfma_f32_16x16x32_bf16 v[110:113], v[158:161], v[206:209], v[110:113]
	v_mfma_f32_16x16x32_bf16 v[122:125], v[150:153], v[214:217], v[122:125]
	v_mfma_f32_16x16x32_bf16 v[114:117], v[158:161], v[214:217], v[114:117]
	s_setprio 0
	s_setprio 1
	v_mfma_f32_16x16x32_bf16 v[38:41], v[170:173], v[186:189], v[38:41]
	v_mfma_f32_16x16x32_bf16 v[34:37], v[178:181], v[186:189], v[34:37]
	v_mfma_f32_16x16x32_bf16 v[66:69], v[170:173], v[194:197], v[66:69]
	v_mfma_f32_16x16x32_bf16 v[46:49], v[178:181], v[194:197], v[46:49]
	v_mfma_f32_16x16x32_bf16 v[78:81], v[170:173], v[202:205], v[78:81]
	v_mfma_f32_16x16x32_bf16 v[62:65], v[178:181], v[202:205], v[62:65]
	v_mfma_f32_16x16x32_bf16 v[106:109], v[170:173], v[210:213], v[106:109]
	v_mfma_f32_16x16x32_bf16 v[102:105], v[178:181], v[210:213], v[102:105]
	v_mfma_f32_16x16x32_bf16 v[38:41], v[174:177], v[190:193], v[38:41]
	v_mfma_f32_16x16x32_bf16 v[34:37], v[182:185], v[190:193], v[34:37]
	v_mfma_f32_16x16x32_bf16 v[66:69], v[174:177], v[198:201], v[66:69]
	v_mfma_f32_16x16x32_bf16 v[46:49], v[182:185], v[198:201], v[46:49]
	v_mfma_f32_16x16x32_bf16 v[78:81], v[174:177], v[206:209], v[78:81]
	v_mfma_f32_16x16x32_bf16 v[62:65], v[182:185], v[206:209], v[62:65]
	v_mfma_f32_16x16x32_bf16 v[106:109], v[174:177], v[214:217], v[106:109]
	v_mfma_f32_16x16x32_bf16 v[102:105], v[182:185], v[214:217], v[102:105]
	s_barrier
; #define PG8_STAGE(bufoff, gbase, voff) do { _Pragma("unroll") for (int _i = 0; _i < 2; ++_i) \
;         __builtin_amdgcn_global_load_lds((const unsigned*)((const char*)(gbase) + (voff)[_i]), (LAS unsigned*)(lds + (bufoff) + ldsw + _i * 8192), 16, 0, 0); } while (0)
; #define PG8_LDA(dst, b, h) do { _Pragma("unroll") for (int m = 0; m < 4; ++m) _Pragma("unroll") for (int k = 0; k < 2; ++k) dst[m][k] = *(const LAS bf16x8*)(lds + PG8_SA(b, h) + aoff + m * 2048 + k * 1024); } while (0)
; #define PG8_LDB(dst, b, h) do { _Pragma("unroll") for (int n = 0; n < 2; ++n) _Pragma("unroll") for (int k = 0; k < 2; ++k) dst[n][k] = *(const LAS bf16x8*)(lds + PG8_SB(b, h) + boff + n * 2048 + k * 1024); } while (0)
; #define PG8_MMA(ai, bj, At, Bt) do { __builtin_amdgcn_s_setprio(1); _Pragma("unroll") for (int m = 0; m < 4; ++m) _Pragma("unroll") for (int n = 0; n < 2; ++n) _Pragma("unroll") for (int k = 0; k < 2; ++k) \
;         acc[ai][bj][m][n] = __builtin_amdgcn_mfma_f32_16x16x32_bf16(Bt[n][k], At[m][k], acc[ai][bj][m][n], 0, 0, 0); __builtin_amdgcn_s_setprio(0); } while (0)
; #define PG8_WAIT_V(n) asm volatile("s_waitcnt vmcnt(" #n ")" ::: "memory")
; #define PG8_WAIT_L(n) asm volatile("s_waitcnt lgkmcnt(" #n ")" ::: "memory")
; #define PG8_BAR __builtin_amdgcn_s_barrier()
; #define PG8_SCHED __builtin_amdgcn_sched_barrier(0)
; template <class Epi, class Sched, bool ALIGN_EPI, class Hook = NoHook>
; __device__ __forceinline__ void gemm_phase(LAS unsigned char* lds, const Gemm g, const Sched& S, const Epi& E, const Hook& H = Hook()) {
;     ...
;             PG8_LDB(B0, 1, 0); PG8_LDB(B1, 1, 1); PG8_SCHED; PG8_LDA(At, 1, 0); PG8_STAGE(PG8_SA(0, 1), a2 + hA, voffA);
;             PG8_WAIT_V(8); PG8_WAIT_L(0); PG8_BAR; PG8_MMA(0, 0, At, B0); PG8_MMA(0, 1, At, B1); PG8_BAR; PG8_SCHED;
;             PG8_LDA(At, 1, 1); PG8_STAGE(PG8_SB(1, 0), b3, voffB); PG8_STAGE(PG8_SB(1, 1), b3 + hB, voffB); PG8_STAGE(PG8_SA(1, 0), a3, voffA);
;             PG8_WAIT_V(8); PG8_WAIT_L(0); PG8_BAR; PG8_MMA(1, 0, At, B0); PG8_MMA(1, 1, At, B1); PG8_BAR; PG8_SCHED;
;         }
;         if constexpr (Hook::ON) H.after(te, acc, cur, wr, wc, fr, fq);
;         }
;         if constexpr (ALIGN_EPI) { if (wr == 0) PG8_BAR; }
;         if constexpr (!Epi::AFTER_DRAIN) { E(acc, cur, wr, wc, fr, fq); S.done(cur); }
;         if (!has_next) break;
	s_setprio 0
	ds_read_b128 v[146:149], v143
	ds_read_b128 v[150:153], v143 offset:1024
	s_add_u32 s16, s16, 0x2b0000
	s_addc_u32 s17, s17, 0
	s_mov_b32 m0, s29
	ds_read_b128 v[154:157], v143 offset:2048
	global_load_lds_dwordx4 v130, s[16:17]
	ds_read_b128 v[158:161], v143 offset:3072
	ds_read_b128 v[170:173], v144
	ds_read_b128 v[174:177], v144 offset:1024
	ds_read_b128 v[178:181], v144 offset:2048
	ds_read_b128 v[182:185], v144 offset:3072
	ds_read_b128 v[186:189], v142 offset:32768
	s_mov_b32 m0, s39
	ds_read_b128 v[190:193], v142 offset:33792
	global_load_lds_dwordx4 v132, s[16:17]
	ds_read_b128 v[194:197], v142 offset:34816
	ds_read_b128 v[198:201], v142 offset:35840
	ds_read_b128 v[202:205], v142 offset:36864
	ds_read_b128 v[206:209], v142 offset:37888
	ds_read_b128 v[210:213], v142 offset:38912
	ds_read_b128 v[214:217], v142 offset:39936
	s_waitcnt vmcnt(8) lgkmcnt(0)
	s_barrier
	s_setprio 1
	v_mfma_f32_16x16x32_bf16 v[82:85], v[146:149], v[186:189], v[82:85]
	v_mfma_f32_16x16x32_bf16 v[54:57], v[154:157], v[186:189], v[54:57]
	v_mfma_f32_16x16x32_bf16 v[58:61], v[146:149], v[194:197], v[58:61]
	v_mfma_f32_16x16x32_bf16 v[42:45], v[154:157], v[194:197], v[42:45]
	v_mfma_f32_16x16x32_bf16 v[70:73], v[146:149], v[202:205], v[70:73]
	v_mfma_f32_16x16x32_bf16 v[50:53], v[154:157], v[202:205], v[50:53]
	v_mfma_f32_16x16x32_bf16 v[86:89], v[146:149], v[210:213], v[86:89]
	v_mfma_f32_16x16x32_bf16 v[74:77], v[154:157], v[210:213], v[74:77]
	v_mfma_f32_16x16x32_bf16 v[82:85], v[150:153], v[190:193], v[82:85]
	v_mfma_f32_16x16x32_bf16 v[54:57], v[158:161], v[190:193], v[54:57]
	v_mfma_f32_16x16x32_bf16 v[58:61], v[150:153], v[198:201], v[58:61]
	v_mfma_f32_16x16x32_bf16 v[42:45], v[158:161], v[198:201], v[42:45]
	v_mfma_f32_16x16x32_bf16 v[70:73], v[150:153], v[206:209], v[70:73]
	v_mfma_f32_16x16x32_bf16 v[50:53], v[158:161], v[206:209], v[50:53]
	v_mfma_f32_16x16x32_bf16 v[86:89], v[150:153], v[214:217], v[86:89]
	v_mfma_f32_16x16x32_bf16 v[74:77], v[158:161], v[214:217], v[74:77]
	s_setprio 0
	s_setprio 1
	v_mfma_f32_16x16x32_bf16 v[14:17], v[170:173], v[186:189], v[14:17]
	v_mfma_f32_16x16x32_bf16 v[2:5], v[178:181], v[186:189], v[2:5]
	v_mfma_f32_16x16x32_bf16 v[18:21], v[170:173], v[194:197], v[18:21]
	v_mfma_f32_16x16x32_bf16 v[6:9], v[178:181], v[194:197], v[6:9]
	v_mfma_f32_16x16x32_bf16 v[22:25], v[170:173], v[202:205], v[22:25]
	v_mfma_f32_16x16x32_bf16 v[10:13], v[178:181], v[202:205], v[10:13]
	v_mfma_f32_16x16x32_bf16 v[30:33], v[170:173], v[210:213], v[30:33]
	v_mfma_f32_16x16x32_bf16 v[26:29], v[178:181], v[210:213], v[26:29]
	v_mfma_f32_16x16x32_bf16 v[14:17], v[174:177], v[190:193], v[14:17]
	v_mfma_f32_16x16x32_bf16 v[2:5], v[182:185], v[190:193], v[2:5]
	v_mfma_f32_16x16x32_bf16 v[18:21], v[174:177], v[198:201], v[18:21]
	v_mfma_f32_16x16x32_bf16 v[6:9], v[182:185], v[198:201], v[6:9]
	v_mfma_f32_16x16x32_bf16 v[22:25], v[174:177], v[206:209], v[22:25]
	v_mfma_f32_16x16x32_bf16 v[10:13], v[182:185], v[206:209], v[10:13]
	v_mfma_f32_16x16x32_bf16 v[30:33], v[174:177], v[214:217], v[30:33]
	v_mfma_f32_16x16x32_bf16 v[26:29], v[182:185], v[214:217], v[26:29]
	s_barrier
	s_setprio 0
	s_mov_b32 m0, s36
	s_add_u32 s52, s10, s2
	s_addc_u32 s53, s11, s3
	s_add_u32 s10, s10, 0x2b0080
	ds_read_b128 v[186:189], v142 offset:49152
	ds_read_b128 v[190:193], v142 offset:50176
	global_load_lds_dwordx4 v162, s[52:53]
	ds_read_b128 v[194:197], v142 offset:51200
	s_mov_b32 m0, s44
	s_addc_u32 s11, s11, 0
	global_load_lds_dwordx4 v134, s[52:53]
	ds_read_b128 v[198:201], v142 offset:52224
	s_mov_b32 m0, s37
	ds_read_b128 v[202:205], v142 offset:53248
	global_load_lds_dwordx4 v162, s[10:11]
	s_mov_b32 m0, s45
	ds_read_b128 v[206:209], v142 offset:54272
	global_load_lds_dwordx4 v134, s[10:11]
	s_mov_b32 m0, s41
	ds_read_b128 v[210:213], v142 offset:55296
	global_load_lds_dwordx4 v130, s[54:55]
	s_mov_b32 m0, s42
	s_nop 0
	global_load_lds_dwordx4 v132, s[54:55]
	s_add_i32 s18, s18, 2
	s_add_u32 s4, s4, 0x100
	s_addc_u32 s5, s5, 0
	s_cmpk_gt_u32 s18, 0xa9
	ds_read_b128 v[214:217], v142 offset:56320
	s_waitcnt vmcnt(8) lgkmcnt(0)
	s_barrier
	s_setprio 1
	v_mfma_f32_16x16x32_bf16 v[94:97], v[146:149], v[186:189], v[94:97]
	v_mfma_f32_16x16x32_bf16 v[90:93], v[154:157], v[186:189], v[90:93]
	v_mfma_f32_16x16x32_bf16 v[118:121], v[146:149], v[194:197], v[118:121]
	v_mfma_f32_16x16x32_bf16 v[98:101], v[154:157], v[194:197], v[98:101]
	v_mfma_f32_16x16x32_bf16 v[126:129], v[146:149], v[202:205], v[126:129]
	v_mfma_f32_16x16x32_bf16 v[110:113], v[154:157], v[202:205], v[110:113]
	v_mfma_f32_16x16x32_bf16 v[122:125], v[146:149], v[210:213], v[122:125]
	v_mfma_f32_16x16x32_bf16 v[114:117], v[154:157], v[210:213], v[114:117]
	v_mfma_f32_16x16x32_bf16 v[94:97], v[150:153], v[190:193], v[94:97]
	v_mfma_f32_16x16x32_bf16 v[90:93], v[158:161], v[190:193], v[90:93]
	v_mfma_f32_16x16x32_bf16 v[118:121], v[150:153], v[198:201], v[118:121]
	v_mfma_f32_16x16x32_bf16 v[98:101], v[158:161], v[198:201], v[98:101]
	v_mfma_f32_16x16x32_bf16 v[126:129], v[150:153], v[206:209], v[126:129]
	v_mfma_f32_16x16x32_bf16 v[110:113], v[158:161], v[206:209], v[110:113]
	v_mfma_f32_16x16x32_bf16 v[122:125], v[150:153], v[214:217], v[122:125]
	v_mfma_f32_16x16x32_bf16 v[114:117], v[158:161], v[214:217], v[114:117]
	s_setprio 0
	s_setprio 1
	v_mfma_f32_16x16x32_bf16 v[38:41], v[170:173], v[186:189], v[38:41]
	v_mfma_f32_16x16x32_bf16 v[34:37], v[178:181], v[186:189], v[34:37]
	v_mfma_f32_16x16x32_bf16 v[66:69], v[170:173], v[194:197], v[66:69]
	v_mfma_f32_16x16x32_bf16 v[46:49], v[178:181], v[194:197], v[46:49]
	v_mfma_f32_16x16x32_bf16 v[78:81], v[170:173], v[202:205], v[78:81]
	v_mfma_f32_16x16x32_bf16 v[62:65], v[178:181], v[202:205], v[62:65]
	v_mfma_f32_16x16x32_bf16 v[106:109], v[170:173], v[210:213], v[106:109]
	v_mfma_f32_16x16x32_bf16 v[102:105], v[178:181], v[210:213], v[102:105]
	v_mfma_f32_16x16x32_bf16 v[38:41], v[174:177], v[190:193], v[38:41]
	v_mfma_f32_16x16x32_bf16 v[34:37], v[182:185], v[190:193], v[34:37]
	v_mfma_f32_16x16x32_bf16 v[66:69], v[174:177], v[198:201], v[66:69]
	v_mfma_f32_16x16x32_bf16 v[46:49], v[182:185], v[198:201], v[46:49]
	v_mfma_f32_16x16x32_bf16 v[78:81], v[174:177], v[206:209], v[78:81]
	v_mfma_f32_16x16x32_bf16 v[62:65], v[182:185], v[206:209], v[62:65]
	v_mfma_f32_16x16x32_bf16 v[106:109], v[174:177], v[214:217], v[106:109]
	v_mfma_f32_16x16x32_bf16 v[102:105], v[182:185], v[214:217], v[102:105]
	s_barrier
	s_setprio 0
	s_cbranch_scc0 .LBB0_1406
	s_cmpk_lt_u32 s22, 0x100
	s_cbranch_scc0 .LBB0_1409
	s_barrier
